# phase M1: odd workgroups run gdn_prep before rg_prompt (two phase passes with skip flags) to de-synchronise memory bursts
# baseline (speedup 1.0000x reference)
.LBB0_1:
	v_writelane_b32 v255, s2, 40
	s_mov_b64 s[60:61], s[0:1]
	s_mul_hi_i32 s0, s2, 0x13e22cbd
	s_lshr_b32 s1, s0, 31
	s_ashr_i32 s0, s0, 9
	s_add_i32 s0, s0, s1
	s_mul_i32 s1, s0, 0x19c0
	s_sub_i32 s30, s2, s1
	v_writelane_b32 v250, s4, 0
	s_add_i32 s9, s30, 0xffffee80
	s_cmpk_gt_i32 s30, 0x117f
	v_writelane_b32 v250, s5, 1
	v_writelane_b32 v250, s6, 2
	v_writelane_b32 v250, s7, 3
	s_cselect_b32 s6, s9, s30
	s_sext_i32_i16 s1, s6
	s_lshr_b32 s7, s1, 15
	s_bfe_u32 s1, s7, 0x4000c
	s_add_i32 s8, s6, s1
	s_lshl_b32 s1, s8, 2
	s_and_b32 s3, s1, 0xffc0
	s_sext_i32_i16 s1, s1
	s_bfe_u32 s1, s1, 0x80017
	s_add_i32 s1, s3, s1
	s_and_b32 s1, s1, 0xff00
	s_load_dwordx4 s[72:75], s[60:61], 0x100
	s_load_dwordx4 s[16:19], s[60:61], 0x110
	s_sub_i32 s5, s3, s1
	s_sext_i32_i16 s1, s5
	s_cmpk_lt_i32 s1, 0x80
	s_cselect_b32 s1, 27, 28
	s_cselect_b32 s3, 8, 9
	s_cmpk_gt_i32 s30, 0x117f
	s_cselect_b32 s14, s1, s3
	s_waitcnt lgkmcnt(0)
	s_add_u32 s66, s74, 0xcf21000
	s_addc_u32 s67, s75, 0
	s_add_u32 s64, s74, 0x11021000
	s_addc_u32 s65, s75, 0
	s_add_u32 s70, s74, 0x130a1000
	s_addc_u32 s71, s75, 0
	s_add_u32 s27, s74, 0x23cc1000
	s_addc_u32 s26, s75, 0
	s_add_u32 s10, s74, 0x2df41000
	s_addc_u32 s11, s75, 0
	v_writelane_b32 v250, s10, 4
	s_cmp_lt_i32 s17, 0
	s_load_dwordx4 s[16:19], s[60:61], 0x110
	v_writelane_b32 v250, s11, 5
	s_cselect_b64 s[10:11], -1, 0
	s_add_u32 s84, s60, 0x120
	v_writelane_b32 v250, s10, 6
	s_addc_u32 s85, s61, 0
	s_load_dwordx16 s[36:51], s[60:61], 0x98
	v_writelane_b32 v250, s11, 7
	s_add_u32 s10, s74, 0x38f43000
	s_addc_u32 s11, s75, 0
	s_cmpk_lt_i32 s2, 0x100
	s_cselect_b64 s[20:21], -1, 0
	s_add_u32 s28, s74, 0x38f43200
	v_writelane_b32 v250, s10, 8
	s_addc_u32 s29, s75, 0
	s_add_u32 s1, s74, 0x38f43400
	v_writelane_b32 v250, s11, 9
	v_writelane_b32 v250, s1, 10
	s_addc_u32 s1, s75, 0
	v_writelane_b32 v250, s1, 11
	s_add_u32 s1, s74, 0x38f43100
	v_writelane_b32 v250, s1, 12
	s_addc_u32 s1, s75, 0
	v_writelane_b32 v250, s1, 13
	s_ashr_i32 s1, s2, 31
	s_mov_b32 s68, s1
	s_lshr_b32 s1, s1, 29
	s_add_i32 s1, s2, s1
	s_ashr_i32 s3, s1, 3
	s_and_b32 s1, s1, -8
	s_sub_i32 s4, s2, s1
	s_lshl_b32 s15, s4, 5
	s_cmpk_lt_i32 s2, 0x80
	s_cselect_b64 s[10:11], -1, 0
	v_writelane_b32 v250, s10, 14
	s_cmpk_lt_i32 s2, 0x500
	s_mov_b32 s57, 0
	v_writelane_b32 v250, s11, 15
	s_cselect_b64 s[10:11], -1, 0
	v_writelane_b32 v250, s10, 16
	s_mov_b32 s56, s2
	v_and_b32_e32 v197, 0x3ff, v0
	v_writelane_b32 v250, s11, 17
	s_add_u32 s10, s72, 0x5a20000
	s_addc_u32 s11, s73, 0
	s_add_u32 s78, s74, 0x2dd41000
	s_addc_u32 s79, s75, 0
	s_add_u32 s80, s74, 0x2de41000
	v_writelane_b32 v250, s10, 18
	s_addc_u32 s81, s75, 0
	s_add_u32 s1, s74, 0x29d41000
	v_writelane_b32 v250, s11, 19
	v_writelane_b32 v250, s1, 20
	s_addc_u32 s1, s75, 0
	s_add_u32 s82, s74, 0x33f41000
	s_addc_u32 s83, s75, 0
	v_writelane_b32 v250, s1, 21
	s_add_u32 s1, s74, 0x38f41000
	v_writelane_b32 v250, s1, 22
	s_addc_u32 s1, s75, 0
	s_add_u32 s10, s74, 0x37f41000
	v_writelane_b32 v250, s1, 23
	s_addc_u32 s11, s75, 0
	v_writelane_b32 v250, s10, 24
	v_and_b32_e32 v0, 0x3fffffff, v0
	v_mov_b32_e32 v145, 0
	v_writelane_b32 v250, s11, 25
	s_add_u32 s10, s74, 0x2ff41000
	s_addc_u32 s11, s75, 0
	v_writelane_b32 v250, s10, 26
	s_add_u32 s1, s72, 0x4100000
	v_mov_b32_e32 v198, 0x3727c5ac
	v_writelane_b32 v250, s11, 27
	v_writelane_b32 v250, s1, 28
	s_addc_u32 s1, s73, 0
	v_writelane_b32 v250, s1, 29
	s_waitcnt lgkmcnt(0)
	s_bfe_u32 s1, s18, 0x1000d
	s_load_dwordx4 s[16:19], s[60:61], 0x110
	s_add_u32 s22, s74, 0xce21000
	v_writelane_b32 v250, s1, 30
	s_addc_u32 s23, s75, 0
	v_mov_b32_e32 v199, 0x4000
	s_waitcnt lgkmcnt(0)
	s_bfe_u32 s1, s18, 0x1000e
	v_writelane_b32 v250, s1, 31
	s_add_u32 s1, s74, 0xce00000
	v_writelane_b32 v250, s1, 32
	s_addc_u32 s1, s75, 0
	v_writelane_b32 v250, s1, 33
	s_cmpk_lt_i32 s2, 0x861
	s_mul_i32 s1, s4, 0x10c
	s_cselect_b64 s[10:11], -1, 0
	s_or_b32 s16, s1, 1
	v_writelane_b32 v250, s10, 34
	s_cmpk_lt_i32 s2, 0x596
	s_mul_i32 s1, s4, 0xb2
	v_writelane_b32 v250, s11, 35
	s_cselect_b64 s[10:11], -1, 0
	s_add_i32 s17, s1, 6
	v_writelane_b32 v250, s10, 36
	s_cmpk_lt_i32 s2, 0x6700
	v_mov_b32_e32 v146, 0.5
	v_writelane_b32 v250, s11, 37
	s_cselect_b64 s[10:11], -1, 0
	s_ashr_i32 s1, s0, 31
	v_writelane_b32 v250, s10, 38
	s_cmpk_gt_i32 s30, 0x57f
	v_mov_b32_e32 v200, 0x358637bd
	v_writelane_b32 v250, s11, 39
	s_cselect_b64 s[10:11], -1, 0
	s_cmpk_gt_u32 s9, 0x57f
	s_cselect_b64 s[12:13], -1, 0
	s_and_b64 s[10:11], s[10:11], s[12:13]
	s_add_i32 s9, s30, 0xffffe900
	v_writelane_b32 v250, s10, 40
	s_cmp_gt_u32 s9, 0xfffff13f
	s_mul_i32 s13, s0, 0x2010000
	v_writelane_b32 v250, s11, 41
	s_cselect_b64 s[10:11], -1, 0
	v_writelane_b32 v250, s10, 42
	s_cmpk_lt_u32 s30, 0x1080
	s_mul_hi_i32 s12, s0, 0x2010000
	v_writelane_b32 v250, s11, 43
	s_cselect_b64 s[10:11], -1, 0
	v_writelane_b32 v250, s10, 44
	v_mov_b32_e32 v201, 1
	v_mov_b64_e32 v[148:149], 0x100
	v_writelane_b32 v250, s11, 45
	s_lshl_b64 s[10:11], s[0:1], 22
	s_add_u32 s10, s46, s10
	v_writelane_b32 v250, s36, 46
	s_addc_u32 s11, s47, s11
	s_lshl_b32 s1, s30, 2
	v_writelane_b32 v250, s37, 47
	v_writelane_b32 v250, s38, 48
	v_writelane_b32 v250, s39, 49
	v_writelane_b32 v250, s40, 50
	v_writelane_b32 v250, s41, 51
	v_writelane_b32 v250, s42, 52
	v_writelane_b32 v250, s43, 53
	v_writelane_b32 v250, s44, 54
	v_writelane_b32 v250, s45, 55
	v_writelane_b32 v250, s46, 56
	v_writelane_b32 v250, s47, 57
	s_and_b32 s9, s1, 0x7fc0
	v_writelane_b32 v250, s48, 58
	s_addk_i32 s9, 0xbe00
	v_writelane_b32 v250, s49, 59
	v_writelane_b32 v251, s9, 0
	s_lshl_b32 s9, s30, 6
	v_writelane_b32 v250, s50, 60
	s_and_b32 s9, s9, 0x3c0
	s_add_i32 s1, s1, 0x3df00
	v_writelane_b32 v250, s51, 61
	v_writelane_b32 v251, s9, 1
	s_and_b32 s1, s1, 0x3ffc0
	s_and_b32 s9, s30, 0x1ff0
	s_load_dwordx16 s[36:51], s[60:61], 0x58
	v_writelane_b32 v250, s10, 62
	s_cmpk_eq_i32 s9, 0x1040
	s_cselect_b32 s9, 0x1800, 0
	v_writelane_b32 v250, s11, 63
	s_cselect_b32 s10, 16, 0
	s_add_i32 s11, s1, 0xfffff800
	s_cmpk_lt_u32 s1, 0x2010
	s_cselect_b32 s11, s11, -1
	s_or_b32 s18, s1, 16
	s_waitcnt lgkmcnt(0)
	s_add_u32 s24, s36, s13
	v_writelane_b32 v251, s36, 2
	s_addc_u32 s25, s37, s12
	s_cmpk_gt_u32 s30, 0x16ff
	v_writelane_b32 v251, s37, 3
	v_writelane_b32 v251, s38, 4
	v_writelane_b32 v251, s39, 5
	v_writelane_b32 v251, s40, 6
	v_writelane_b32 v251, s41, 7
	v_writelane_b32 v251, s42, 8
	v_writelane_b32 v251, s43, 9
	v_writelane_b32 v251, s44, 10
	v_writelane_b32 v251, s45, 11
	v_writelane_b32 v251, s46, 12
	v_writelane_b32 v251, s47, 13
	v_writelane_b32 v251, s48, 14
	v_writelane_b32 v251, s49, 15
	v_writelane_b32 v251, s50, 16
	v_writelane_b32 v251, s51, 17
	s_mov_b32 s12, 0xe900
	v_writelane_b32 v251, s24, 18
	s_cselect_b32 s12, s12, 0xfa80
	s_movk_i32 s13, 0xe8
	v_writelane_b32 v251, s25, 19
	s_cselect_b32 s13, s13, 0x50
	s_add_i32 s12, s12, s30
	v_writelane_b32 v251, s13, 20
	s_and_b32 s13, s12, 0xffff
	s_mul_i32 s13, s13, 0xba2f
	s_lshr_b32 s13, s13, 21
	s_mul_i32 s19, s13, 44
	s_and_b32 s8, s8, 0xfff0
	s_bfe_u32 s7, s7, 0x6000a
	s_sub_i32 s12, s12, s19
	s_sub_i32 s8, s6, s8
	s_add_i32 s6, s6, s7
	s_lshl_b32 s7, s13, 6
	v_writelane_b32 v251, s7, 21
	s_lshl_b32 s7, s12, 6
	s_and_b32 s7, s7, 0xffc0
	v_writelane_b32 v251, s7, 22
	s_lshl_b32 s7, s14, 3
	s_sext_i32_i16 s6, s6
	s_add_u32 s12, s60, s7
	s_addc_u32 s13, s61, 0
	s_lshl_b32 s6, s6, 1
	v_writelane_b32 v251, s12, 23
	s_and_b32 s6, s6, 0xffffff80
	s_and_b32 s5, s5, 64
	v_writelane_b32 v251, s13, 24
	s_or_b32 s5, s6, s5
	v_writelane_b32 v251, s5, 25
	s_sext_i32_i16 s5, s8
	s_lshl_b32 s5, s5, 6
	v_writelane_b32 v251, s5, 26
	s_lshl_b64 s[6:7], s[56:57], 9
	v_writelane_b32 v251, s6, 27
	s_cmp_eq_u64 s[72:73], 0
	s_mul_i32 s5, s4, 33
	v_writelane_b32 v251, s7, 28
	s_cselect_b64 s[6:7], -1, 0
	s_cmp_lt_i32 s4, 0
	s_cselect_b32 s5, s5, s15
	v_writelane_b32 v251, s6, 29
	s_add_i32 s5, s5, s3
	s_mov_b32 s46, s2
	v_writelane_b32 v251, s7, 30
	s_ashr_i32 s6, s5, 31
	s_lshr_b32 s6, s6, 27
	s_add_i32 s6, s5, s6
	s_and_b32 s7, s6, 0xffe0
	s_sub_i32 s5, s5, s7
	s_bfe_i32 s7, s5, 0x80000
	s_bfe_u32 s7, s7, 0x3000c
	s_add_i32 s7, s5, s7
	s_and_b32 s8, s7, 0xf8
	s_sub_i32 s5, s5, s8
	s_ashr_i32 s6, s6, 5
	s_bfe_i32 s7, s7, 0x80000
	s_lshl_b32 s6, s6, 3
	s_sext_i32_i16 s7, s7
	s_sext_i32_i8 s5, s5
	s_add_i32 s14, s6, s5
	s_lshr_b32 s6, s7, 3
	s_ashr_i32 s5, s7, 3
	s_bfe_i64 s[6:7], s[6:7], 0x100000
	v_writelane_b32 v251, s5, 31
	s_lshl_b64 s[6:7], s[6:7], 19
	s_ashr_i32 s15, s14, 31
	v_writelane_b32 v251, s6, 32
	s_mul_i32 s5, s4, 0x10d
	s_mul_hi_i32 s8, s14, 0x160000
	v_writelane_b32 v251, s7, 33
	s_lshl_b64 s[6:7], s[14:15], 19
	s_add_u32 s6, s27, s6
	v_writelane_b32 v251, s27, 34
	s_addc_u32 s7, s26, s7
	v_writelane_b32 v251, s26, 35
	s_add_u32 s12, s6, 0x40000
	v_writelane_b32 v251, s6, 36
	s_addc_u32 s13, s7, 0
	s_cmp_lt_i32 s4, 1
	s_cselect_b32 s5, s5, s16
	s_add_i32 s5, s5, s3
	v_writelane_b32 v251, s7, 37
	s_mul_hi_i32 s6, s5, 0x3e0f83e1
	s_lshr_b32 s7, s6, 31
	s_ashr_i32 s6, s6, 6
	v_writelane_b32 v251, s12, 38
	s_add_i32 s6, s6, s7
	s_mul_i32 s7, s6, 0x108
	v_writelane_b32 v251, s13, 39
	s_lshl_b32 s6, s6, 3
	s_mov_b32 s12, s14
	s_sub_i32 s5, s5, s7
	s_sub_i32 s7, 0x41, s6
	v_writelane_b32 v251, s12, 40
	s_min_u32 s7, s7, 8
	v_cvt_f32_ubyte0_e32 v2, s7
	v_writelane_b32 v251, s13, 41
	s_mul_i32 s12, s14, 0x160000
	s_add_u32 s14, s70, s12
	s_addc_u32 s15, s71, s8
	s_add_u32 s12, s14, 0xb0000
	v_writelane_b32 v251, s14, 42
	s_addc_u32 s13, s15, 0
	s_cmp_lt_i32 s4, 6
	s_mulk_i32 s4, 0xb3
	s_cselect_b32 s4, s4, s17
	s_add_i32 s4, s4, s3
	s_mul_hi_i32 s3, s4, 0x2e8ba2e9
	v_writelane_b32 v251, s15, 43
	s_lshr_b32 s8, s3, 31
	s_ashr_i32 s3, s3, 5
	v_writelane_b32 v251, s12, 44
	s_add_i32 s3, s3, s8
	v_cvt_f32_i32_e32 v1, s5
	v_writelane_b32 v251, s13, 45
	s_lshl_b32 s12, s3, 3
	v_rcp_iflag_f32_e32 v3, v2
	s_mul_i32 s8, s3, 0xb0
	s_sub_i32 s3, 0x41, s12
	s_sub_i32 s8, s4, s8
	s_min_u32 s13, s3, 8
	s_cmpk_lt_u32 s1, 0x2000
	s_cselect_b32 s3, s18, s11
	s_cmpk_lt_u32 s1, 0x1800
	v_mul_f32_e32 v3, v1, v3
	s_cselect_b32 s1, s1, s3
	s_cmpk_lt_u32 s30, 0x1040
	v_trunc_f32_e32 v3, v3
	s_cselect_b32 s1, s1, s9
	v_fma_f32 v1, -v3, v2, v1
	v_writelane_b32 v251, s1, 46
	s_cselect_b32 s1, 64, s10
	v_cmp_ge_f32_e64 s[2:3], |v1|, v2
	v_cvt_i32_f32_e32 v1, v3
	v_writelane_b32 v251, s1, 47
	s_ashr_i32 s1, s5, 30
	s_or_b32 s1, s1, 1
	s_and_b64 s[2:3], s[2:3], exec
	s_cselect_b32 s1, s1, 0
	v_readfirstlane_b32 s2, v1
	s_add_i32 s2, s2, s1
	s_mul_i32 s1, s2, s7
	s_sub_i32 s1, s5, s1
	s_bfe_i64 s[4:5], s[2:3], 0x100000
	s_sext_i32_i16 s1, s1
	s_lshl_b64 s[4:5], s[4:5], 19
	v_cvt_f32_ubyte0_e32 v2, s13
	s_add_i32 s6, s6, s1
	v_writelane_b32 v251, s4, 48
	v_cvt_f32_i32_e32 v1, s8
	v_rcp_iflag_f32_e32 v3, v2
	v_writelane_b32 v251, s5, 49
	s_mov_b32 s4, s6
	s_ashr_i32 s7, s6, 31
	v_writelane_b32 v251, s4, 50
	v_mul_f32_e32 v3, v1, v3
	v_trunc_f32_e32 v3, v3
	v_writelane_b32 v251, s5, 51
	s_lshl_b64 s[4:5], s[6:7], 19
	s_add_u32 s4, s64, s4
	s_addc_u32 s5, s65, s5
	s_add_u32 s6, s4, 0x40000
	v_writelane_b32 v251, s4, 52
	v_fma_f32 v1, -v3, v2, v1
	s_addc_u32 s7, s5, 0
	v_writelane_b32 v251, s5, 53
	v_cmp_ge_f32_e64 s[4:5], |v1|, v2
	v_cvt_i32_f32_e32 v1, v3
	s_ashr_i32 s1, s8, 30
	s_or_b32 s1, s1, 1
	s_and_b64 s[4:5], s[4:5], exec
	s_cselect_b32 s1, s1, 0
	v_readfirstlane_b32 s3, v1
	s_add_i32 s4, s3, s1
	v_writelane_b32 v251, s6, 54
	s_mul_i32 s1, s4, s13
	s_sub_i32 s1, s8, s1
	v_writelane_b32 v251, s7, 55
	s_bfe_i64 s[6:7], s[4:5], 0x100000
	s_sext_i32_i16 s1, s1
	s_lshl_b64 s[6:7], s[6:7], 19
	s_add_i32 s12, s12, s1
	v_writelane_b32 v251, s6, 56
	s_mul_hi_i32 s1, s0, 0xb00000
	s_ashr_i32 s13, s12, 31
	v_writelane_b32 v251, s7, 57
	s_mov_b32 s6, s12
	v_writelane_b32 v251, s6, 58
	s_mul_i32 s0, s0, 0xb00000
	s_load_dwordx4 s[8:11], s[60:61], 0x110
	v_writelane_b32 v251, s7, 59
	v_writelane_b32 v251, s20, 60
	s_lshl_b64 s[6:7], s[12:13], 19
	s_add_u32 s6, s64, s6
	v_writelane_b32 v251, s21, 61
	v_writelane_b32 v251, s1, 62
	v_writelane_b32 v251, s0, 63
	s_sext_i32_i16 s0, s2
	v_writelane_b32 v252, s0, 0
	s_sext_i32_i16 s0, s4
	s_addc_u32 s7, s65, s7
	v_writelane_b32 v252, s0, 1
	s_add_u32 s0, s6, 0x40000
	v_writelane_b32 v252, s6, 2
	s_addc_u32 s1, s7, 0
	s_load_dwordx8 s[12:19], s[60:61], 0x0
	v_writelane_b32 v252, s7, 3
	v_writelane_b32 v252, s0, 4
	s_mov_b64 s[44:45], s[28:29]
	v_mbcnt_lo_u32_b32 v1, -1, 0
	v_writelane_b32 v252, s1, 5
	s_lshl_b32 s0, s46, 1
	v_writelane_b32 v252, s0, 6
	s_add_i32 s0, s46, 0x4000
	v_writelane_b32 v252, s0, 7
	s_lshl_b32 s0, s46, 6
	v_writelane_b32 v252, s0, 8
	s_lshl_b32 s0, s46, 2
	v_writelane_b32 v252, s0, 9
	s_lshl_b64 s[0:1], s[56:57], 11
	s_add_u32 s0, s74, s0
	s_addc_u32 s1, s75, s1
	s_add_u32 s0, s0, 0xce00000
	s_addc_u32 s1, s1, 0
	v_writelane_b32 v252, s0, 10
	s_lshl_b64 s[2:3], s[56:57], 13
	s_waitcnt lgkmcnt(0)
	s_mov_b64 s[4:5], s[16:17]
	v_writelane_b32 v252, s1, 11
	s_lshl_b32 s0, s46, 14
	v_writelane_b32 v252, s0, 12
	s_add_u32 s0, s12, s2
	s_addc_u32 s1, s13, s3
	v_writelane_b32 v252, s0, 13
	s_mov_b64 s[6:7], s[18:19]
	v_cndmask_b32_e64 v196, 0, 1, s[20:21]
	v_writelane_b32 v252, s1, 14
	s_add_u32 s0, s14, s2
	v_writelane_b32 v252, s0, 15
	v_mov_b64_e32 v[150:151], 0xff
	v_mbcnt_hi_u32_b32 v202, -1, v1
	v_writelane_b32 v252, s1, 16
	v_writelane_b32 v252, s2, 17
	v_writelane_b32 v252, s3, 18
	v_writelane_b32 v252, s4, 19
	v_writelane_b32 v252, s5, 20
	v_writelane_b32 v252, s6, 21
	v_writelane_b32 v252, s7, 22
	s_addc_u32 s1, s15, s3
	s_add_u32 s0, s0, 0xfc000000
	s_addc_u32 s1, s1, -1
	v_writelane_b32 v252, s0, 23
	v_mov_b32_e32 v203, 0x29d41020
	v_mov_b32_e32 v204, 0x3c0
	v_writelane_b32 v252, s1, 24
	s_add_u32 s0, s74, s2
	v_writelane_b32 v252, s2, 25
	s_addc_u32 s1, s75, s3
	s_add_u32 s0, s0, 0xcf21000
	v_writelane_b32 v252, s3, 26
	s_addc_u32 s1, s1, 0
	v_writelane_b32 v252, s0, 27
	v_mov_b32_e32 v205, 0x41b17218
	v_mov_b32_e32 v206, 0x4200
	v_writelane_b32 v252, s1, 28
	s_lshl_b64 s[0:1], s[56:57], 12
	s_add_u32 s0, s74, s0
	s_addc_u32 s1, s75, s1
	s_add_u32 s0, s0, 0x23cc1000
	s_addc_u32 s1, s1, 0
	v_writelane_b32 v252, s0, 29
	v_mov_b32_e32 v207, 0x2df41020
	v_mov_b32_e32 v208, 0x2ff41020
	v_writelane_b32 v252, s1, 30
	v_cmp_eq_u32_e64 s[0:1], 0, v0
	v_mov_b32_e32 v209, 0x3db504f3
	v_mov_b64_e32 v[154:155], 0x861
	v_writelane_b32 v252, s0, 31
	v_mov_b64_e32 v[156:157], 0x595
	v_mov_b64_e32 v[158:159], 0x596
	v_writelane_b32 v252, s1, 32
	v_cmp_eq_u32_e64 s[0:1], 0, v197
	v_mov_b32_e32 v210, 0x88
	v_mov_b32_e32 v211, 0x78
	v_writelane_b32 v252, s0, 33
	v_mov_b32_e32 v240, v145
	v_mov_b32_e32 v241, v145
	v_writelane_b32 v252, s1, 34
	s_load_dwordx4 s[0:3], s[60:61], 0x20
	s_movk_i32 s33, 0x2000
	s_mov_b32 s86, 0x800000
	s_movk_i32 s87, 0x3000
	s_mov_b32 s88, 0xbfb8aa3b
	s_waitcnt lgkmcnt(0)
	v_writelane_b32 v252, s0, 35
	s_mov_b32 s89, 0x3c23d70a
	s_mov_b32 s90, 0x3f317217
	v_writelane_b32 v252, s1, 36
	v_writelane_b32 v252, s2, 37
	v_writelane_b32 v252, s3, 38
	v_writelane_b32 v252, s84, 39
	s_mov_b32 s91, 0x7f800000
	s_mov_b32 s92, 0xbeaaaaab
	v_writelane_b32 v252, s85, 40
	v_writelane_b32 v252, s22, 41
	s_mov_b32 s93, 0xbca3d70a
	s_mov_b32 s94, 0x3e2aaaab
	v_writelane_b32 v252, s23, 42
	v_writelane_b32 v252, s46, 43
	v_writelane_b32 v252, s60, 44
	s_mov_b32 s95, 0x25d41000
	s_mov_b32 s96, 0x27d41000
	v_writelane_b32 v252, s61, 45
	v_writelane_b32 v252, s66, 46
	s_mov_b32 s97, 0x130a4000
	s_mov_b32 s12, s8
	v_writelane_b32 v252, s67, 47
	v_writelane_b32 v252, s64, 48
	s_mov_b64 s[76:77], 0x800
	s_nop 0
	v_writelane_b32 v252, s65, 49
	v_writelane_b32 v252, s70, 50
	s_nop 1
	v_writelane_b32 v252, s71, 51
	v_writelane_b32 v252, s44, 52
	s_nop 1
	v_writelane_b32 v252, s45, 53
	v_writelane_b32 v252, s68, 54
	v_writelane_b32 v252, s78, 55
	s_nop 1
	v_writelane_b32 v252, s79, 56
	v_writelane_b32 v252, s80, 57
	s_nop 1
	v_writelane_b32 v252, s81, 58
	v_writelane_b32 v252, s82, 59
	s_nop 1
	v_writelane_b32 v252, s83, 60
	s_branch .LBB0_3

.LBB0_23:
	v_sub_co_u32_e64 v0, s[0:1], s12, 1
	s_xor_b64 s[2:3], s[0:1], -1
	v_writelane_b32 v252, s2, 61
	s_mov_b32 s5, s46
	v_readlane_b32 s36, v250, 46
	v_writelane_b32 v252, s3, 62
	v_readfirstlane_b32 s3, v0
	s_mul_hi_i32 s2, s3, 0x38e38e39
	s_lshr_b32 s4, s2, 31
	s_ashr_i32 s2, s2, 1
	s_add_i32 s2, s2, s4
	s_mul_i32 s4, s2, 9
	s_sub_i32 s13, s3, s4
	s_and_b64 s[0:1], s[0:1], exec
	s_cselect_b32 s0, 12, s13
	s_lshr_b32 s0, s10, s0
	s_and_b32 s0, s0, 1
	s_cmp_eq_u32 s13, 3
	s_cselect_b32 s100, 1, 0
	v_readlane_b32 s101, v255, 40
	s_nop 3
	s_and_b32 s101, s101, s100
	s_and_b32 s101, s101, 1
	s_or_b32 s0, s0, s101
	s_ashr_i32 s3, s2, 31
	s_mul_i32 s1, s2, 0x3380000
	v_writelane_b32 v252, s0, 63
	s_mul_hi_i32 s0, s2, 0x3380000
	s_add_u32 s8, s74, s1
	s_mul_i32 s10, s2, 3
	s_addc_u32 s9, s75, s0
	s_add_i32 s4, s10, 2
	s_add_u32 s14, s8, 0x2100000
	s_addc_u32 s15, s9, 0
	s_lshl_b64 s[0:1], s[2:3], 10
	v_writelane_b32 v253, s0, 0
	v_readlane_b32 s48, v250, 58
	v_readlane_b32 s49, v250, 59
	v_writelane_b32 v253, s1, 1
	s_lshl_b64 s[0:1], s[2:3], 12
	s_add_u32 s6, s48, s0
	s_addc_u32 s7, s49, s1
	v_readlane_b32 s50, v250, 60
	v_writelane_b32 v253, s6, 2
	v_readlane_b32 s51, v250, 61
	v_readlane_b32 s46, v250, 56
	v_writelane_b32 v253, s7, 3
	s_add_u32 s6, s50, s0
	s_addc_u32 s7, s51, s1
	v_writelane_b32 v253, s6, 4
	s_mov_b32 s46, s5
	s_lshl_b32 s5, s4, 2
	v_writelane_b32 v253, s7, 5
	v_writelane_b32 v253, s5, 6
	s_lshl_b32 s4, s4, 8
	v_writelane_b32 v253, s4, 7
	s_lshl_b64 s[4:5], s[2:3], 7
	v_writelane_b32 v253, s4, 8
	s_lshl_b32 s6, s2, 3
	s_mov_b32 s11, s57
	v_writelane_b32 v253, s5, 9
	v_readlane_b32 s48, v251, 2
	s_lshl_b64 s[4:5], s[2:3], 14
	v_writelane_b32 v253, s6, 10
	s_lshl_b64 s[6:7], s[2:3], 15
	s_lshl_b64 s[16:17], s[2:3], 3
	v_readlane_b32 s52, v251, 6
	v_writelane_b32 v253, s16, 11
	v_readlane_b32 s53, v251, 7
	s_add_u32 s4, s52, s4
	v_writelane_b32 v253, s17, 12
	s_addc_u32 s5, s53, s5
	v_readlane_b32 s54, v251, 8
	v_writelane_b32 v253, s4, 13
	v_readlane_b32 s55, v251, 9
	v_readlane_b32 s38, v250, 48
	v_writelane_b32 v253, s5, 14
	s_add_u32 s4, s54, s0
	s_addc_u32 s5, s55, s1
	v_writelane_b32 v253, s4, 15
	v_readlane_b32 s39, v250, 49
	v_readlane_b32 s44, v250, 54
	v_writelane_b32 v253, s5, 16
	s_mul_i32 s5, s2, 0xc000
	s_mul_hi_i32 s4, s2, 0xc000
	s_add_u32 s16, s38, s5
	s_addc_u32 s17, s39, s4
	s_lshl_b64 s[4:5], s[2:3], 9
	v_readlane_b32 s45, v250, 55
	v_writelane_b32 v253, s16, 17
	s_add_u32 s4, s44, s4
	s_addc_u32 s5, s45, s5
	v_writelane_b32 v253, s17, 18
	v_writelane_b32 v253, s4, 19
	v_readlane_b32 s57, v251, 11
	s_mov_b32 s57, s11
	v_writelane_b32 v253, s5, 20
	s_add_u32 s4, s72, s6
	v_writelane_b32 v253, s4, 21
	s_addc_u32 s4, s73, s7
	v_writelane_b32 v253, s4, 22
	s_lshl_b64 s[6:7], s[2:3], 6
	v_writelane_b32 v253, s6, 23
	s_mul_hi_i32 s4, s2, 0x8400
	s_mul_i32 s5, s2, 0x8400
	v_writelane_b32 v253, s7, 24
	s_lshl_b64 s[2:3], s[2:3], 18
	v_writelane_b32 v253, s2, 25
	s_add_u32 s11, s8, 0x1080000
	s_addc_u32 s16, s9, 0
	v_writelane_b32 v253, s3, 26
	v_readlane_b32 s2, v250, 32
	s_add_u32 s6, s2, s5
	v_readlane_b32 s2, v250, 33
	s_addc_u32 s7, s2, s4
	s_cmp_eq_u32 s13, 1
	v_writelane_b32 v253, s6, 27
	s_cselect_b32 s2, 1, 3
	s_mov_b32 s3, 0x2e00000
	v_writelane_b32 v253, s7, 28
	s_cselect_b32 s6, 48, 0xf0
	s_cselect_b32 s7, 0xb00000, s3
	s_add_i32 s10, s2, s10
	s_cmp_lg_u32 s13, 8
	s_cselect_b64 s[2:3], -1, 0
	s_sub_i32 s4, s12, 37
	s_cmp_lt_u32 s4, -9
	s_cselect_b64 s[4:5], -1, 0
	s_or_b64 s[2:3], s[4:5], s[2:3]
	v_readlane_b32 s60, v251, 14
	v_readlane_b32 s61, v251, 15
	s_add_u32 s7, s8, s7
	v_writelane_b32 v253, s12, 29
	s_addc_u32 s12, s9, 0
	s_mov_b64 s[60:61], s[18:19]
	s_add_u32 s4, s60, s6
	s_addc_u32 s5, s61, 0
	v_writelane_b32 v253, s4, 30
	v_readlane_b32 s58, v251, 12
	v_readlane_b32 s59, v251, 13
	v_writelane_b32 v253, s5, 31
	v_readlane_b32 s4, v251, 29
	v_readlane_b32 s5, v251, 30
	s_nor_b64 s[2:3], s[2:3], s[4:5]
	v_writelane_b32 v253, s2, 32
	v_readlane_b32 s62, v251, 16
	v_readlane_b32 s63, v251, 17
	v_writelane_b32 v253, s3, 33
	s_lshl_b32 s2, s10, 2
	v_writelane_b32 v253, s2, 34
	s_lshl_b32 s2, s10, 8
	s_cmp_eq_u32 s13, 0
	v_writelane_b32 v253, s2, 35
	s_cselect_b32 s2, 0, 0x2300000
	s_add_u32 s4, s8, s2
	s_addc_u32 s5, s9, 0
	v_readlane_b32 s2, v251, 32
	v_readlane_b32 s3, v251, 33
	s_add_u32 s2, s14, s2
	v_writelane_b32 v253, s13, 36
	s_addc_u32 s3, s15, s3
	v_writelane_b32 v253, s14, 37
	s_add_u32 s8, s2, 0x40000
	v_writelane_b32 v253, s15, 38
	s_addc_u32 s9, s3, 0
	v_writelane_b32 v253, s8, 39
	v_readlane_b32 s37, v250, 47
	v_readlane_b32 s42, v250, 52
	v_writelane_b32 v253, s9, 40
	s_add_u32 s8, s2, 0x40080
	v_writelane_b32 v253, s2, 41
	s_addc_u32 s9, s3, 0
	v_readlane_b32 s43, v250, 53
	v_writelane_b32 v253, s3, 42
	v_readlane_b32 s3, v251, 31
	v_writelane_b32 v253, s8, 43
	s_mul_i32 s2, s3, 0x160000
	s_add_u32 s6, s7, s2
	v_writelane_b32 v253, s9, 44
	s_mul_hi_i32 s2, s3, 0x160000
	v_writelane_b32 v253, s7, 45
	s_addc_u32 s7, s12, s2
	s_add_u32 s2, s6, 0xb0000
	v_writelane_b32 v253, s12, 46
	s_addc_u32 s3, s7, 0
	v_writelane_b32 v253, s2, 47
	v_readlane_b32 s49, v251, 3
	v_readlane_b32 s50, v251, 4
	v_writelane_b32 v253, s3, 48
	s_add_u32 s2, s6, 0xb0080
	v_writelane_b32 v253, s6, 49
	s_addc_u32 s3, s7, 0
	s_mov_b32 s52, 0x3fd744fd
	v_writelane_b32 v253, s7, 50
	v_writelane_b32 v253, s2, 51
	s_mov_b64 s[42:43], 0x4000
	s_mov_b64 s[48:49], 0x80
	v_writelane_b32 v253, s3, 52
	v_readlane_b32 s2, v251, 48
	v_readlane_b32 s3, v251, 49
	s_add_u32 s2, s11, s2
	s_addc_u32 s3, s16, s3
	v_writelane_b32 v253, s11, 53
	s_add_u32 s6, s2, 0x40000
	v_writelane_b32 v253, s16, 54
	s_addc_u32 s7, s3, 0
	v_writelane_b32 v253, s6, 55
	s_mov_b32 s50, 0xcf21000
	s_mov_b32 s53, 0.5
	v_writelane_b32 v253, s7, 56
	s_add_u32 s6, s2, 0x40080
	v_writelane_b32 v253, s2, 57
	s_addc_u32 s7, s3, 0
	s_mov_b32 s54, 0xe900
	v_writelane_b32 v253, s3, 58
	v_readlane_b32 s2, v251, 56
	v_writelane_b32 v253, s6, 59
	v_readlane_b32 s3, v251, 57
	s_add_u32 s2, s4, s2
	v_writelane_b32 v253, s7, 60
	s_addc_u32 s3, s5, s3
	v_writelane_b32 v253, s4, 61
	s_add_u32 s4, s2, 0x40000
	v_writelane_b32 v253, s5, 62
	s_addc_u32 s5, s3, 0
	v_writelane_b32 v253, s4, 63
	s_movk_i32 s55, 0xe8
	s_mov_b64 s[44:45], s[20:21]
	v_writelane_b32 v254, s5, 0
	s_add_u32 s4, s2, 0x40080
	v_writelane_b32 v254, s2, 1
	s_addc_u32 s5, s3, 0
	v_readlane_b32 s40, v250, 50
	v_writelane_b32 v254, s3, 2
	v_writelane_b32 v254, s4, 3
	s_add_u32 s2, s58, s0
	s_addc_u32 s3, s59, s1
	v_writelane_b32 v254, s5, 4
	v_writelane_b32 v254, s2, 5
	v_readlane_b32 s41, v250, 51
	v_readlane_b32 s47, v250, 57
	v_writelane_b32 v254, s3, 6
	s_add_u32 s2, s62, s0
	s_addc_u32 s3, s63, s1
	v_writelane_b32 v254, s2, 7
	s_add_u32 s0, s36, s0
	s_addc_u32 s1, s37, s1
	v_writelane_b32 v254, s3, 8
	v_writelane_b32 v254, s0, 9
	v_readlane_b32 s51, v251, 5
	v_readlane_b32 s56, v251, 10
	v_writelane_b32 v254, s1, 10
	s_mov_b32 s0, 0
	v_writelane_b32 v254, s0, 11
	s_branch .LBB0_26

.LBB0_184:
	s_and_b64 vcc, exec, s[0:1]
	s_cbranch_vccz .LBB0_388
	v_readlane_b32 s2, v253, 36
	s_cmp_gt_i32 s2, 1
	s_mov_b64 s[0:1], -1
	s_cbranch_scc0 .LBB0_386
	s_cmp_gt_i32 s2, 2
	s_cbranch_scc0 .LBB0_368
	v_readlane_b32 s100, v255, 40
	v_readlane_b32 s101, v254, 11
	s_nop 3
	s_and_b32 s100, s100, 1
	s_cmp_eq_u32 s101, 0
	s_cselect_b32 s101, s100, 0
	v_writelane_b32 v255, s101, 41
	v_readlane_b32 s101, v254, 11
	s_nop 3
	s_cmp_eq_u32 s101, 1
	s_cselect_b32 s101, s100, 0
	v_writelane_b32 v255, s101, 42
	v_writelane_b32 v254, s58, 12
	v_readfirstlane_b32 s0, v160
	s_ashr_i32 s0, s0, 5
	v_writelane_b32 v254, s59, 13
	v_writelane_b32 v254, s40, 14
	s_and_b32 s0, s0, -2
	v_and_b32_e32 v90, 48, v160
	v_writelane_b32 v254, s41, 15
	v_writelane_b32 v254, s56, 16
	v_mov_b32_e32 v91, v145
	v_and_b32_e32 v89, 15, v160
	v_writelane_b32 v254, s57, 17
	v_writelane_b32 v254, s0, 18
	v_readlane_b32 s0, v253, 13
	v_readlane_b32 s1, v253, 14
	v_bfe_u32 v93, v160, 4, 2
	v_mul_u32_u24_e32 v0, 0x2100, v89
	v_lshl_add_u64 v[100:101], s[0:1], 0, v[90:91]
	v_readlane_b32 s0, v254, 5
	v_readlane_b32 s1, v254, 6
	v_lshlrev_b32_e32 v88, 3, v93
	v_or_b32_e32 v1, v88, v0
	v_lshl_add_u64 v[104:105], s[0:1], 0, v[90:91]
	v_readlane_b32 s0, v254, 7
	v_readlane_b32 s1, v254, 8
	v_lshlrev_b32_e32 v144, 1, v1
	v_readlane_b32 s2, v253, 15
	v_lshl_add_u64 v[106:107], s[0:1], 0, v[90:91]
	v_readlane_b32 s0, v254, 9
	v_readlane_b32 s1, v254, 10
	v_and_b32_e32 v92, 63, v160
	v_lshlrev_b32_e32 v161, 2, v93
	v_lshl_add_u64 v[94:95], s[70:71], 0, v[144:145]
	v_lshlrev_b32_e32 v144, 5, v93
	v_readlane_b32 s3, v253, 16
	v_lshl_add_u64 v[108:109], s[0:1], 0, v[90:91]
	v_readlane_b32 s0, v253, 25
	v_lshl_add_u64 v[96:97], s[2:3], 0, v[144:145]
	v_or_b32_e32 v0, v0, v161
	v_lshl_or_b32 v110, v89, 10, v161
	v_lshlrev_b32_e32 v144, 4, v92
	v_readlane_b32 s1, v253, 26
	v_add_u32_e32 v99, -3, v89
	s_mov_b32 s4, 0
	v_cmp_eq_u32_e64 s[6:7], 0, v89
	v_lshlrev_b32_e32 v98, 1, v0
	v_lshl_add_u64 v[102:103], s[2:3], 0, v[90:91]
	v_mov_b32_e32 v111, v145
	v_lshlrev_b32_e32 v112, 1, v110
	v_mov_b32_e32 v113, v145
	v_lshl_add_u64 v[114:115], s[0:1], 0, v[144:145]
	s_branch .LBB0_189

.LBB0_193:
	s_xor_b64 s[70:71], s[54:55], -1
	v_readlane_b32 s100, v255, 41
	s_nop 3
	s_cmp_lg_u32 s100, 0
	s_cbranch_scc1 .LBB0_192
	v_readlane_b32 s54, v254, 18
	s_or_b32 s80, s78, s54
	s_lshl_b32 s54, s80, 6
	s_ashr_i32 s55, s54, 31
	s_lshl_b64 s[78:79], s[54:55], 2
	v_readlane_b32 s82, v253, 13
	v_readlane_b32 s83, v253, 14
	s_add_u32 s84, s82, s78
	s_addc_u32 s85, s83, s79
	v_lshlrev_b32_e32 v144, 2, v88
	s_waitcnt lgkmcnt(0)
	v_lshl_add_u64 v[40:41], s[84:85], 0, v[144:145]
	s_movk_i32 s81, 0x1000
	v_add_co_u32_e32 v36, vcc, s81, v40
	s_mov_b64 s[82:83], 0x1000
	s_nop 0
	v_addc_co_u32_e32 v37, vcc, 0, v41, vcc
	v_add_co_u32_e32 v42, vcc, s33, v40
	v_lshl_add_u64 v[0:1], v[40:41], 0, s[82:83]
	s_nop 0
	v_addc_co_u32_e32 v43, vcc, 0, v41, vcc
	s_mov_b64 s[82:83], 0x2000
	global_load_dwordx4 v[8:11], v144, s[84:85] offset:16
	global_load_dwordx4 v[44:47], v144, s[84:85]
	global_load_dwordx4 v[28:31], v[42:43], off offset:-4096
	global_load_dwordx4 v[20:23], v[0:1], off offset:16
	v_lshl_add_u64 v[0:1], v[40:41], 0, s[82:83]
	s_mov_b64 s[82:83], 0x3000
	v_lshl_add_u64 v[12:13], v[40:41], 0, s[82:83]
	s_lshl_b64 s[82:83], s[54:55], 1
	v_add_co_u32_e32 v48, vcc, s87, v40
	v_lshl_add_u64 v[78:79], v[94:95], 0, s[82:83]
	s_nop 0
	v_addc_co_u32_e32 v49, vcc, 0, v41, vcc
	v_lshl_add_u64 v[50:51], v[96:97], 0, s[78:79]
	v_lshl_add_u64 v[38:39], v[78:79], 0, s[58:59]
	global_load_dwordx4 v[4:7], v[42:43], off
	s_nop 0
	global_load_dwordx4 v[0:3], v[0:1], off offset:16
	s_nop 0
	global_load_dwordx4 v[16:19], v[48:49], off
	s_nop 0
	global_load_dwordx4 v[12:15], v[12:13], off offset:16
	s_nop 0
	global_load_dwordx4 v[24:27], v[50:51], off offset:16
	global_load_dwordx4 v[32:35], v[50:51], off
	s_nop 0
	v_lshl_add_u64 v[38:39], v[78:79], 0, s[60:61]
	v_lshl_add_u64 v[74:75], v[78:79], 0, s[56:57]
	s_mov_b32 s100, 0xffff3a00
	s_mov_b32 s101, -1
	v_lshl_add_u64 v[242:243], v[74:75], 0, s[100:101]
	global_load_dwordx4 v[132:135], v[242:243], off
	s_mov_b32 s100, 0xffff7c00
	s_mov_b32 s101, -1
	v_lshl_add_u64 v[242:243], v[74:75], 0, s[100:101]
	global_load_dwordx4 v[136:139], v[242:243], off
	s_mov_b32 s100, 0xffffbe00
	s_mov_b32 s101, -1
	v_lshl_add_u64 v[242:243], v[74:75], 0, s[100:101]
	global_load_dwordx4 v[140:143], v[242:243], off
	s_mov_b32 s100, 0x0
	s_mov_b32 s101, 0
	v_lshl_add_u64 v[242:243], v[74:75], 0, s[100:101]
	global_load_dwordx4 v[162:165], v[242:243], off
	s_mov_b32 s100, 0x35a00
	s_mov_b32 s101, 0
	v_lshl_add_u64 v[242:243], v[74:75], 0, s[100:101]
	global_load_dwordx4 v[166:169], v[242:243], off
	s_mov_b32 s100, 0x39c00
	s_mov_b32 s101, 0
	v_lshl_add_u64 v[242:243], v[74:75], 0, s[100:101]
	global_load_dwordx4 v[172:175], v[242:243], off
	s_mov_b32 s100, 0x3de00
	s_mov_b32 s101, 0
	v_lshl_add_u64 v[242:243], v[74:75], 0, s[100:101]
	global_load_dwordx4 v[176:179], v[242:243], off
	s_mov_b32 s100, 0x42000
	s_mov_b32 s101, 0
	v_lshl_add_u64 v[242:243], v[74:75], 0, s[100:101]
	global_load_dwordx4 v[180:183], v[242:243], off
	s_mov_b32 s100, 0x77a00
	s_mov_b32 s101, 0
	v_lshl_add_u64 v[242:243], v[74:75], 0, s[100:101]
	global_load_dwordx4 v[184:187], v[242:243], off
	s_mov_b32 s100, 0x7fe00
	s_mov_b32 s101, 0
	v_lshl_add_u64 v[242:243], v[74:75], 0, s[100:101]
	global_load_dwordx4 v[192:195], v[242:243], off
	s_mov_b32 s100, 0x7bc00
	s_mov_b32 s101, 0
	v_lshl_add_u64 v[242:243], v[74:75], 0, s[100:101]
	global_load_dwordx4 v[212:215], v[242:243], off
	s_mov_b32 s100, 0x84000
	s_mov_b32 s101, 0
	v_lshl_add_u64 v[242:243], v[74:75], 0, s[100:101]
	global_load_dwordx4 v[216:219], v[242:243], off
	s_mov_b32 s100, 0xb9a00
	s_mov_b32 s101, 0
	v_lshl_add_u64 v[242:243], v[74:75], 0, s[100:101]
	global_load_dwordx4 v[220:223], v[242:243], off
	s_mov_b32 s100, 0xbdc00
	s_mov_b32 s101, 0
	v_lshl_add_u64 v[242:243], v[74:75], 0, s[100:101]
	global_load_dwordx4 v[224:227], v[242:243], off
	s_mov_b32 s100, 0xc1e00
	s_mov_b32 s101, 0
	v_lshl_add_u64 v[242:243], v[74:75], 0, s[100:101]
	global_load_dwordx4 v[228:231], v[242:243], off
	s_mov_b32 s100, 0xc6000
	s_mov_b32 s101, 0
	v_lshl_add_u64 v[242:243], v[74:75], 0, s[100:101]
	global_load_dwordx4 v[232:235], v[242:243], off
	s_mov_b32 s100, 0xffff3a40
	s_mov_b32 s101, -1
	v_lshl_add_u64 v[242:243], v[74:75], 0, s[100:101]
	global_load_dwordx4 v[236:239], v[242:243], off
	s_mov_b32 s100, 0xffff7c40
	s_mov_b32 s101, -1
	v_lshl_add_u64 v[242:243], v[74:75], 0, s[100:101]
	global_load_dwordx4 v[246:249], v[242:243], off
	s_nop 0
	s_waitcnt vmcnt(23)
	v_mov_b32_e32 v86, v4
	s_nop 0
	s_waitcnt vmcnt(21)
	v_mov_b32_e32 v87, v16
	v_mov_b32_e32 v16, v5
	v_mov_b32_e32 v84, v6
	s_nop 0
	s_waitcnt vmcnt(17)
	v_cndmask_b32_e64 v62, 0, v135, s[2:3]
	v_cndmask_b32_e64 v56, 0, v134, s[2:3]
	v_cndmask_b32_e64 v57, 0, v133, s[2:3]
	v_cndmask_b32_e64 v58, 0, v132, s[2:3]
	s_mov_b32 s100, 0xffffbe40
	s_mov_b32 s101, -1
	v_lshl_add_u64 v[242:243], v[74:75], 0, s[100:101]
	global_load_dwordx4 v[132:135], v[242:243], off
	s_nop 0
	v_mov_b32_e32 v38, v44
	v_mov_b32_e32 v39, v28
	v_mov_b32_e32 v85, v18
	v_mov_b32_e32 v18, v7
	v_mov_b32_e32 v80, v0
	v_mov_b32_e32 v81, v12
	v_mov_b32_e32 v12, v1
	v_mov_b32_e32 v82, v2
	v_mov_b32_e32 v83, v14
	v_mov_b32_e32 v14, v3
	s_nop 0
	s_waitcnt vmcnt(17)
	v_cndmask_b32_e64 v59, 0, v136, s[4:5]
	v_cndmask_b32_e64 v63, 0, v139, s[4:5]
	v_cndmask_b32_e64 v55, 0, v137, s[4:5]
	v_lshlrev_b32_e32 v53, 16, v59
	v_lshlrev_b32_e32 v52, 16, v58
	v_pk_mul_f32 v[52:53], v[38:39], v[52:53]
	v_cndmask_b32_e64 v138, 0, v138, s[4:5]
	v_add_f32_e32 v28, v32, v52
	v_add_f32_e32 v61, v28, v53
	v_and_b32_e32 v53, 0xffff0000, v59
	v_and_b32_e32 v52, 0xffff0000, v58
	v_mov_b32_e32 v28, v45
	v_pk_mul_f32 v[44:45], v[28:29], v[52:53]
	v_lshlrev_b32_e32 v53, 16, v55
	v_add_f32_e32 v44, v33, v44
	v_add_f32_e32 v60, v44, v45
	v_lshlrev_b32_e32 v52, 16, v57
	v_mov_b32_e32 v44, v46
	v_mov_b32_e32 v45, v30
	v_pk_mul_f32 v[52:53], v[44:45], v[52:53]
	s_nop 0
	v_add_f32_e32 v30, v34, v52
	v_add_f32_e32 v59, v30, v53
	v_and_b32_e32 v53, 0xffff0000, v55
	v_and_b32_e32 v52, 0xffff0000, v57
	v_mov_b32_e32 v30, v47
	v_pk_mul_f32 v[46:47], v[30:31], v[52:53]
	v_lshlrev_b32_e32 v53, 16, v138
	v_add_f32_e32 v46, v35, v46
	v_add_f32_e32 v58, v46, v47
	v_lshlrev_b32_e32 v52, 16, v56
	v_mov_b32_e32 v46, v8
	v_mov_b32_e32 v47, v20
	v_pk_mul_f32 v[52:53], v[46:47], v[52:53]
	v_mov_b32_e32 v20, v9
	v_add_f32_e32 v8, v24, v52
	v_add_f32_e32 v55, v8, v53
	v_and_b32_e32 v53, 0xffff0000, v138
	s_mov_b32 s100, 0x40
	s_mov_b32 s101, 0
	v_lshl_add_u64 v[242:243], v[74:75], 0, s[100:101]
	global_load_dwordx4 v[136:139], v[242:243], off
	v_and_b32_e32 v52, 0xffff0000, v56
	v_pk_mul_f32 v[8:9], v[20:21], v[52:53]
	v_mov_b32_e32 v56, v10
	v_add_f32_e32 v8, v25, v8
	v_add_f32_e32 v54, v8, v9
	v_lshlrev_b32_e32 v9, 16, v63
	v_lshlrev_b32_e32 v8, 16, v62
	v_mov_b32_e32 v57, v22
	v_pk_mul_f32 v[8:9], v[56:57], v[8:9]
	v_mov_b32_e32 v22, v11
	v_add_f32_e32 v8, v26, v8
	v_add_f32_e32 v53, v8, v9
	v_and_b32_e32 v9, 0xffff0000, v63
	v_and_b32_e32 v8, 0xffff0000, v62
	v_pk_mul_f32 v[8:9], v[22:23], v[8:9]
	s_nop 0
	v_add_f32_e32 v8, v27, v8
	v_add_f32_e32 v52, v8, v9
	v_lshl_add_u64 v[8:9], v[78:79], 0, s[62:63]
	s_nop 0
	s_nop 0
	s_waitcnt vmcnt(17)
	v_cndmask_b32_e64 v62, 0, v143, s[8:9]
	v_cndmask_b32_e64 v63, 0, v142, s[8:9]
	v_cndmask_b32_e64 v64, 0, v141, s[8:9]
	v_cndmask_b32_e64 v65, 0, v140, s[8:9]
	s_mov_b32 s100, 0x35a40
	s_mov_b32 s101, 0
	v_lshl_add_u64 v[242:243], v[74:75], 0, s[100:101]
	global_load_dwordx4 v[140:143], v[242:243], off
	s_nop 0
	s_nop 0
	s_waitcnt vmcnt(17)
	v_cndmask_b32_e64 v67, 0, v162, s[10:11]
	v_cndmask_b32_e64 v66, 0, v163, s[10:11]
	v_lshlrev_b32_e32 v9, 16, v67
	v_lshlrev_b32_e32 v8, 16, v65
	v_pk_mul_f32 v[8:9], v[86:87], v[8:9]
	v_cndmask_b32_e64 v164, 0, v164, s[10:11]
	v_add_f32_e32 v4, v61, v8
	v_add_f32_e32 v61, v4, v9
	v_and_b32_e32 v9, 0xffff0000, v67
	v_and_b32_e32 v8, 0xffff0000, v65
	v_pk_mul_f32 v[4:5], v[16:17], v[8:9]
	v_cndmask_b32_e64 v165, 0, v165, s[10:11]
	v_add_f32_e32 v4, v60, v4
	v_add_f32_e32 v8, v4, v5
	v_lshlrev_b32_e32 v5, 16, v66
	v_lshlrev_b32_e32 v4, 16, v64
	v_pk_mul_f32 v[4:5], v[84:85], v[4:5]
	s_nop 0
	v_add_f32_e32 v4, v59, v4
	v_add_f32_e32 v6, v4, v5
	v_and_b32_e32 v5, 0xffff0000, v66
	v_and_b32_e32 v4, 0xffff0000, v64
	v_pk_mul_f32 v[4:5], v[18:19], v[4:5]
	s_nop 0
	v_add_f32_e32 v4, v58, v4
	v_add_f32_e32 v7, v4, v5
	v_lshlrev_b32_e32 v5, 16, v164
	v_lshlrev_b32_e32 v4, 16, v63
	v_pk_mul_f32 v[4:5], v[80:81], v[4:5]
	s_nop 0
	v_add_f32_e32 v0, v55, v4
	v_add_f32_e32 v9, v0, v5
	v_and_b32_e32 v5, 0xffff0000, v164
	v_and_b32_e32 v4, 0xffff0000, v63
	v_pk_mul_f32 v[0:1], v[12:13], v[4:5]
	s_nop 0
	v_add_f32_e32 v0, v54, v0
	v_add_f32_e32 v4, v0, v1
	v_lshlrev_b32_e32 v1, 16, v165
	v_lshlrev_b32_e32 v0, 16, v62
	v_pk_mul_f32 v[0:1], v[82:83], v[0:1]
	v_cvt_pk_bf16_f32 v2, v9, v4
	s_nop 0
	v_add_f32_e32 v0, v53, v0
	v_add_f32_e32 v5, v0, v1
	v_and_b32_e32 v1, 0xffff0000, v165
	s_mov_b32 s100, 0x39c40
	s_mov_b32 s101, 0
	v_lshl_add_u64 v[242:243], v[74:75], 0, s[100:101]
	global_load_dwordx4 v[162:165], v[242:243], off
	v_and_b32_e32 v0, 0xffff0000, v62
	v_pk_mul_f32 v[0:1], v[14:15], v[0:1]
	s_nop 0
	v_add_f32_e32 v0, v52, v0
	v_add_f32_e32 v3, v0, v1
	v_cvt_pk_bf16_f32 v0, v61, v8
	v_cvt_pk_bf16_f32 v1, v6, v7
	v_cvt_pk_bf16_f32 v3, v5, v3
	s_mov_b32 s81, 0x35000
	v_add_co_u32_e32 v68, vcc, s81, v74
	s_mov_b32 s81, 0x39000
	s_nop 0
	v_addc_co_u32_e32 v69, vcc, 0, v75, vcc
	s_nop 0
	v_add_co_u32_e32 v70, vcc, s81, v74
	s_mov_b32 s81, 0x3d000
	s_nop 0
	v_addc_co_u32_e32 v71, vcc, 0, v75, vcc
	v_add_co_u32_e32 v72, vcc, s81, v74
	s_mov_b32 s81, 0x42000
	s_nop 0
	v_addc_co_u32_e32 v73, vcc, 0, v75, vcc
	v_add_co_u32_e32 v76, vcc, s81, v74
	s_nop 0
	s_waitcnt vmcnt(17)
	v_cndmask_b32_e64 v10, 0, v169, s[12:13]
	v_cndmask_b32_e64 v11, 0, v168, s[12:13]
	v_cndmask_b32_e64 v8, 0, v167, s[12:13]
	v_cndmask_b32_e64 v9, 0, v166, s[12:13]
	s_mov_b32 s100, 0x3de40
	s_mov_b32 s101, 0
	v_lshl_add_u64 v[242:243], v[74:75], 0, s[100:101]
	global_load_dwordx4 v[166:169], v[242:243], off
	s_nop 0
	v_addc_co_u32_e32 v77, vcc, 0, v75, vcc
	s_nop 0
	s_waitcnt vmcnt(17)
	v_cndmask_b32_e64 v53, 0, v172, s[14:15]
	v_cndmask_b32_e64 v52, 0, v175, s[14:15]
	v_cndmask_b32_e64 v7, 0, v173, s[14:15]
	v_lshlrev_b32_e32 v5, 16, v53
	v_lshlrev_b32_e32 v4, 16, v9
	v_pk_mul_f32 v[4:5], v[38:39], v[4:5]
	v_cndmask_b32_e64 v174, 0, v174, s[14:15]
	v_add_f32_e32 v4, v32, v4
	v_add_f32_e32 v58, v4, v5
	v_and_b32_e32 v5, 0xffff0000, v53
	v_and_b32_e32 v4, 0xffff0000, v9
	v_pk_mul_f32 v[4:5], v[28:29], v[4:5]
	s_nop 0
	v_add_f32_e32 v4, v33, v4
	v_add_f32_e32 v59, v4, v5
	v_lshlrev_b32_e32 v5, 16, v7
	v_lshlrev_b32_e32 v4, 16, v8
	v_pk_mul_f32 v[4:5], v[44:45], v[4:5]
	s_nop 0
	v_add_f32_e32 v4, v34, v4
	v_add_f32_e32 v9, v4, v5
	v_and_b32_e32 v5, 0xffff0000, v7
	v_and_b32_e32 v4, 0xffff0000, v8
	v_pk_mul_f32 v[4:5], v[30:31], v[4:5]
	s_nop 0
	v_add_f32_e32 v4, v35, v4
	v_add_f32_e32 v8, v4, v5
	v_lshlrev_b32_e32 v5, 16, v174
	v_lshlrev_b32_e32 v4, 16, v11
	v_pk_mul_f32 v[4:5], v[46:47], v[4:5]
	s_nop 0
	v_add_f32_e32 v4, v24, v4
	v_add_f32_e32 v7, v4, v5
	v_and_b32_e32 v5, 0xffff0000, v174
	s_mov_b32 s100, 0x42040
	s_mov_b32 s101, 0
	v_lshl_add_u64 v[242:243], v[74:75], 0, s[100:101]
	global_load_dwordx4 v[172:175], v[242:243], off
	v_and_b32_e32 v4, 0xffff0000, v11
	v_pk_mul_f32 v[4:5], v[20:21], v[4:5]
	v_and_b32_e32 v11, 0xffff0000, v52
	v_add_f32_e32 v4, v25, v4
	v_add_f32_e32 v6, v4, v5
	v_lshlrev_b32_e32 v5, 16, v52
	s_nop 0
	v_lshlrev_b32_e32 v4, 16, v10
	v_pk_mul_f32 v[4:5], v[56:57], v[4:5]
	v_and_b32_e32 v10, 0xffff0000, v10
	v_add_f32_e32 v4, v26, v4
	v_pk_mul_f32 v[10:11], v[22:23], v[10:11]
	v_add_f32_e32 v5, v4, v5
	v_add_f32_e32 v4, v27, v10
	v_add_f32_e32 v4, v4, v11
	s_nop 0
	s_waitcnt vmcnt(17)
	v_cndmask_b32_e64 v60, 0, v179, s[16:17]
	v_cndmask_b32_e64 v61, 0, v178, s[16:17]
	v_cndmask_b32_e64 v62, 0, v177, s[16:17]
	v_cndmask_b32_e64 v63, 0, v176, s[16:17]
	s_mov_b32 s100, 0x77a40
	s_mov_b32 s101, 0
	v_lshl_add_u64 v[242:243], v[74:75], 0, s[100:101]
	global_load_dwordx4 v[176:179], v[242:243], off
	s_nop 0
	v_lshlrev_b32_e32 v10, 16, v63
	s_nop 0
	s_waitcnt vmcnt(17)
	v_cndmask_b32_e64 v180, 0, v180, s[10:11]
	v_lshlrev_b32_e32 v11, 16, v180
	v_pk_mul_f32 v[10:11], v[86:87], v[10:11]
	v_cndmask_b32_e64 v181, 0, v181, s[10:11]
	v_add_f32_e32 v10, v58, v10
	v_add_f32_e32 v58, v10, v11
	v_and_b32_e32 v11, 0xffff0000, v180
	v_and_b32_e32 v10, 0xffff0000, v63
	v_pk_mul_f32 v[10:11], v[16:17], v[10:11]
	v_cndmask_b32_e64 v182, 0, v182, s[10:11]
	v_add_f32_e32 v10, v59, v10
	v_add_f32_e32 v52, v10, v11
	v_lshlrev_b32_e32 v11, 16, v181
	v_lshlrev_b32_e32 v10, 16, v62
	v_pk_mul_f32 v[10:11], v[84:85], v[10:11]
	v_cndmask_b32_e64 v183, 0, v183, s[10:11]
	v_add_f32_e32 v9, v9, v10
	v_add_f32_e32 v59, v9, v11
	v_and_b32_e32 v11, 0xffff0000, v181
	v_and_b32_e32 v10, 0xffff0000, v62
	v_pk_mul_f32 v[10:11], v[18:19], v[10:11]
	v_lshlrev_b32_e32 v9, 16, v182
	v_add_f32_e32 v8, v8, v10
	v_add_f32_e32 v10, v8, v11
	v_lshlrev_b32_e32 v8, 16, v61
	v_pk_mul_f32 v[8:9], v[80:81], v[8:9]
	s_nop 0
	v_add_f32_e32 v7, v7, v8
	v_add_f32_e32 v11, v7, v9
	v_and_b32_e32 v9, 0xffff0000, v182
	v_and_b32_e32 v8, 0xffff0000, v61
	v_pk_mul_f32 v[8:9], v[12:13], v[8:9]
	v_lshlrev_b32_e32 v7, 16, v183
	v_add_f32_e32 v6, v6, v8
	v_add_f32_e32 v8, v6, v9
	v_lshlrev_b32_e32 v6, 16, v60
	v_pk_mul_f32 v[6:7], v[82:83], v[6:7]
	s_nop 0
	v_add_f32_e32 v5, v5, v6
	v_add_f32_e32 v9, v5, v7
	v_and_b32_e32 v7, 0xffff0000, v183
	s_mov_b32 s100, 0x7bc40
	s_mov_b32 s101, 0
	v_lshl_add_u64 v[242:243], v[74:75], 0, s[100:101]
	global_load_dwordx4 v[180:183], v[242:243], off
	v_and_b32_e32 v6, 0xffff0000, v60
	v_pk_mul_f32 v[6:7], v[14:15], v[6:7]
	v_cvt_pk_bf16_f32 v5, v59, v10
	s_nop 0
	v_add_f32_e32 v4, v4, v6
	v_add_f32_e32 v7, v4, v7
	v_cvt_pk_bf16_f32 v4, v58, v52
	v_cvt_pk_bf16_f32 v6, v11, v8
	v_cvt_pk_bf16_f32 v7, v9, v7
	s_mov_b32 s81, 0x77000
	v_add_co_u32_e32 v60, vcc, s81, v74
	s_mov_b32 s81, 0x7b000
	s_nop 0
	v_addc_co_u32_e32 v61, vcc, 0, v75, vcc
	s_nop 0
	v_add_co_u32_e32 v62, vcc, s81, v74
	s_mov_b32 s81, 0x7f000
	s_nop 0
	v_addc_co_u32_e32 v63, vcc, 0, v75, vcc
	v_add_co_u32_e32 v64, vcc, s81, v74
	s_mov_b32 s81, 0x84000
	s_nop 0
	v_addc_co_u32_e32 v65, vcc, 0, v75, vcc
	s_nop 0
	v_add_co_u32_e32 v66, vcc, s81, v74
	s_nop 0
	s_waitcnt vmcnt(17)
	v_cndmask_b32_e64 v54, 0, v187, s[18:19]
	v_cndmask_b32_e64 v55, 0, v186, s[18:19]
	v_cndmask_b32_e64 v52, 0, v185, s[18:19]
	v_cndmask_b32_e64 v53, 0, v184, s[18:19]
	s_mov_b32 s100, 0x7fe40
	s_mov_b32 s101, 0
	v_lshl_add_u64 v[242:243], v[74:75], 0, s[100:101]
	global_load_dwordx4 v[184:187], v[242:243], off
	s_nop 0
	v_addc_co_u32_e32 v67, vcc, 0, v75, vcc
	s_nop 0
	s_waitcnt vmcnt(17)
	v_cndmask_b32_e64 v123, 0, v194, s[22:23]
	v_cndmask_b32_e64 v124, 0, v193, s[22:23]
	v_cndmask_b32_e64 v125, 0, v192, s[22:23]
	s_nop 0
	s_waitcnt vmcnt(16)
	v_cndmask_b32_e64 v59, 0, v212, s[20:21]
	v_cndmask_b32_e64 v58, 0, v215, s[20:21]
	v_cndmask_b32_e64 v11, 0, v213, s[20:21]
	v_lshlrev_b32_e32 v9, 16, v59
	v_lshlrev_b32_e32 v8, 16, v53
	v_pk_mul_f32 v[8:9], v[38:39], v[8:9]
	v_cndmask_b32_e64 v214, 0, v214, s[20:21]
	v_add_f32_e32 v8, v32, v8
	v_add_f32_e32 v122, v8, v9
	v_and_b32_e32 v9, 0xffff0000, v59
	v_and_b32_e32 v8, 0xffff0000, v53
	v_pk_mul_f32 v[8:9], v[28:29], v[8:9]
	s_nop 0
	v_add_f32_e32 v8, v33, v8
	v_add_f32_e32 v59, v8, v9
	v_lshlrev_b32_e32 v9, 16, v11
	v_lshlrev_b32_e32 v8, 16, v52
	v_pk_mul_f32 v[8:9], v[44:45], v[8:9]
	s_nop 0
	v_add_f32_e32 v8, v34, v8
	v_add_f32_e32 v53, v8, v9
	v_and_b32_e32 v9, 0xffff0000, v11
	v_and_b32_e32 v8, 0xffff0000, v52
	v_pk_mul_f32 v[8:9], v[30:31], v[8:9]
	s_nop 0
	v_add_f32_e32 v8, v35, v8
	v_add_f32_e32 v52, v8, v9
	v_lshlrev_b32_e32 v9, 16, v214
	v_lshlrev_b32_e32 v8, 16, v55
	v_pk_mul_f32 v[8:9], v[46:47], v[8:9]
	s_nop 0
	v_add_f32_e32 v8, v24, v8
	v_add_f32_e32 v11, v8, v9
	v_and_b32_e32 v9, 0xffff0000, v214
	v_and_b32_e32 v8, 0xffff0000, v55
	v_pk_mul_f32 v[8:9], v[20:21], v[8:9]
	v_and_b32_e32 v55, 0xffff0000, v58
	v_add_f32_e32 v8, v25, v8
	v_add_f32_e32 v10, v8, v9
	v_lshlrev_b32_e32 v9, 16, v58
	v_cndmask_b32_e64 v58, 0, v195, s[22:23]
	s_mov_b32 s100, 0x84040
	s_mov_b32 s101, 0
	v_lshl_add_u64 v[242:243], v[74:75], 0, s[100:101]
	global_load_dwordx4 v[192:195], v[242:243], off
	s_mov_b32 s100, 0xb9a40
	s_mov_b32 s101, 0
	v_lshl_add_u64 v[242:243], v[74:75], 0, s[100:101]
	global_load_dwordx4 v[212:215], v[242:243], off
	s_nop 0
	v_lshlrev_b32_e32 v8, 16, v54
	v_pk_mul_f32 v[8:9], v[56:57], v[8:9]
	v_and_b32_e32 v54, 0xffff0000, v54
	v_add_f32_e32 v8, v26, v8
	v_pk_mul_f32 v[54:55], v[22:23], v[54:55]
	v_add_f32_e32 v9, v8, v9
	v_add_f32_e32 v8, v27, v54
	v_add_f32_e32 v8, v8, v55
	v_lshlrev_b32_e32 v54, 16, v125
	s_nop 0
	s_waitcnt vmcnt(17)
	v_cndmask_b32_e64 v216, 0, v216, s[10:11]
	v_lshlrev_b32_e32 v55, 16, v216
	v_pk_mul_f32 v[54:55], v[86:87], v[54:55]
	v_cndmask_b32_e64 v217, 0, v217, s[10:11]
	v_add_f32_e32 v54, v122, v54
	v_add_f32_e32 v122, v54, v55
	v_and_b32_e32 v55, 0xffff0000, v216
	v_and_b32_e32 v54, 0xffff0000, v125
	v_pk_mul_f32 v[54:55], v[16:17], v[54:55]
	v_cndmask_b32_e64 v218, 0, v218, s[10:11]
	v_add_f32_e32 v54, v59, v54
	v_add_f32_e32 v59, v54, v55
	v_lshlrev_b32_e32 v55, 16, v217
	v_lshlrev_b32_e32 v54, 16, v124
	v_pk_mul_f32 v[54:55], v[84:85], v[54:55]
	v_cndmask_b32_e64 v219, 0, v219, s[10:11]
	v_add_f32_e32 v53, v53, v54
	v_add_f32_e32 v118, v53, v55
	v_and_b32_e32 v55, 0xffff0000, v217
	v_and_b32_e32 v54, 0xffff0000, v124
	v_pk_mul_f32 v[54:55], v[18:19], v[54:55]
	v_lshlrev_b32_e32 v53, 16, v218
	v_add_f32_e32 v52, v52, v54
	v_add_f32_e32 v54, v52, v55
	v_lshlrev_b32_e32 v52, 16, v123
	v_pk_mul_f32 v[52:53], v[80:81], v[52:53]
	s_nop 0
	v_add_f32_e32 v11, v11, v52
	v_add_f32_e32 v55, v11, v53
	v_and_b32_e32 v53, 0xffff0000, v218
	v_and_b32_e32 v52, 0xffff0000, v123
	v_pk_mul_f32 v[52:53], v[12:13], v[52:53]
	v_lshlrev_b32_e32 v11, 16, v219
	v_add_f32_e32 v10, v10, v52
	v_add_f32_e32 v52, v10, v53
	v_lshlrev_b32_e32 v10, 16, v58
	v_pk_mul_f32 v[10:11], v[82:83], v[10:11]
	s_nop 0
	v_add_f32_e32 v9, v9, v10
	v_add_f32_e32 v53, v9, v11
	v_and_b32_e32 v11, 0xffff0000, v219
	s_mov_b32 s100, 0xbdc40
	s_mov_b32 s101, 0
	v_lshl_add_u64 v[242:243], v[74:75], 0, s[100:101]
	global_load_dwordx4 v[216:219], v[242:243], off
	v_and_b32_e32 v10, 0xffff0000, v58
	v_pk_mul_f32 v[10:11], v[14:15], v[10:11]
	v_cvt_pk_bf16_f32 v9, v118, v54
	s_nop 0
	v_add_f32_e32 v8, v8, v10
	v_add_f32_e32 v11, v8, v11
	v_cvt_pk_bf16_f32 v8, v122, v59
	v_cvt_pk_bf16_f32 v10, v55, v52
	v_cvt_pk_bf16_f32 v11, v53, v11
	s_mov_b32 s81, 0xb9000
	v_add_co_u32_e32 v52, vcc, s81, v74
	s_mov_b32 s81, 0xbd000
	s_nop 0
	v_addc_co_u32_e32 v53, vcc, 0, v75, vcc
	s_nop 0
	v_add_co_u32_e32 v54, vcc, s81, v74
	s_mov_b32 s81, 0xc1000
	s_nop 0
	v_addc_co_u32_e32 v55, vcc, 0, v75, vcc
	s_nop 0
	s_waitcnt vmcnt(17)
	v_cndmask_b32_e64 v122, 0, v223, s[0:1]
	v_cndmask_b32_e64 v123, 0, v222, s[0:1]
	v_cndmask_b32_e64 v124, 0, v221, s[0:1]
	v_cndmask_b32_e64 v125, 0, v220, s[0:1]
	s_mov_b32 s100, 0xc1e40
	s_mov_b32 s101, 0
	v_lshl_add_u64 v[242:243], v[74:75], 0, s[100:101]
	global_load_dwordx4 v[220:223], v[242:243], off
	s_nop 0
	v_lshlrev_b32_e32 v58, 16, v125
	s_nop 0
	s_waitcnt vmcnt(17)
	v_cndmask_b32_e64 v224, 0, v224, s[24:25]
	v_lshlrev_b32_e32 v59, 16, v224
	v_pk_mul_f32 v[38:39], v[38:39], v[58:59]
	v_cndmask_b32_e64 v225, 0, v225, s[24:25]
	v_add_f32_e32 v32, v32, v38
	v_add_f32_e32 v126, v32, v39
	v_and_b32_e32 v39, 0xffff0000, v224
	v_and_b32_e32 v38, 0xffff0000, v125
	v_pk_mul_f32 v[28:29], v[28:29], v[38:39]
	v_cndmask_b32_e64 v226, 0, v226, s[24:25]
	v_add_f32_e32 v28, v33, v28
	v_add_f32_e32 v33, v28, v29
	v_lshlrev_b32_e32 v29, 16, v225
	v_lshlrev_b32_e32 v28, 16, v124
	v_pk_mul_f32 v[28:29], v[44:45], v[28:29]
	v_cndmask_b32_e64 v227, 0, v227, s[24:25]
	v_add_f32_e32 v28, v34, v28
	v_add_f32_e32 v32, v28, v29
	v_and_b32_e32 v29, 0xffff0000, v225
	v_and_b32_e32 v28, 0xffff0000, v124
	v_pk_mul_f32 v[28:29], v[30:31], v[28:29]
	v_lshlrev_b32_e32 v31, 16, v226
	v_lshlrev_b32_e32 v30, 16, v123
	v_pk_mul_f32 v[30:31], v[46:47], v[30:31]
	v_add_f32_e32 v28, v35, v28
	v_add_f32_e32 v24, v24, v30
	v_add_f32_e32 v29, v28, v29
	v_add_f32_e32 v28, v24, v31
	v_and_b32_e32 v31, 0xffff0000, v226
	v_and_b32_e32 v30, 0xffff0000, v123
	v_pk_mul_f32 v[20:21], v[20:21], v[30:31]
	v_and_b32_e32 v31, 0xffff0000, v227
	v_add_f32_e32 v20, v25, v20
	v_add_f32_e32 v24, v20, v21
	v_lshlrev_b32_e32 v21, 16, v227
	s_mov_b32 s100, 0xc6040
	s_mov_b32 s101, 0
	v_lshl_add_u64 v[242:243], v[74:75], 0, s[100:101]
	global_load_dwordx4 v[224:227], v[242:243], off
	v_lshlrev_b32_e32 v20, 16, v122
	v_pk_mul_f32 v[20:21], v[56:57], v[20:21]
	v_add_co_u32_e32 v56, vcc, s81, v74
	s_mov_b32 s81, 0xc6000
	s_nop 0
	v_addc_co_u32_e32 v57, vcc, 0, v75, vcc
	s_nop 0
	v_and_b32_e32 v30, 0xffff0000, v122
	v_add_co_u32_e32 v58, vcc, s81, v74
	v_add_f32_e32 v20, v26, v20
	v_pk_mul_f32 v[22:23], v[22:23], v[30:31]
	v_addc_co_u32_e32 v59, vcc, 0, v75, vcc
	v_add_f32_e32 v21, v20, v21
	v_add_f32_e32 v20, v27, v22
	v_add_f32_e32 v20, v20, v23
	s_nop 0
	s_waitcnt vmcnt(17)
	v_cndmask_b32_e64 v25, 0, v231, s[26:27]
	v_cndmask_b32_e64 v26, 0, v230, s[26:27]
	v_cndmask_b32_e64 v27, 0, v229, s[26:27]
	v_cndmask_b32_e64 v30, 0, v228, s[26:27]
	s_nop 0
	v_lshlrev_b32_e32 v22, 16, v30
	s_nop 0
	s_waitcnt vmcnt(16)
	v_cndmask_b32_e64 v38, 0, v232, s[10:11]
	v_lshlrev_b32_e32 v23, 16, v38
	v_pk_mul_f32 v[22:23], v[86:87], v[22:23]
	v_cndmask_b32_e64 v35, 0, v233, s[10:11]
	v_add_f32_e32 v22, v126, v22
	v_add_f32_e32 v39, v22, v23
	v_and_b32_e32 v23, 0xffff0000, v38
	v_and_b32_e32 v22, 0xffff0000, v30
	v_pk_mul_f32 v[16:17], v[16:17], v[22:23]
	v_cndmask_b32_e64 v34, 0, v234, s[10:11]
	v_add_f32_e32 v16, v33, v16
	v_add_f32_e32 v22, v16, v17
	v_lshlrev_b32_e32 v17, 16, v35
	v_lshlrev_b32_e32 v16, 16, v27
	v_pk_mul_f32 v[16:17], v[84:85], v[16:17]
	v_cndmask_b32_e64 v31, 0, v235, s[10:11]
	v_add_f32_e32 v16, v32, v16
	v_add_f32_e32 v23, v16, v17
	v_and_b32_e32 v17, 0xffff0000, v35
	v_and_b32_e32 v16, 0xffff0000, v27
	v_pk_mul_f32 v[16:17], v[18:19], v[16:17]
	s_nop 0
	v_add_f32_e32 v16, v29, v16
	v_add_f32_e32 v18, v16, v17
	v_lshlrev_b32_e32 v17, 16, v34
	v_lshlrev_b32_e32 v16, 16, v26
	v_pk_mul_f32 v[16:17], v[80:81], v[16:17]
	s_nop 0
	v_add_f32_e32 v16, v28, v16
	v_add_f32_e32 v19, v16, v17
	v_and_b32_e32 v17, 0xffff0000, v34
	v_and_b32_e32 v16, 0xffff0000, v26
	v_pk_mul_f32 v[12:13], v[12:13], v[16:17]
	s_nop 0
	v_add_f32_e32 v12, v24, v12
	v_add_f32_e32 v16, v12, v13
	v_lshlrev_b32_e32 v13, 16, v31
	v_lshlrev_b32_e32 v12, 16, v25
	v_pk_mul_f32 v[12:13], v[82:83], v[12:13]
	s_nop 0
	v_add_f32_e32 v12, v21, v12
	v_add_f32_e32 v17, v12, v13
	v_and_b32_e32 v13, 0xffff0000, v31
	v_and_b32_e32 v12, 0xffff0000, v25
	v_pk_mul_f32 v[12:13], v[14:15], v[12:13]
	v_cvt_pk_bf16_f32 v14, v19, v16
	s_nop 0
	v_add_f32_e32 v12, v20, v12
	v_add_f32_e32 v15, v12, v13
	v_cvt_pk_bf16_f32 v12, v39, v22
	v_cvt_pk_bf16_f32 v13, v23, v18
	v_cvt_pk_bf16_f32 v15, v17, v15
	global_load_dwordx4 v[24:27], v144, s[84:85] offset:144
	global_load_dwordx4 v[80:83], v144, s[84:85] offset:128
	s_mov_b64 s[84:85], 0x1080
	v_lshl_add_u64 v[16:17], v[40:41], 0, s[84:85]
	s_mov_b64 s[84:85], 0x2080
	global_load_dwordx4 v[44:47], v[36:37], off offset:128
	s_nop 0
	global_load_dwordx4 v[36:39], v[16:17], off offset:16
	v_lshl_add_u64 v[16:17], v[40:41], 0, s[84:85]
	s_mov_b64 s[84:85], 0x3080
	v_lshl_add_u64 v[120:121], v[78:79], 0, 64
	v_lshl_add_u64 v[28:29], v[40:41], 0, s[84:85]
	v_lshl_add_u64 v[78:79], v[120:121], 0, s[58:59]
	global_load_dwordx4 v[20:23], v[42:43], off offset:128
	s_nop 0
	global_load_dwordx4 v[16:19], v[16:17], off offset:16
	s_nop 0
	global_load_dwordx4 v[32:35], v[48:49], off offset:128
	s_nop 0
	global_load_dwordx4 v[28:31], v[28:29], off offset:16
	s_nop 0
	global_load_dwordx4 v[40:43], v[50:51], off offset:144
	s_nop 0
	global_load_dwordx4 v[48:51], v[50:51], off offset:128
	s_ashr_i32 s81, s80, 31
	s_nop 0
	v_lshl_add_u64 v[78:79], v[120:121], 0, s[60:61]
	s_nop 0
	s_waitcnt vmcnt(25)
	v_cndmask_b32_e64 v122, 0, v239, s[2:3]
	v_cndmask_b32_e64 v123, 0, v238, s[2:3]
	v_cndmask_b32_e64 v124, 0, v237, s[2:3]
	v_cndmask_b32_e64 v118, 0, v236, s[2:3]
	s_nop 0
	s_waitcnt vmcnt(8)
	v_mov_b32_e32 v78, v80
	s_waitcnt vmcnt(7)
	v_mov_b32_e32 v79, v44
	s_nop 0
	v_cndmask_b32_e64 v126, 0, v249, s[4:5]
	v_cndmask_b32_e64 v87, 0, v246, s[4:5]
	v_cndmask_b32_e64 v127, 0, v248, s[4:5]
	v_cndmask_b32_e64 v86, 0, v247, s[4:5]
	v_lshlrev_b32_e32 v85, 16, v87
	v_lshlrev_b32_e32 v84, 16, v118
	v_pk_mul_f32 v[84:85], v[78:79], v[84:85]
	s_nop 0
	s_waitcnt vmcnt(0)
	v_add_f32_e32 v44, v48, v84
	v_add_f32_e32 v119, v44, v85
	v_and_b32_e32 v85, 0xffff0000, v87
	v_and_b32_e32 v84, 0xffff0000, v118
	v_mov_b32_e32 v44, v81
	v_pk_mul_f32 v[80:81], v[44:45], v[84:85]
	v_lshlrev_b32_e32 v85, 16, v86
	v_add_f32_e32 v80, v49, v80
	v_add_f32_e32 v118, v80, v81
	v_lshlrev_b32_e32 v84, 16, v124
	v_mov_b32_e32 v80, v82
	v_mov_b32_e32 v81, v46
	v_pk_mul_f32 v[84:85], v[80:81], v[84:85]
	s_nop 0
	v_add_f32_e32 v46, v50, v84
	v_add_f32_e32 v87, v46, v85
	v_and_b32_e32 v85, 0xffff0000, v86
	v_and_b32_e32 v84, 0xffff0000, v124
	v_mov_b32_e32 v46, v83
	v_pk_mul_f32 v[82:83], v[46:47], v[84:85]
	v_lshlrev_b32_e32 v85, 16, v127
	v_add_f32_e32 v82, v51, v82
	v_add_f32_e32 v86, v82, v83
	v_lshlrev_b32_e32 v84, 16, v123
	v_mov_b32_e32 v82, v24
	v_mov_b32_e32 v83, v36
	v_pk_mul_f32 v[84:85], v[82:83], v[84:85]
	v_mov_b32_e32 v36, v25
	v_add_f32_e32 v24, v40, v84
	v_add_f32_e32 v125, v24, v85
	v_and_b32_e32 v85, 0xffff0000, v127
	v_and_b32_e32 v84, 0xffff0000, v123
	v_pk_mul_f32 v[24:25], v[36:37], v[84:85]
	v_mov_b32_e32 v84, v26
	v_add_f32_e32 v24, v41, v24
	v_add_f32_e32 v124, v24, v25
	v_lshlrev_b32_e32 v25, 16, v126
	v_lshlrev_b32_e32 v24, 16, v122
	v_mov_b32_e32 v85, v38
	v_pk_mul_f32 v[24:25], v[84:85], v[24:25]
	v_mov_b32_e32 v38, v27
	v_add_f32_e32 v24, v42, v24
	v_add_f32_e32 v123, v24, v25
	v_and_b32_e32 v25, 0xffff0000, v126
	v_and_b32_e32 v24, 0xffff0000, v122
	v_pk_mul_f32 v[24:25], v[38:39], v[24:25]
	s_nop 0
	v_add_f32_e32 v24, v43, v24
	v_add_f32_e32 v122, v24, v25
	v_lshl_add_u64 v[24:25], v[120:121], 0, s[62:63]
	s_nop 0
	v_mov_b32_e32 v120, v20
	v_mov_b32_e32 v121, v32
	v_mov_b32_e32 v32, v21
	s_nop 0
	v_cndmask_b32_e64 v126, 0, v135, s[8:9]
	v_cndmask_b32_e64 v127, 0, v134, s[8:9]
	v_cndmask_b32_e64 v128, 0, v133, s[8:9]
	v_cndmask_b32_e64 v129, 0, v132, s[8:9]
	s_nop 0
	s_nop 0
	v_cndmask_b32_e64 v75, 0, v136, s[10:11]
	v_cndmask_b32_e64 v74, 0, v137, s[10:11]
	v_lshlrev_b32_e32 v25, 16, v75
	v_lshlrev_b32_e32 v24, 16, v129
	v_pk_mul_f32 v[24:25], v[120:121], v[24:25]
	v_cndmask_b32_e64 v138, 0, v138, s[10:11]
	v_add_f32_e32 v20, v119, v24
	v_add_f32_e32 v130, v20, v25
	v_and_b32_e32 v25, 0xffff0000, v75
	v_and_b32_e32 v24, 0xffff0000, v129
	v_pk_mul_f32 v[20:21], v[32:33], v[24:25]
	v_mov_b32_e32 v119, v34
	v_add_f32_e32 v20, v118, v20
	v_add_f32_e32 v24, v20, v21
	v_lshlrev_b32_e32 v21, 16, v74
	v_lshlrev_b32_e32 v20, 16, v128
	v_mov_b32_e32 v118, v22
	v_pk_mul_f32 v[20:21], v[118:119], v[20:21]
	v_mov_b32_e32 v34, v23
	v_add_f32_e32 v20, v87, v20
	v_add_f32_e32 v22, v20, v21
	v_and_b32_e32 v21, 0xffff0000, v74
	v_and_b32_e32 v20, 0xffff0000, v128
	v_pk_mul_f32 v[20:21], v[34:35], v[20:21]
	v_mov_b32_e32 v87, v28
	v_add_f32_e32 v20, v86, v20
	v_add_f32_e32 v23, v20, v21
	v_lshlrev_b32_e32 v21, 16, v138
	v_lshlrev_b32_e32 v20, 16, v127
	v_mov_b32_e32 v86, v16
	v_pk_mul_f32 v[20:21], v[86:87], v[20:21]
	v_mov_b32_e32 v28, v17
	v_add_f32_e32 v16, v125, v20
	v_add_f32_e32 v25, v16, v21
	v_and_b32_e32 v21, 0xffff0000, v138
	v_and_b32_e32 v20, 0xffff0000, v127
	v_pk_mul_f32 v[16:17], v[28:29], v[20:21]
	v_cndmask_b32_e64 v139, 0, v139, s[10:11]
	v_add_f32_e32 v16, v124, v16
	v_add_f32_e32 v20, v16, v17
	v_lshlrev_b32_e32 v17, 16, v139
	v_lshlrev_b32_e32 v16, 16, v126
	v_mov_b32_e32 v74, v18
	v_mov_b32_e32 v75, v30
	v_pk_mul_f32 v[16:17], v[74:75], v[16:17]
	v_mov_b32_e32 v30, v19
	v_add_f32_e32 v16, v123, v16
	v_add_f32_e32 v21, v16, v17
	v_and_b32_e32 v17, 0xffff0000, v139
	v_and_b32_e32 v16, 0xffff0000, v126
	v_pk_mul_f32 v[16:17], v[30:31], v[16:17]
	v_cvt_pk_bf16_f32 v18, v25, v20
	s_nop 0
	v_add_f32_e32 v16, v122, v16
	v_add_f32_e32 v19, v16, v17
	v_cvt_pk_bf16_f32 v16, v130, v24
	v_cvt_pk_bf16_f32 v17, v22, v23
	v_cvt_pk_bf16_f32 v19, v21, v19
	s_nop 0
	s_nop 0
	v_cndmask_b32_e64 v24, 0, v143, s[12:13]
	v_cndmask_b32_e64 v25, 0, v142, s[12:13]
	v_cndmask_b32_e64 v26, 0, v141, s[12:13]
	v_cndmask_b32_e64 v27, 0, v140, s[12:13]
	s_nop 0
	s_nop 0
	v_cndmask_b32_e64 v69, 0, v162, s[14:15]
	v_cndmask_b32_e64 v68, 0, v163, s[14:15]
	v_lshlrev_b32_e32 v21, 16, v69
	v_lshlrev_b32_e32 v20, 16, v27
	v_pk_mul_f32 v[20:21], v[78:79], v[20:21]
	v_cndmask_b32_e64 v164, 0, v164, s[14:15]
	v_add_f32_e32 v20, v48, v20
	v_add_f32_e32 v70, v20, v21
	v_and_b32_e32 v21, 0xffff0000, v69
	v_and_b32_e32 v20, 0xffff0000, v27
	v_pk_mul_f32 v[20:21], v[44:45], v[20:21]
	v_cndmask_b32_e64 v165, 0, v165, s[14:15]
	v_add_f32_e32 v20, v49, v20
	v_add_f32_e32 v69, v20, v21
	v_lshlrev_b32_e32 v21, 16, v68
	v_lshlrev_b32_e32 v20, 16, v26
	v_pk_mul_f32 v[20:21], v[80:81], v[20:21]
	s_nop 0
	v_add_f32_e32 v20, v50, v20
	v_add_f32_e32 v71, v20, v21
	v_and_b32_e32 v21, 0xffff0000, v68
	v_and_b32_e32 v20, 0xffff0000, v26
	v_pk_mul_f32 v[20:21], v[46:47], v[20:21]
	s_nop 0
	v_add_f32_e32 v20, v51, v20
	v_add_f32_e32 v68, v20, v21
	v_lshlrev_b32_e32 v21, 16, v164
	v_lshlrev_b32_e32 v20, 16, v25
	v_pk_mul_f32 v[20:21], v[82:83], v[20:21]
	s_nop 0
	v_add_f32_e32 v20, v40, v20
	v_add_f32_e32 v122, v20, v21
	v_and_b32_e32 v21, 0xffff0000, v164
	v_and_b32_e32 v20, 0xffff0000, v25
	v_pk_mul_f32 v[20:21], v[36:37], v[20:21]
	v_and_b32_e32 v25, 0xffff0000, v165
	v_add_f32_e32 v20, v41, v20
	v_add_f32_e32 v22, v20, v21
	v_lshlrev_b32_e32 v21, 16, v165
	v_lshlrev_b32_e32 v20, 16, v24
	v_pk_mul_f32 v[20:21], v[84:85], v[20:21]
	v_and_b32_e32 v24, 0xffff0000, v24
	v_add_f32_e32 v20, v42, v20
	v_pk_mul_f32 v[24:25], v[38:39], v[24:25]
	v_add_f32_e32 v21, v20, v21
	v_add_f32_e32 v20, v43, v24
	v_add_f32_e32 v20, v20, v25
	s_nop 0
	s_nop 0
	v_cndmask_b32_e64 v72, 0, v169, s[16:17]
	v_cndmask_b32_e64 v23, 0, v168, s[16:17]
	v_cndmask_b32_e64 v73, 0, v167, s[16:17]
	v_cndmask_b32_e64 v123, 0, v166, s[16:17]
	s_nop 0
	s_nop 0
	v_cndmask_b32_e64 v77, 0, v172, s[10:11]
	v_cndmask_b32_e64 v76, 0, v173, s[10:11]
	v_lshlrev_b32_e32 v25, 16, v77
	v_lshlrev_b32_e32 v24, 16, v123
	v_pk_mul_f32 v[24:25], v[120:121], v[24:25]
	v_cndmask_b32_e64 v174, 0, v174, s[10:11]
	v_add_f32_e32 v24, v70, v24
	v_add_f32_e32 v70, v24, v25
	v_and_b32_e32 v25, 0xffff0000, v77
	v_and_b32_e32 v24, 0xffff0000, v123
	v_pk_mul_f32 v[24:25], v[32:33], v[24:25]
	v_cndmask_b32_e64 v175, 0, v175, s[10:11]
	v_add_f32_e32 v24, v69, v24
	v_add_f32_e32 v69, v24, v25
	v_lshlrev_b32_e32 v25, 16, v76
	v_lshlrev_b32_e32 v24, 16, v73
	v_pk_mul_f32 v[24:25], v[118:119], v[24:25]
	s_nop 0
	v_add_f32_e32 v24, v71, v24
	v_add_f32_e32 v71, v24, v25
	v_and_b32_e32 v25, 0xffff0000, v76
	v_and_b32_e32 v24, 0xffff0000, v73
	v_pk_mul_f32 v[24:25], v[34:35], v[24:25]
	s_nop 0
	v_add_f32_e32 v24, v68, v24
	v_add_f32_e32 v68, v24, v25
	v_lshlrev_b32_e32 v25, 16, v174
	v_lshlrev_b32_e32 v24, 16, v23
	v_pk_mul_f32 v[24:25], v[86:87], v[24:25]
	s_nop 0
	v_add_f32_e32 v24, v122, v24
	v_add_f32_e32 v73, v24, v25
	v_and_b32_e32 v25, 0xffff0000, v174
	v_and_b32_e32 v24, 0xffff0000, v23
	v_pk_mul_f32 v[24:25], v[28:29], v[24:25]
	v_lshlrev_b32_e32 v23, 16, v175
	v_add_f32_e32 v22, v22, v24
	v_add_f32_e32 v24, v22, v25
	v_lshlrev_b32_e32 v22, 16, v72
	v_pk_mul_f32 v[22:23], v[74:75], v[22:23]
	s_nop 0
	v_add_f32_e32 v21, v21, v22
	v_add_f32_e32 v25, v21, v23
	v_and_b32_e32 v23, 0xffff0000, v175
	v_and_b32_e32 v22, 0xffff0000, v72
	v_pk_mul_f32 v[22:23], v[30:31], v[22:23]
	v_cvt_pk_bf16_f32 v21, v71, v68
	s_nop 0
	v_add_f32_e32 v20, v20, v22
	v_add_f32_e32 v23, v20, v23
	v_cvt_pk_bf16_f32 v20, v70, v69
	v_cvt_pk_bf16_f32 v22, v73, v24
	v_cvt_pk_bf16_f32 v23, v25, v23
	s_nop 0
	s_nop 0
	v_cndmask_b32_e64 v60, 0, v179, s[18:19]
	v_cndmask_b32_e64 v61, 0, v178, s[18:19]
	v_cndmask_b32_e64 v68, 0, v177, s[18:19]
	v_cndmask_b32_e64 v69, 0, v176, s[18:19]
	s_nop 0
	s_nop 0
	v_cndmask_b32_e64 v63, 0, v180, s[20:21]
	v_cndmask_b32_e64 v62, 0, v181, s[20:21]
	v_lshlrev_b32_e32 v25, 16, v63
	v_lshlrev_b32_e32 v24, 16, v69
	v_pk_mul_f32 v[24:25], v[78:79], v[24:25]
	v_cndmask_b32_e64 v182, 0, v182, s[20:21]
	v_add_f32_e32 v24, v48, v24
	v_add_f32_e32 v70, v24, v25
	v_and_b32_e32 v25, 0xffff0000, v63
	v_and_b32_e32 v24, 0xffff0000, v69
	v_pk_mul_f32 v[24:25], v[44:45], v[24:25]
	v_cndmask_b32_e64 v183, 0, v183, s[20:21]
	v_add_f32_e32 v24, v49, v24
	v_add_f32_e32 v69, v24, v25
	v_lshlrev_b32_e32 v25, 16, v62
	v_lshlrev_b32_e32 v24, 16, v68
	v_pk_mul_f32 v[24:25], v[80:81], v[24:25]
	s_nop 0
	v_add_f32_e32 v24, v50, v24
	v_add_f32_e32 v71, v24, v25
	v_and_b32_e32 v25, 0xffff0000, v62
	v_and_b32_e32 v24, 0xffff0000, v68
	v_pk_mul_f32 v[24:25], v[46:47], v[24:25]
	s_nop 0
	v_add_f32_e32 v24, v51, v24
	v_add_f32_e32 v68, v24, v25
	v_lshlrev_b32_e32 v25, 16, v182
	v_lshlrev_b32_e32 v24, 16, v61
	v_pk_mul_f32 v[24:25], v[82:83], v[24:25]
	s_nop 0
	v_add_f32_e32 v24, v40, v24
	v_add_f32_e32 v72, v24, v25
	v_and_b32_e32 v25, 0xffff0000, v182
	v_and_b32_e32 v24, 0xffff0000, v61
	v_pk_mul_f32 v[24:25], v[36:37], v[24:25]
	v_and_b32_e32 v61, 0xffff0000, v183
	v_add_f32_e32 v24, v41, v24
	v_add_f32_e32 v26, v24, v25
	v_lshlrev_b32_e32 v25, 16, v183
	v_lshlrev_b32_e32 v24, 16, v60
	v_pk_mul_f32 v[24:25], v[84:85], v[24:25]
	v_and_b32_e32 v60, 0xffff0000, v60
	v_add_f32_e32 v24, v42, v24
	v_pk_mul_f32 v[60:61], v[38:39], v[60:61]
	v_add_f32_e32 v25, v24, v25
	v_add_f32_e32 v24, v43, v60
	v_add_f32_e32 v24, v24, v61
	s_nop 0
	s_nop 0
	v_cndmask_b32_e64 v64, 0, v187, s[22:23]
	v_cndmask_b32_e64 v27, 0, v186, s[22:23]
	v_cndmask_b32_e64 v65, 0, v185, s[22:23]
	v_cndmask_b32_e64 v73, 0, v184, s[22:23]
	s_nop 0
	s_nop 0
	v_cndmask_b32_e64 v67, 0, v192, s[10:11]
	v_cndmask_b32_e64 v66, 0, v193, s[10:11]
	v_lshlrev_b32_e32 v61, 16, v67
	v_lshlrev_b32_e32 v60, 16, v73
	v_pk_mul_f32 v[60:61], v[120:121], v[60:61]
	v_cndmask_b32_e64 v194, 0, v194, s[10:11]
	v_add_f32_e32 v60, v70, v60
	v_add_f32_e32 v70, v60, v61
	v_and_b32_e32 v61, 0xffff0000, v67
	v_and_b32_e32 v60, 0xffff0000, v73
	v_pk_mul_f32 v[60:61], v[32:33], v[60:61]
	v_cndmask_b32_e64 v195, 0, v195, s[10:11]
	v_add_f32_e32 v60, v69, v60
	v_add_f32_e32 v67, v60, v61
	v_lshlrev_b32_e32 v61, 16, v66
	v_lshlrev_b32_e32 v60, 16, v65
	v_pk_mul_f32 v[60:61], v[118:119], v[60:61]
	s_nop 0
	v_add_f32_e32 v60, v71, v60
	v_add_f32_e32 v69, v60, v61
	v_and_b32_e32 v61, 0xffff0000, v66
	v_and_b32_e32 v60, 0xffff0000, v65
	v_pk_mul_f32 v[60:61], v[34:35], v[60:61]
	s_nop 0
	v_add_f32_e32 v60, v68, v60
	v_add_f32_e32 v65, v60, v61
	v_lshlrev_b32_e32 v61, 16, v194
	v_lshlrev_b32_e32 v60, 16, v27
	v_pk_mul_f32 v[60:61], v[86:87], v[60:61]
	s_nop 0
	v_add_f32_e32 v60, v72, v60
	v_add_f32_e32 v66, v60, v61
	v_and_b32_e32 v61, 0xffff0000, v194
	v_and_b32_e32 v60, 0xffff0000, v27
	v_pk_mul_f32 v[60:61], v[28:29], v[60:61]
	v_lshlrev_b32_e32 v27, 16, v195
	v_add_f32_e32 v26, v26, v60
	v_add_f32_e32 v60, v26, v61
	v_lshlrev_b32_e32 v26, 16, v64
	v_pk_mul_f32 v[26:27], v[74:75], v[26:27]
	s_nop 0
	v_add_f32_e32 v25, v25, v26
	v_add_f32_e32 v61, v25, v27
	v_and_b32_e32 v27, 0xffff0000, v195
	v_and_b32_e32 v26, 0xffff0000, v64
	v_pk_mul_f32 v[26:27], v[30:31], v[26:27]
	v_cvt_pk_bf16_f32 v25, v69, v65
	s_nop 0
	v_add_f32_e32 v24, v24, v26
	v_add_f32_e32 v27, v24, v27
	v_cvt_pk_bf16_f32 v24, v70, v67
	v_cvt_pk_bf16_f32 v26, v66, v60
	v_cvt_pk_bf16_f32 v27, v61, v27
	s_nop 0
	s_nop 0
	v_cndmask_b32_e64 v212, 0, v212, s[0:1]
	s_nop 0
	v_cndmask_b32_e64 v213, 0, v213, s[0:1]
	v_cndmask_b32_e64 v214, 0, v214, s[0:1]
	v_cndmask_b32_e64 v215, 0, v215, s[0:1]
	s_nop 0
	v_cndmask_b32_e64 v65, 0, v216, s[24:25]
	v_cndmask_b32_e64 v64, 0, v217, s[24:25]
	v_lshlrev_b32_e32 v53, 16, v65
	v_lshlrev_b32_e32 v52, 16, v212
	v_pk_mul_f32 v[52:53], v[78:79], v[52:53]
	v_cndmask_b32_e64 v218, 0, v218, s[24:25]
	v_add_f32_e32 v48, v48, v52
	v_add_f32_e32 v48, v48, v53
	v_and_b32_e32 v53, 0xffff0000, v65
	v_and_b32_e32 v52, 0xffff0000, v212
	v_pk_mul_f32 v[44:45], v[44:45], v[52:53]
	v_cndmask_b32_e64 v219, 0, v219, s[24:25]
	v_add_f32_e32 v44, v49, v44
	v_add_f32_e32 v49, v44, v45
	v_lshlrev_b32_e32 v45, 16, v64
	v_lshlrev_b32_e32 v44, 16, v213
	v_pk_mul_f32 v[44:45], v[80:81], v[44:45]
	s_nop 0
	v_add_f32_e32 v44, v50, v44
	v_add_f32_e32 v50, v44, v45
	v_and_b32_e32 v45, 0xffff0000, v64
	v_and_b32_e32 v44, 0xffff0000, v213
	v_pk_mul_f32 v[44:45], v[46:47], v[44:45]
	s_nop 0
	v_add_f32_e32 v44, v51, v44
	v_add_f32_e32 v46, v44, v45
	v_lshlrev_b32_e32 v45, 16, v218
	v_lshlrev_b32_e32 v44, 16, v214
	v_pk_mul_f32 v[44:45], v[82:83], v[44:45]
	s_nop 0
	v_add_f32_e32 v40, v40, v44
	v_add_f32_e32 v47, v40, v45
	v_and_b32_e32 v45, 0xffff0000, v218
	v_and_b32_e32 v44, 0xffff0000, v214
	v_pk_mul_f32 v[36:37], v[36:37], v[44:45]
	v_and_b32_e32 v45, 0xffff0000, v219
	v_add_f32_e32 v36, v41, v36
	v_add_f32_e32 v40, v36, v37
	v_lshlrev_b32_e32 v37, 16, v219
	v_lshlrev_b32_e32 v36, 16, v215
	v_pk_mul_f32 v[36:37], v[84:85], v[36:37]
	v_and_b32_e32 v44, 0xffff0000, v215
	v_add_f32_e32 v36, v42, v36
	v_pk_mul_f32 v[38:39], v[38:39], v[44:45]
	v_add_f32_e32 v37, v36, v37
	v_add_f32_e32 v36, v43, v38
	s_nop 0
	v_add_f32_e32 v36, v36, v39
	s_nop 0
	v_cndmask_b32_e64 v41, 0, v223, s[26:27]
	v_cndmask_b32_e64 v51, 0, v222, s[26:27]
	v_cndmask_b32_e64 v52, 0, v221, s[26:27]
	v_cndmask_b32_e64 v53, 0, v220, s[26:27]
	s_nop 0
	v_lshlrev_b32_e32 v38, 16, v53
	s_nop 0
	v_cndmask_b32_e64 v224, 0, v224, s[10:11]
	v_lshlrev_b32_e32 v39, 16, v224
	v_pk_mul_f32 v[38:39], v[120:121], v[38:39]
	v_cndmask_b32_e64 v225, 0, v225, s[10:11]
	v_add_f32_e32 v38, v48, v38
	v_add_f32_e32 v48, v38, v39
	v_and_b32_e32 v39, 0xffff0000, v224
	v_and_b32_e32 v38, 0xffff0000, v53
	v_pk_mul_f32 v[32:33], v[32:33], v[38:39]
	v_cndmask_b32_e64 v226, 0, v226, s[10:11]
	v_add_f32_e32 v32, v49, v32
	v_add_f32_e32 v38, v32, v33
	v_lshlrev_b32_e32 v33, 16, v225
	v_lshlrev_b32_e32 v32, 16, v52
	v_pk_mul_f32 v[32:33], v[118:119], v[32:33]
	v_cndmask_b32_e64 v227, 0, v227, s[10:11]
	v_add_f32_e32 v32, v50, v32
	v_add_f32_e32 v39, v32, v33
	v_and_b32_e32 v33, 0xffff0000, v225
	v_and_b32_e32 v32, 0xffff0000, v52
	v_pk_mul_f32 v[32:33], v[34:35], v[32:33]
	s_nop 0
	v_add_f32_e32 v32, v46, v32
	v_add_f32_e32 v34, v32, v33
	v_lshlrev_b32_e32 v33, 16, v226
	v_lshlrev_b32_e32 v32, 16, v51
	v_pk_mul_f32 v[32:33], v[86:87], v[32:33]
	s_nop 0
	v_add_f32_e32 v32, v47, v32
	v_add_f32_e32 v35, v32, v33
	v_and_b32_e32 v33, 0xffff0000, v226
	v_and_b32_e32 v32, 0xffff0000, v51
	v_pk_mul_f32 v[28:29], v[28:29], v[32:33]
	s_nop 0
	v_add_f32_e32 v28, v40, v28
	v_add_f32_e32 v32, v28, v29
	v_lshlrev_b32_e32 v29, 16, v227
	v_lshlrev_b32_e32 v28, 16, v41
	v_pk_mul_f32 v[28:29], v[74:75], v[28:29]
	s_nop 0
	v_add_f32_e32 v28, v37, v28
	v_add_f32_e32 v33, v28, v29
	v_and_b32_e32 v29, 0xffff0000, v227
	v_and_b32_e32 v28, 0xffff0000, v41
	v_pk_mul_f32 v[28:29], v[30:31], v[28:29]
	v_cvt_pk_bf16_f32 v30, v35, v32
	s_nop 0
	v_add_f32_e32 v28, v36, v28
	v_add_f32_e32 v31, v28, v29
	v_cvt_pk_bf16_f32 v28, v48, v38
	v_cvt_pk_bf16_f32 v29, v39, v34
	v_cvt_pk_bf16_f32 v31, v33, v31
	s_lshl_b64 s[80:81], s[80:81], 14
	v_lshl_add_u64 v[120:121], v[100:101], 0, s[78:79]
	v_lshl_add_u64 v[122:123], v[102:103], 0, s[78:79]
	v_lshl_add_u64 v[124:125], v[104:105], 0, s[78:79]
	v_lshl_add_u64 v[126:127], v[106:107], 0, s[78:79]
	v_lshl_add_u64 v[128:129], v[108:109], 0, s[78:79]
	v_readlane_b32 s78, v255, 2
	s_add_u32 s78, s78, s54
	v_readlane_b32 s79, v255, 4
	v_and_or_b32 v32, v202, 64, v92
	s_addc_u32 s79, s79, s55
	v_lshl_or_b32 v184, v32, 2, 60
	v_lshl_add_u64 v[32:33], v[110:111], 0, s[54:55]
	s_add_u32 s54, s68, s54
	s_addc_u32 s55, s69, s55
	v_lshl_add_u64 v[118:119], v[116:117], 0, s[82:83]
	v_lshl_add_u64 v[130:131], s[78:79], 2, v[90:91]
	v_lshl_add_u64 v[132:133], v[32:33], 1, s[66:67]
	v_lshl_add_u64 v[134:135], s[54:55], 1, v[112:113]
	v_lshl_add_u64 v[136:137], v[114:115], 0, s[80:81]
	s_mov_b64 s[78:79], 0
	s_branch .LBB0_195

.LBB0_283:
	s_mov_b32 s40, 0
	s_ashr_i32 s41, s40, 31
	s_andn2_b64 vcc, exec, s[30:31]
	s_mov_b64 s[28:29], -1
	v_readlane_b32 s100, v255, 42
	s_nop 3
	s_cmp_lg_u32 s100, 0
	s_cbranch_scc1 .LBB0_282
	s_cbranch_vccnz .LBB0_287
	s_lshl_b64 s[28:29], s[40:41], 2
	s_add_u32 s28, s46, s28
	s_addc_u32 s29, s47, s29
	v_lshl_add_u64 v[0:1], v[48:49], 0, s[28:29]
	v_add_co_u32_e32 v4, vcc, 0x3000, v0
	s_mov_b64 s[8:9], 0x3000
	s_nop 0
	v_addc_co_u32_e32 v5, vcc, 0, v1, vcc
	global_load_dwordx4 v[24:27], v[0:1], off offset:16
	global_load_dwordx4 v[28:31], v[0:1], off
	v_lshl_add_u64 v[2:3], v[0:1], 0, s[8:9]
	global_load_dwordx4 v[12:15], v[4:5], off
	global_load_dwordx4 v[8:11], v[2:3], off offset:16
	s_mov_b64 s[28:29], 0x6000
	v_add_co_u32_e32 v4, vcc, s83, v0
	v_lshl_add_u64 v[2:3], v[0:1], 0, s[28:29]
	s_nop 0
	v_addc_co_u32_e32 v5, vcc, 0, v1, vcc
	s_mov_b64 s[28:29], 0x9000
	global_load_dwordx4 v[20:23], v[4:5], off
	global_load_dwordx4 v[16:19], v[2:3], off offset:16
	v_lshl_add_u64 v[2:3], v[0:1], 0, s[28:29]
	s_lshl_b64 s[28:29], s[40:41], 1
	s_add_u32 s28, s74, s28
	v_add_co_u32_e32 v0, vcc, 0x9000, v0
	s_addc_u32 s29, s75, s29
	s_nop 0
	v_addc_co_u32_e32 v1, vcc, 0, v1, vcc
	v_lshl_add_u64 v[66:67], s[28:29], 0, v[50:51]
	global_load_dwordx4 v[4:7], v[0:1], off
	s_nop 0
	global_load_dwordx4 v[0:3], v[2:3], off offset:16
	v_add_co_u32_e32 v62, vcc, 0x13095000, v66
	s_nop 1
	v_addc_co_u32_e32 v63, vcc, 0, v67, vcc
	global_load_dwordx4 v[112:115], v[62:63], off offset:2560
	v_add_co_u32_e32 v62, vcc, 0x13099000, v66
	s_nop 1
	v_addc_co_u32_e32 v63, vcc, 0, v67, vcc
	global_load_dwordx4 v[116:119], v[62:63], off offset:3072
	v_add_co_u32_e32 v62, vcc, 0x1309d000, v66
	s_nop 1
	v_addc_co_u32_e32 v63, vcc, 0, v67, vcc
	global_load_dwordx4 v[222:225], v[62:63], off offset:3584
	v_add_co_u32_e32 v62, vcc, 0x130a2000, v66
	s_nop 1
	v_addc_co_u32_e32 v63, vcc, 0, v67, vcc
	global_load_dwordx4 v[226:229], v[62:63], off
	v_add_co_u32_e32 v62, vcc, 0x130a6000, v66
	s_nop 1
	v_addc_co_u32_e32 v63, vcc, 0, v67, vcc
	global_load_dwordx4 v[230:233], v[62:63], off offset:512
	v_add_co_u32_e32 v62, vcc, 0x130aa000, v66
	s_nop 1
	v_addc_co_u32_e32 v63, vcc, 0, v67, vcc
	global_load_dwordx4 v[234:237], v[62:63], off offset:1024
	v_add_co_u32_e32 v62, vcc, 0x130ae000, v66
	s_nop 1
	v_addc_co_u32_e32 v63, vcc, 0, v67, vcc
	global_load_dwordx4 v[242:245], v[62:63], off offset:1536
	v_add_co_u32_e32 v62, vcc, 0x130b2000, v66
	s_nop 1
	v_addc_co_u32_e32 v63, vcc, 0, v67, vcc
	global_load_dwordx4 v[246:249], v[62:63], off offset:2048
	v_add_co_u32_e32 v62, vcc, 0x130b6000, v66
	s_nop 1
	v_addc_co_u32_e32 v63, vcc, 0, v67, vcc
	global_load_dwordx2 v[80:81], v[62:63], off offset:2560
	global_load_dwordx2 v[86:87], v[62:63], off offset:2568
	v_add_co_u32_e32 v62, vcc, 0x130ba000, v66
	s_nop 1
	v_addc_co_u32_e32 v63, vcc, 0, v67, vcc
	global_load_dwordx4 v[62:65], v[62:63], off offset:3072
	s_waitcnt vmcnt(10)
	v_cndmask_b32_e64 v76, v112, 0, s[56:57]
	v_cndmask_b32_e64 v75, v113, 0, s[56:57]
	v_cndmask_b32_e64 v68, v115, 0, s[56:57]
	v_cndmask_b32_e64 v69, v114, 0, s[56:57]
	v_lshlrev_b32_e32 v70, 16, v76
	v_lshlrev_b32_e32 v102, 16, v69
	v_and_b32_e32 v106, 0xffff0000, v69
	v_lshlrev_b32_e32 v152, 16, v68
	v_and_b32_e32 v220, 0xffff0000, v68
	v_and_b32_e32 v76, 0xffff0000, v76
	v_lshlrev_b32_e32 v84, 16, v75
	v_and_b32_e32 v98, 0xffff0000, v75
	s_waitcnt vmcnt(9)
	v_cndmask_b32_e64 v77, v116, 0, s[58:59]
	v_cndmask_b32_e64 v94, v117, 0, s[58:59]
	v_cndmask_b32_e64 v92, v119, 0, s[58:59]
	v_cndmask_b32_e64 v93, v118, 0, s[58:59]
	v_lshlrev_b32_e32 v71, 16, v77
	v_and_b32_e32 v77, 0xffff0000, v77
	v_lshlrev_b32_e32 v85, 16, v94
	v_and_b32_e32 v99, 0xffff0000, v94
	v_lshlrev_b32_e32 v103, 16, v93
	v_and_b32_e32 v107, 0xffff0000, v93
	v_lshlrev_b32_e32 v153, 16, v92
	v_and_b32_e32 v221, 0xffff0000, v92
	s_waitcnt vmcnt(8)
	v_cndmask_b32_e64 v95, v222, 0, s[60:61]
	v_cndmask_b32_e64 v74, v223, 0, s[60:61]
	v_cndmask_b32_e64 v82, v225, 0, s[60:61]
	v_cndmask_b32_e64 v78, v224, 0, s[60:61]
	v_lshlrev_b32_e32 v68, 16, v95
	s_waitcnt vmcnt(7)
	v_cndmask_b32_e64 v96, v226, 0, s[48:49]
	v_cndmask_b32_e64 v110, v227, 0, s[48:49]
	v_cndmask_b32_e64 v83, v229, 0, s[48:49]
	v_cndmask_b32_e64 v79, v228, 0, s[48:49]
	v_lshlrev_b32_e32 v69, 16, v96
	v_and_b32_e32 v75, 0xffff0000, v110
	s_waitcnt vmcnt(6)
	v_cndmask_b32_e64 v135, v230, 0, s[48:49]
	v_cndmask_b32_e64 v132, v231, 0, s[48:49]
	v_cndmask_b32_e64 v126, v233, 0, s[48:49]
	v_cndmask_b32_e64 v122, v232, 0, s[48:49]
	s_waitcnt vmcnt(5)
	v_cndmask_b32_e64 v136, v234, 0, s[48:49]
	v_cndmask_b32_e64 v133, v235, 0, s[48:49]
	v_cndmask_b32_e64 v127, v237, 0, s[48:49]
	v_cndmask_b32_e64 v123, v236, 0, s[48:49]
	s_waitcnt vmcnt(4)
	v_cndmask_b32_e64 v128, v242, 0, s[48:49]
	v_cndmask_b32_e64 v130, v243, 0, s[48:49]
	v_cndmask_b32_e64 v191, v245, 0, s[48:49]
	v_cndmask_b32_e64 v124, v244, 0, s[48:49]
	s_waitcnt vmcnt(3)
	v_cndmask_b32_e64 v129, v246, 0, s[48:49]
	v_cndmask_b32_e64 v131, v247, 0, s[48:49]
	v_cndmask_b32_e64 v216, v249, 0, s[48:49]
	v_cndmask_b32_e64 v125, v248, 0, s[48:49]
	s_waitcnt vmcnt(1)
	v_cndmask_b32_e64 v192, v80, 0, s[48:49]
	v_cndmask_b32_e64 v212, v81, 0, s[48:49]
	v_cndmask_b32_e64 v193, v87, 0, s[48:49]
	v_cndmask_b32_e64 v194, v86, 0, s[48:49]
	s_waitcnt vmcnt(0)
	v_cndmask_b32_e64 v195, v65, 0, s[48:49]
	v_cndmask_b32_e64 v213, v64, 0, s[48:49]
	v_cndmask_b32_e64 v214, v63, 0, s[48:49]
	v_cndmask_b32_e64 v215, v62, 0, s[48:49]
	v_mov_b32_e32 v64, v28
	v_mov_b32_e32 v65, v12
	v_mov_b32_e32 v62, v30
	v_mov_b32_e32 v63, v14
	v_mov_b32_e32 v14, v31
	v_mov_b32_e32 v30, v24
	v_mov_b32_e32 v31, v8
	v_mov_b32_e32 v8, v25
	v_pk_mov_b32 v[24:25], v[70:71], v[68:69] op_sel:[1,0]
	v_pk_mul_f32 v[72:73], v[64:65], v[70:71]
	v_pk_mul_f32 v[116:117], v[64:65], v[24:25]
	v_mov_b32_e32 v24, v20
	v_mov_b32_e32 v25, v4
	v_mov_b32_e32 v12, v29
	v_mov_b32_e32 v28, v26
	v_mov_b32_e32 v29, v10
	v_mov_b32_e32 v10, v27
	v_pk_mul_f32 v[26:27], v[24:25], v[68:69]
	v_add_f32_e32 v4, v72, v73
	v_add_f32_e32 v4, v4, v26
	v_and_b32_e32 v71, 0xffff0000, v96
	v_and_b32_e32 v70, 0xffff0000, v95
	v_pk_mul_f32 v[80:81], v[12:13], v[76:77]
	v_add_f32_e32 v134, v4, v27
	v_pk_mov_b32 v[26:27], v[76:77], v[70:71] op_sel:[1,0]
	v_mov_b32_e32 v4, v21
	v_pk_mul_f32 v[94:95], v[12:13], v[26:27]
	v_pk_mul_f32 v[20:21], v[4:5], v[70:71]
	v_add_f32_e32 v26, v80, v81
	v_add_f32_e32 v20, v26, v20
	v_lshlrev_b32_e32 v73, 16, v110
	v_lshlrev_b32_e32 v72, 16, v74
	v_add_f32_e32 v137, v20, v21
	v_pk_mov_b32 v[20:21], v[84:85], v[72:73] op_sel:[1,0]
	v_pk_mul_f32 v[86:87], v[62:63], v[84:85]
	v_pk_mul_f32 v[118:119], v[62:63], v[20:21]
	v_mov_b32_e32 v20, v22
	v_mov_b32_e32 v21, v6
	v_pk_mul_f32 v[26:27], v[20:21], v[72:73]
	v_add_f32_e32 v6, v86, v87
	v_add_f32_e32 v6, v6, v26
	v_and_b32_e32 v74, 0xffff0000, v74
	v_pk_mul_f32 v[100:101], v[14:15], v[98:99]
	v_add_f32_e32 v86, v6, v27
	v_pk_mov_b32 v[26:27], v[98:99], v[74:75] op_sel:[1,0]
	v_mov_b32_e32 v6, v23
	v_pk_mul_f32 v[98:99], v[14:15], v[26:27]
	v_pk_mul_f32 v[22:23], v[6:7], v[74:75]
	v_add_f32_e32 v26, v100, v101
	v_add_f32_e32 v22, v26, v22
	v_lshlrev_b32_e32 v77, 16, v79
	v_lshlrev_b32_e32 v76, 16, v78
	v_add_f32_e32 v87, v22, v23
	v_pk_mov_b32 v[22:23], v[102:103], v[76:77] op_sel:[1,0]
	v_pk_mul_f32 v[104:105], v[30:31], v[102:103]
	v_pk_mul_f32 v[120:121], v[30:31], v[22:23]
	v_mov_b32_e32 v22, v16
	v_mov_b32_e32 v23, v0
	v_pk_mul_f32 v[26:27], v[22:23], v[76:77]
	v_add_f32_e32 v0, v104, v105
	v_add_f32_e32 v0, v0, v26
	v_and_b32_e32 v79, 0xffff0000, v79
	v_and_b32_e32 v78, 0xffff0000, v78
	v_pk_mul_f32 v[112:113], v[8:9], v[106:107]
	v_pk_mul_f32 v[218:219], v[28:29], v[152:153]
	v_add_f32_e32 v152, v0, v27
	v_pk_mov_b32 v[26:27], v[106:107], v[78:79] op_sel:[1,0]
	v_mov_b32_e32 v0, v17
	v_pk_mul_f32 v[102:103], v[8:9], v[26:27]
	v_pk_mul_f32 v[16:17], v[0:1], v[78:79]
	v_add_f32_e32 v26, v112, v113
	v_add_f32_e32 v16, v26, v16
	v_lshlrev_b32_e32 v81, 16, v83
	v_lshlrev_b32_e32 v80, 16, v82
	v_add_f32_e32 v217, v16, v17
	v_pk_mov_b32 v[16:17], v[152:153], v[80:81] op_sel:[1,0]
	v_mov_b32_e32 v26, v18
	v_mov_b32_e32 v27, v2
	v_pk_mul_f32 v[112:113], v[28:29], v[16:17]
	v_pk_mul_f32 v[16:17], v[26:27], v[80:81]
	v_add_f32_e32 v2, v218, v219
	v_add_f32_e32 v2, v2, v16
	v_and_b32_e32 v83, 0xffff0000, v83
	v_and_b32_e32 v82, 0xffff0000, v82
	v_pk_mul_f32 v[222:223], v[10:11], v[220:221]
	v_add_f32_e32 v18, v2, v17
	v_pk_mov_b32 v[16:17], v[220:221], v[82:83] op_sel:[1,0]
	v_mov_b32_e32 v2, v19
	v_pk_mul_f32 v[84:85], v[10:11], v[16:17]
	v_pk_mul_f32 v[16:17], v[2:3], v[82:83]
	v_add_f32_e32 v19, v222, v223
	v_add_f32_e32 v16, v19, v16
	v_mul_f32_e32 v19, 0xbfb8aa3b, v137
	v_exp_f32_e32 v19, v19
	v_mul_f32_e32 v153, 0xbfb8aa3b, v18
	v_exp_f32_e32 v153, v153
	v_add_f32_e32 v16, v16, v17
	v_add_f32_e32 v19, 1.0, v19
	v_rcp_f32_e32 v19, v19
	v_add_f32_e32 v153, 1.0, v153
	v_rcp_f32_e32 v153, v153
	v_mul_f32_e32 v17, 0xbfb8aa3b, v134
	v_mul_f32_e32 v19, v137, v19
	v_mul_f32_e32 v137, 0xbfb8aa3b, v86
	v_exp_f32_e32 v137, v137
	v_exp_f32_e32 v17, v17
	v_mul_f32_e32 v153, v18, v153
	v_mul_f32_e32 v18, 0xbfb8aa3b, v16
	v_add_f32_e32 v137, 1.0, v137
	v_rcp_f32_e32 v137, v137
	v_exp_f32_e32 v18, v18
	v_add_f32_e32 v17, 1.0, v17
	v_rcp_f32_e32 v17, v17
	v_mul_f32_e32 v86, v86, v137
	v_mul_f32_e32 v137, 0xbfb8aa3b, v87
	v_exp_f32_e32 v137, v137
	v_add_f32_e32 v18, 1.0, v18
	v_rcp_f32_e32 v18, v18
	v_mul_f32_e32 v17, v134, v17
	v_add_f32_e32 v137, 1.0, v137
	v_rcp_f32_e32 v137, v137
	v_mul_f32_e32 v134, v19, v19
	v_fmac_f32_e32 v134, v17, v17
	v_fmac_f32_e32 v134, v86, v86
	v_mul_f32_e32 v87, v87, v137
	v_mul_f32_e32 v137, 0xbfb8aa3b, v152
	v_exp_f32_e32 v137, v137
	v_fmac_f32_e32 v134, v87, v87
	v_pk_mul_f32 v[92:93], v[64:65], v[68:69]
	v_add_f32_e32 v116, v116, v117
	v_add_f32_e32 v137, 1.0, v137
	v_rcp_f32_e32 v137, v137
	v_pk_mul_f32 v[108:109], v[12:13], v[70:71]
	v_add_f32_e32 v94, v94, v95
	v_pk_mul_f32 v[96:97], v[62:63], v[72:73]
	v_mul_f32_e32 v137, v152, v137
	v_mul_f32_e32 v152, 0xbfb8aa3b, v217
	v_exp_f32_e32 v152, v152
	v_fmac_f32_e32 v134, v137, v137
	v_pk_mul_f32 v[114:115], v[14:15], v[74:75]
	v_add_f32_e32 v98, v98, v99
	v_add_f32_e32 v152, 1.0, v152
	v_rcp_f32_e32 v152, v152
	v_pk_mul_f32 v[100:101], v[30:31], v[76:77]
	v_add_f32_e32 v120, v120, v121
	v_pk_mul_f32 v[110:111], v[8:9], v[78:79]
	v_mul_f32_e32 v152, v217, v152
	v_mul_f32_e32 v217, v16, v18
	v_cvt_pk_bf16_f32 v16, v17, v19
	v_cvt_pk_bf16_f32 v17, v86, v87
	v_lshlrev_b32_e32 v87, 16, v136
	v_lshlrev_b32_e32 v86, 16, v135
	v_cvt_pk_bf16_f32 v18, v137, v152
	v_cvt_pk_bf16_f32 v19, v153, v217
	ds_write_b128 v169, v[16:19]
	v_pk_mov_b32 v[16:17], v[68:69], v[86:87] op_sel:[1,0]
	v_fmac_f32_e32 v134, v152, v152
	v_pk_mul_f32 v[68:69], v[64:65], v[16:17]
	v_pk_mul_f32 v[16:17], v[24:25], v[16:17]
	v_pk_mul_f32 v[18:19], v[24:25], v[86:87]
	v_add_f32_e32 v16, v116, v16
	v_add_f32_e32 v16, v16, v17
	v_mul_f32_e32 v17, 0xbfb8aa3b, v16
	v_exp_f32_e32 v17, v17
	v_fmac_f32_e32 v134, v153, v153
	v_fmac_f32_e32 v134, v217, v217
	v_add_f32_e32 v102, v102, v103
	v_add_f32_e32 v17, 1.0, v17
	v_rcp_f32_e32 v17, v17
	v_pk_mul_f32 v[104:105], v[28:29], v[80:81]
	v_pk_mul_f32 v[106:107], v[10:11], v[82:83]
	v_add_f32_e32 v104, v104, v105
	v_mul_f32_e32 v152, v16, v17
	v_add_f32_e32 v16, v92, v93
	v_add_f32_e32 v16, v16, v18
	v_and_b32_e32 v93, 0xffff0000, v136
	v_and_b32_e32 v92, 0xffff0000, v135
	v_add_f32_e32 v137, v16, v19
	v_pk_mov_b32 v[16:17], v[70:71], v[92:93] op_sel:[1,0]
	v_pk_mul_f32 v[18:19], v[4:5], v[92:93]
	v_pk_mul_f32 v[70:71], v[12:13], v[16:17]
	v_pk_mul_f32 v[16:17], v[4:5], v[16:17]
	v_and_b32_e32 v105, 0xffff0000, v127
	v_add_f32_e32 v16, v94, v16
	v_add_f32_e32 v16, v16, v17
	v_mul_f32_e32 v17, 0xbfb8aa3b, v16
	v_exp_f32_e32 v17, v17
	v_add_f32_e32 v84, v84, v85
	v_pk_mul_f32 v[116:117], v[64:65], v[86:87]
	v_add_f32_e32 v17, 1.0, v17
	v_rcp_f32_e32 v17, v17
	v_add_f32_e32 v68, v68, v69
	v_and_b32_e32 v69, 0xffff0000, v129
	v_pk_mul_f32 v[94:95], v[12:13], v[92:93]
	v_mul_f32_e32 v16, v16, v17
	v_add_f32_e32 v17, v108, v109
	v_add_f32_e32 v17, v17, v18
	v_lshlrev_b32_e32 v109, 16, v133
	v_lshlrev_b32_e32 v108, 16, v132
	v_add_f32_e32 v136, v17, v19
	v_pk_mov_b32 v[18:19], v[72:73], v[108:109] op_sel:[1,0]
	v_add_f32_e32 v17, v118, v119
	v_pk_mul_f32 v[72:73], v[62:63], v[18:19]
	v_pk_mul_f32 v[18:19], v[20:21], v[18:19]
	v_mul_f32_e32 v135, v16, v16
	v_add_f32_e32 v17, v17, v18
	v_add_f32_e32 v17, v17, v19
	v_mul_f32_e32 v18, 0xbfb8aa3b, v17
	v_exp_f32_e32 v18, v18
	v_fmac_f32_e32 v135, v152, v152
	v_cvt_pk_bf16_f32 v16, v152, v16
	v_pk_mul_f32 v[152:153], v[20:21], v[108:109]
	v_add_f32_e32 v18, 1.0, v18
	v_rcp_f32_e32 v18, v18
	v_add_f32_e32 v70, v70, v71
	v_pk_mul_f32 v[118:119], v[62:63], v[108:109]
	v_mul_f32_e32 v17, v17, v18
	v_add_f32_e32 v18, v96, v97
	v_add_f32_e32 v18, v18, v152
	v_and_b32_e32 v97, 0xffff0000, v133
	v_and_b32_e32 v96, 0xffff0000, v132
	v_add_f32_e32 v152, v18, v153
	v_pk_mov_b32 v[18:19], v[74:75], v[96:97] op_sel:[1,0]
	v_fmac_f32_e32 v135, v17, v17
	v_pk_mul_f32 v[74:75], v[14:15], v[18:19]
	v_pk_mul_f32 v[18:19], v[6:7], v[18:19]
	v_pk_mul_f32 v[132:133], v[6:7], v[96:97]
	v_add_f32_e32 v18, v98, v18
	v_add_f32_e32 v18, v18, v19
	v_mul_f32_e32 v19, 0xbfb8aa3b, v18
	v_exp_f32_e32 v19, v19
	v_pk_mul_f32 v[98:99], v[14:15], v[96:97]
	v_add_f32_e32 v74, v74, v75
	v_add_f32_e32 v19, 1.0, v19
	v_rcp_f32_e32 v19, v19
	s_nop 0
	v_mul_f32_e32 v18, v18, v19
	v_fmac_f32_e32 v135, v18, v18
	v_cvt_pk_bf16_f32 v17, v17, v18
	v_add_f32_e32 v18, v114, v115
	v_add_f32_e32 v18, v18, v132
	v_lshlrev_b32_e32 v115, 16, v123
	v_lshlrev_b32_e32 v114, 16, v122
	v_add_f32_e32 v153, v18, v133
	v_pk_mov_b32 v[18:19], v[76:77], v[114:115] op_sel:[1,0]
	v_pk_mul_f32 v[132:133], v[22:23], v[114:115]
	v_pk_mul_f32 v[76:77], v[30:31], v[18:19]
	v_pk_mul_f32 v[18:19], v[22:23], v[18:19]
	v_add_f32_e32 v76, v76, v77
	v_add_f32_e32 v18, v120, v18
	v_add_f32_e32 v18, v18, v19
	v_mul_f32_e32 v19, 0xbfb8aa3b, v18
	v_exp_f32_e32 v19, v19
	v_pk_mul_f32 v[120:121], v[30:31], v[114:115]
	v_and_b32_e32 v77, 0xffff0000, v125
	v_add_f32_e32 v19, 1.0, v19
	v_rcp_f32_e32 v19, v19
	s_nop 0
	v_mul_f32_e32 v217, v18, v19
	v_add_f32_e32 v18, v100, v101
	v_add_f32_e32 v18, v18, v132
	v_and_b32_e32 v101, 0xffff0000, v123
	v_and_b32_e32 v100, 0xffff0000, v122
	v_add_f32_e32 v218, v18, v133
	v_pk_mov_b32 v[18:19], v[78:79], v[100:101] op_sel:[1,0]
	v_pk_mul_f32 v[122:123], v[0:1], v[100:101]
	v_pk_mul_f32 v[78:79], v[8:9], v[18:19]
	v_pk_mul_f32 v[18:19], v[0:1], v[18:19]
	v_fmac_f32_e32 v135, v217, v217
	v_add_f32_e32 v18, v102, v18
	v_add_f32_e32 v18, v18, v19
	v_mul_f32_e32 v19, 0xbfb8aa3b, v18
	v_exp_f32_e32 v19, v19
	v_pk_mul_f32 v[102:103], v[8:9], v[100:101]
	v_add_f32_e32 v78, v78, v79
	v_add_f32_e32 v19, 1.0, v19
	v_rcp_f32_e32 v19, v19
	s_nop 0
	v_mul_f32_e32 v18, v18, v19
	v_add_f32_e32 v19, v110, v111
	v_add_f32_e32 v19, v19, v122
	v_lshlrev_b32_e32 v111, 16, v127
	v_lshlrev_b32_e32 v110, 16, v126
	v_fmac_f32_e32 v135, v18, v18
	v_cvt_pk_bf16_f32 v18, v217, v18
	v_add_f32_e32 v217, v19, v123
	v_pk_mov_b32 v[122:123], v[80:81], v[110:111] op_sel:[1,0]
	v_add_f32_e32 v19, v112, v113
	v_pk_mul_f32 v[80:81], v[28:29], v[122:123]
	v_pk_mul_f32 v[122:123], v[26:27], v[122:123]
	v_pk_mul_f32 v[132:133], v[26:27], v[110:111]
	v_add_f32_e32 v19, v19, v122
	v_add_f32_e32 v19, v19, v123
	v_mul_f32_e32 v112, 0xbfb8aa3b, v19
	v_exp_f32_e32 v112, v112
	v_add_f32_e32 v104, v104, v132
	v_add_f32_e32 v132, v104, v133
	v_and_b32_e32 v104, 0xffff0000, v126
	v_add_f32_e32 v112, 1.0, v112
	v_rcp_f32_e32 v112, v112
	v_pk_mul_f32 v[126:127], v[2:3], v[104:105]
	v_pk_mul_f32 v[122:123], v[28:29], v[110:111]
	v_mul_f32_e32 v19, v19, v112
	v_pk_mov_b32 v[112:113], v[82:83], v[104:105] op_sel:[1,0]
	v_fmac_f32_e32 v135, v19, v19
	v_pk_mul_f32 v[82:83], v[10:11], v[112:113]
	v_pk_mul_f32 v[112:113], v[2:3], v[112:113]
	v_add_f32_e32 v82, v82, v83
	v_add_f32_e32 v84, v84, v112
	v_add_f32_e32 v84, v84, v113
	v_mul_f32_e32 v85, 0xbfb8aa3b, v84
	v_exp_f32_e32 v85, v85
	v_mul_f32_e32 v113, 0xbfb8aa3b, v132
	v_exp_f32_e32 v113, v113
	v_add_f32_e32 v85, 1.0, v85
	v_rcp_f32_e32 v85, v85
	v_add_f32_e32 v113, 1.0, v113
	v_rcp_f32_e32 v113, v113
	v_mul_f32_e32 v112, v84, v85
	v_cvt_pk_bf16_f32 v19, v19, v112
	ds_write_b128 v169, v[16:19] offset:272
	v_mul_f32_e32 v18, 0xbfb8aa3b, v136
	v_mul_f32_e32 v17, 0xbfb8aa3b, v137
	v_exp_f32_e32 v18, v18
	v_exp_f32_e32 v17, v17
	v_mul_f32_e32 v19, 0xbfb8aa3b, v152
	v_add_f32_e32 v16, v106, v107
	v_exp_f32_e32 v19, v19
	v_mul_f32_e32 v106, 0xbfb8aa3b, v153
	v_exp_f32_e32 v106, v106
	v_mul_f32_e32 v107, 0xbfb8aa3b, v218
	v_fmac_f32_e32 v135, v112, v112
	v_add_f32_e32 v16, v16, v126
	v_add_f32_e32 v18, 1.0, v18
	v_exp_f32_e32 v107, v107
	v_mul_f32_e32 v112, 0xbfb8aa3b, v217
	v_add_f32_e32 v16, v16, v127
	v_add_f32_e32 v17, 1.0, v17
	v_rcp_f32_e32 v18, v18
	v_exp_f32_e32 v112, v112
	v_rcp_f32_e32 v17, v17
	v_add_f32_e32 v19, 1.0, v19
	v_mul_f32_e32 v126, 0xbfb8aa3b, v16
	v_rcp_f32_e32 v19, v19
	v_add_f32_e32 v106, 1.0, v106
	v_exp_f32_e32 v126, v126
	v_rcp_f32_e32 v106, v106
	v_add_f32_e32 v107, 1.0, v107
	v_mul_f32_e32 v18, v136, v18
	v_rcp_f32_e32 v107, v107
	v_add_f32_e32 v112, 1.0, v112
	v_mul_f32_e32 v17, v137, v17
	v_mul_f32_e32 v136, v18, v18
	v_rcp_f32_e32 v112, v112
	v_fmac_f32_e32 v136, v17, v17
	v_mul_f32_e32 v19, v152, v19
	v_add_f32_e32 v126, 1.0, v126
	v_fmac_f32_e32 v136, v19, v19
	v_mul_f32_e32 v106, v153, v106
	v_rcp_f32_e32 v126, v126
	v_fmac_f32_e32 v136, v106, v106
	v_mul_f32_e32 v107, v218, v107
	v_fmac_f32_e32 v136, v107, v107
	v_mul_f32_e32 v112, v217, v112
	v_fmac_f32_e32 v136, v112, v112
	v_mul_f32_e32 v113, v132, v113
	v_fmac_f32_e32 v136, v113, v113
	v_mul_f32_e32 v126, v16, v126
	v_cvt_pk_bf16_f32 v16, v17, v18
	v_cvt_pk_bf16_f32 v17, v19, v106
	v_cvt_pk_bf16_f32 v18, v107, v112
	v_cvt_pk_bf16_f32 v19, v113, v126
	v_lshlrev_b32_e32 v113, 16, v129
	v_lshlrev_b32_e32 v112, 16, v128
	ds_write_b128 v169, v[16:19] offset:544
	v_pk_mov_b32 v[16:17], v[86:87], v[112:113] op_sel:[1,0]
	v_pk_mul_f32 v[18:19], v[24:25], v[112:113]
	v_pk_mul_f32 v[86:87], v[64:65], v[16:17]
	v_pk_mul_f32 v[16:17], v[24:25], v[16:17]
	v_lshlrev_b32_e32 v107, 16, v131
	v_add_f32_e32 v16, v68, v16
	v_add_f32_e32 v16, v16, v17
	v_mul_f32_e32 v17, 0xbfb8aa3b, v16
	v_exp_f32_e32 v17, v17
	v_and_b32_e32 v68, 0xffff0000, v128
	v_pk_mul_f32 v[84:85], v[10:11], v[104:105]
	v_fmac_f32_e32 v136, v126, v126
	v_add_f32_e32 v17, 1.0, v17
	v_rcp_f32_e32 v17, v17
	v_pk_mul_f32 v[126:127], v[64:65], v[112:113]
	v_mul_f32_e32 v106, v16, v17
	v_add_f32_e32 v16, v116, v117
	v_add_f32_e32 v16, v16, v18
	v_add_f32_e32 v116, v16, v19
	v_pk_mov_b32 v[16:17], v[92:93], v[68:69] op_sel:[1,0]
	v_pk_mul_f32 v[18:19], v[4:5], v[68:69]
	v_pk_mul_f32 v[92:93], v[12:13], v[16:17]
	v_pk_mul_f32 v[16:17], v[4:5], v[16:17]
	s_nop 0
	v_add_f32_e32 v16, v70, v16
	v_add_f32_e32 v16, v16, v17
	v_mul_f32_e32 v17, 0xbfb8aa3b, v16
	v_exp_f32_e32 v17, v17
	v_pk_mul_f32 v[70:71], v[12:13], v[68:69]
	v_add_f32_e32 v17, 1.0, v17
	v_rcp_f32_e32 v17, v17
	s_nop 0
	v_mul_f32_e32 v16, v16, v17
	v_mul_f32_e32 v137, v16, v16
	v_add_f32_e32 v17, v94, v95
	v_fmac_f32_e32 v137, v106, v106
	v_cvt_pk_bf16_f32 v16, v106, v16
	v_add_f32_e32 v17, v17, v18
	v_lshlrev_b32_e32 v106, 16, v130
	v_add_f32_e32 v117, v17, v19
	v_pk_mov_b32 v[18:19], v[108:109], v[106:107] op_sel:[1,0]
	v_add_f32_e32 v17, v72, v73
	v_pk_mul_f32 v[94:95], v[62:63], v[18:19]
	v_pk_mul_f32 v[18:19], v[20:21], v[18:19]
	v_pk_mul_f32 v[108:109], v[20:21], v[106:107]
	v_add_f32_e32 v17, v17, v18
	v_add_f32_e32 v17, v17, v19
	v_mul_f32_e32 v18, 0xbfb8aa3b, v17
	v_exp_f32_e32 v18, v18
	v_and_b32_e32 v73, 0xffff0000, v131
	v_and_b32_e32 v72, 0xffff0000, v130
	v_pk_mul_f32 v[128:129], v[62:63], v[106:107]
	v_add_f32_e32 v18, 1.0, v18
	v_rcp_f32_e32 v18, v18
	s_nop 0
	v_mul_f32_e32 v17, v17, v18
	v_add_f32_e32 v18, v118, v119
	v_add_f32_e32 v18, v18, v108
	v_add_f32_e32 v118, v18, v109
	v_pk_mov_b32 v[18:19], v[96:97], v[72:73] op_sel:[1,0]
	v_fmac_f32_e32 v137, v17, v17
	v_pk_mul_f32 v[96:97], v[14:15], v[18:19]
	v_pk_mul_f32 v[18:19], v[6:7], v[18:19]
	v_pk_mul_f32 v[108:109], v[6:7], v[72:73]
	v_add_f32_e32 v18, v74, v18
	v_add_f32_e32 v18, v18, v19
	v_mul_f32_e32 v19, 0xbfb8aa3b, v18
	v_exp_f32_e32 v19, v19
	v_pk_mul_f32 v[74:75], v[14:15], v[72:73]
	v_add_f32_e32 v19, 1.0, v19
	v_rcp_f32_e32 v19, v19
	s_nop 0
	v_mul_f32_e32 v18, v18, v19
	v_fmac_f32_e32 v137, v18, v18
	v_cvt_pk_bf16_f32 v17, v17, v18
	v_add_f32_e32 v18, v98, v99
	v_add_f32_e32 v18, v18, v108
	v_add_f32_e32 v119, v18, v109
	v_lshlrev_b32_e32 v109, 16, v125
	v_lshlrev_b32_e32 v108, 16, v124
	v_pk_mov_b32 v[18:19], v[114:115], v[108:109] op_sel:[1,0]
	v_pk_mul_f32 v[114:115], v[22:23], v[108:109]
	v_pk_mul_f32 v[98:99], v[30:31], v[18:19]
	v_pk_mul_f32 v[18:19], v[22:23], v[18:19]
	v_lshlrev_b32_e32 v125, 16, v216
	v_add_f32_e32 v18, v76, v18
	v_add_f32_e32 v18, v18, v19
	v_mul_f32_e32 v19, 0xbfb8aa3b, v18
	v_exp_f32_e32 v19, v19
	v_and_b32_e32 v76, 0xffff0000, v124
	v_lshlrev_b32_e32 v124, 16, v191
	v_pk_mul_f32 v[130:131], v[30:31], v[108:109]
	v_add_f32_e32 v19, 1.0, v19
	v_rcp_f32_e32 v19, v19
	s_nop 0
	v_mul_f32_e32 v132, v18, v19
	v_add_f32_e32 v18, v120, v121
	v_add_f32_e32 v18, v18, v114
	v_add_f32_e32 v152, v18, v115
	v_pk_mov_b32 v[18:19], v[100:101], v[76:77] op_sel:[1,0]
	v_pk_mul_f32 v[114:115], v[0:1], v[76:77]
	v_pk_mul_f32 v[100:101], v[8:9], v[18:19]
	v_pk_mul_f32 v[18:19], v[0:1], v[18:19]
	v_fmac_f32_e32 v137, v132, v132
	v_add_f32_e32 v18, v78, v18
	v_add_f32_e32 v18, v18, v19
	v_mul_f32_e32 v19, 0xbfb8aa3b, v18
	v_exp_f32_e32 v19, v19
	v_pk_mul_f32 v[78:79], v[8:9], v[76:77]
	v_add_f32_e32 v19, 1.0, v19
	v_rcp_f32_e32 v19, v19
	s_nop 0
	v_mul_f32_e32 v18, v18, v19
	v_add_f32_e32 v19, v102, v103
	v_add_f32_e32 v19, v19, v114
	v_pk_mov_b32 v[102:103], v[110:111], v[124:125] op_sel:[1,0]
	v_add_f32_e32 v153, v19, v115
	v_pk_mul_f32 v[110:111], v[28:29], v[102:103]
	v_pk_mul_f32 v[102:103], v[26:27], v[102:103]
	v_add_f32_e32 v19, v80, v81
	v_add_f32_e32 v19, v19, v102
	v_add_f32_e32 v19, v19, v103
	v_mul_f32_e32 v80, 0xbfb8aa3b, v19
	v_exp_f32_e32 v80, v80
	v_pk_mul_f32 v[114:115], v[26:27], v[124:125]
	v_and_b32_e32 v81, 0xffff0000, v216
	v_fmac_f32_e32 v137, v18, v18
	v_add_f32_e32 v80, 1.0, v80
	v_rcp_f32_e32 v80, v80
	v_cvt_pk_bf16_f32 v18, v132, v18
	v_pk_mul_f32 v[132:133], v[28:29], v[124:125]
	v_mul_f32_e32 v19, v19, v80
	v_add_f32_e32 v80, v122, v123
	v_add_f32_e32 v80, v80, v114
	v_add_f32_e32 v114, v80, v115
	v_and_b32_e32 v80, 0xffff0000, v191
	v_pk_mov_b32 v[102:103], v[104:105], v[80:81] op_sel:[1,0]
	v_fmac_f32_e32 v137, v19, v19
	v_pk_mul_f32 v[120:121], v[10:11], v[102:103]
	v_pk_mul_f32 v[102:103], v[2:3], v[102:103]
	v_pk_mul_f32 v[104:105], v[2:3], v[80:81]
	v_add_f32_e32 v82, v82, v102
	v_add_f32_e32 v82, v82, v103
	v_mul_f32_e32 v83, 0xbfb8aa3b, v82
	v_exp_f32_e32 v83, v83
	v_lshlrev_b32_e32 v103, 16, v213
	v_pk_mul_f32 v[122:123], v[10:11], v[80:81]
	v_add_f32_e32 v120, v120, v121
	v_add_f32_e32 v83, 1.0, v83
	v_rcp_f32_e32 v83, v83
	s_nop 0
	v_mul_f32_e32 v82, v82, v83
	v_cvt_pk_bf16_f32 v19, v19, v82
	ds_write_b128 v169, v[16:19] offset:816
	v_add_f32_e32 v16, v84, v85
	v_add_f32_e32 v16, v16, v104
	v_mul_f32_e32 v18, 0xbfb8aa3b, v117
	v_add_f32_e32 v16, v16, v105
	v_mul_f32_e32 v17, 0xbfb8aa3b, v116
	v_exp_f32_e32 v18, v18
	v_fmac_f32_e32 v137, v82, v82
	v_exp_f32_e32 v17, v17
	v_mul_f32_e32 v19, 0xbfb8aa3b, v118
	v_mul_f32_e32 v82, 0xbfb8aa3b, v119
	v_mul_f32_e32 v102, 0xbfb8aa3b, v16
	v_exp_f32_e32 v19, v19
	v_exp_f32_e32 v82, v82
	v_mul_f32_e32 v83, 0xbfb8aa3b, v152
	v_mul_f32_e32 v84, 0xbfb8aa3b, v153
	v_mul_f32_e32 v85, 0xbfb8aa3b, v114
	v_exp_f32_e32 v102, v102
	v_exp_f32_e32 v83, v83
	v_exp_f32_e32 v84, v84
	v_exp_f32_e32 v85, v85
	v_add_f32_e32 v18, 1.0, v18
	v_add_f32_e32 v17, 1.0, v17
	v_rcp_f32_e32 v18, v18
	v_rcp_f32_e32 v17, v17
	v_add_f32_e32 v19, 1.0, v19
	v_add_f32_e32 v82, 1.0, v82
	v_add_f32_e32 v102, 1.0, v102
	v_rcp_f32_e32 v19, v19
	v_rcp_f32_e32 v82, v82
	v_add_f32_e32 v83, 1.0, v83
	v_add_f32_e32 v84, 1.0, v84
	v_add_f32_e32 v85, 1.0, v85
	v_rcp_f32_e32 v102, v102
	v_rcp_f32_e32 v83, v83
	v_rcp_f32_e32 v84, v84
	v_rcp_f32_e32 v85, v85
	v_mul_f32_e32 v18, v117, v18
	v_mul_f32_e32 v17, v116, v17
	v_mul_f32_e32 v191, v18, v18
	v_fmac_f32_e32 v191, v17, v17
	v_mul_f32_e32 v19, v118, v19
	v_mul_f32_e32 v82, v119, v82
	v_mul_f32_e32 v102, v16, v102
	v_cvt_pk_bf16_f32 v16, v17, v18
	v_cvt_pk_bf16_f32 v17, v19, v82
	v_lshlrev_b32_e32 v119, 16, v215
	v_lshlrev_b32_e32 v118, 16, v192
	v_fmac_f32_e32 v191, v19, v19
	v_mul_f32_e32 v83, v152, v83
	v_mul_f32_e32 v84, v153, v84
	v_mul_f32_e32 v85, v114, v85
	v_cvt_pk_bf16_f32 v18, v83, v84
	v_cvt_pk_bf16_f32 v19, v85, v102
	ds_write_b128 v169, v[16:19] offset:1088
	v_pk_mov_b32 v[16:17], v[112:113], v[118:119] op_sel:[1,0]
	v_fmac_f32_e32 v191, v82, v82
	v_pk_mul_f32 v[116:117], v[64:65], v[16:17]
	v_pk_mul_f32 v[16:17], v[24:25], v[16:17]
	v_add_f32_e32 v82, v86, v87
	v_add_f32_e32 v16, v82, v16
	v_add_f32_e32 v16, v16, v17
	v_mul_f32_e32 v17, 0xbfb8aa3b, v16
	v_exp_f32_e32 v17, v17
	v_pk_mul_f32 v[18:19], v[24:25], v[118:119]
	v_and_b32_e32 v113, 0xffff0000, v215
	v_and_b32_e32 v112, 0xffff0000, v192
	v_add_f32_e32 v17, 1.0, v17
	v_rcp_f32_e32 v17, v17
	v_fmac_f32_e32 v191, v83, v83
	v_add_f32_e32 v83, v92, v93
	v_lshlrev_b32_e32 v105, 16, v214
	v_mul_f32_e32 v82, v16, v17
	v_add_f32_e32 v16, v126, v127
	v_add_f32_e32 v16, v16, v18
	v_add_f32_e32 v126, v16, v19
	v_pk_mov_b32 v[16:17], v[68:69], v[112:113] op_sel:[1,0]
	v_pk_mul_f32 v[18:19], v[4:5], v[112:113]
	v_pk_mul_f32 v[68:69], v[12:13], v[16:17]
	v_pk_mul_f32 v[16:17], v[4:5], v[16:17]
	v_lshlrev_b32_e32 v104, 16, v212
	v_add_f32_e32 v16, v83, v16
	v_add_f32_e32 v16, v16, v17
	v_mul_f32_e32 v17, 0xbfb8aa3b, v16
	v_exp_f32_e32 v17, v17
	v_and_b32_e32 v87, 0xffff0000, v214
	v_and_b32_e32 v86, 0xffff0000, v212
	v_add_f32_e32 v92, v96, v97
	v_add_f32_e32 v17, 1.0, v17
	v_rcp_f32_e32 v17, v17
	v_fmac_f32_e32 v191, v84, v84
	v_fmac_f32_e32 v191, v85, v85
	v_fmac_f32_e32 v191, v102, v102
	v_mul_f32_e32 v16, v16, v17
	v_add_f32_e32 v17, v70, v71
	v_add_f32_e32 v17, v17, v18
	v_add_f32_e32 v127, v17, v19
	v_pk_mov_b32 v[18:19], v[106:107], v[104:105] op_sel:[1,0]
	v_add_f32_e32 v17, v94, v95
	v_pk_mul_f32 v[70:71], v[62:63], v[18:19]
	v_pk_mul_f32 v[18:19], v[20:21], v[18:19]
	v_mul_f32_e32 v192, v16, v16
	v_add_f32_e32 v17, v17, v18
	v_add_f32_e32 v17, v17, v19
	v_mul_f32_e32 v18, 0xbfb8aa3b, v17
	v_exp_f32_e32 v18, v18
	v_fmac_f32_e32 v192, v82, v82
	v_cvt_pk_bf16_f32 v16, v82, v16
	v_pk_mul_f32 v[82:83], v[20:21], v[104:105]
	v_add_f32_e32 v18, 1.0, v18
	v_rcp_f32_e32 v18, v18
	v_lshlrev_b32_e32 v102, 16, v194
	v_add_f32_e32 v94, v98, v99
	v_and_b32_e32 v95, 0xffff0000, v213
	v_mul_f32_e32 v17, v17, v18
	v_add_f32_e32 v18, v128, v129
	v_add_f32_e32 v18, v18, v82
	v_add_f32_e32 v128, v18, v83
	v_pk_mov_b32 v[18:19], v[72:73], v[86:87] op_sel:[1,0]
	v_fmac_f32_e32 v192, v17, v17
	v_pk_mul_f32 v[72:73], v[14:15], v[18:19]
	v_pk_mul_f32 v[18:19], v[6:7], v[18:19]
	v_pk_mul_f32 v[82:83], v[6:7], v[86:87]
	v_add_f32_e32 v18, v92, v18
	v_add_f32_e32 v18, v18, v19
	v_mul_f32_e32 v19, 0xbfb8aa3b, v18
	v_exp_f32_e32 v19, v19
	v_add_f32_e32 v96, v100, v101
	v_lshlrev_b32_e32 v101, 16, v195
	v_lshlrev_b32_e32 v100, 16, v193
	v_add_f32_e32 v19, 1.0, v19
	v_rcp_f32_e32 v19, v19
	v_pk_mul_f32 v[114:115], v[64:65], v[118:119]
	v_pk_mul_f32 v[84:85], v[12:13], v[112:113]
	v_mul_f32_e32 v18, v18, v19
	v_fmac_f32_e32 v192, v18, v18
	v_cvt_pk_bf16_f32 v17, v17, v18
	v_add_f32_e32 v18, v74, v75
	v_add_f32_e32 v18, v18, v82
	v_add_f32_e32 v129, v18, v83
	v_pk_mov_b32 v[18:19], v[108:109], v[102:103] op_sel:[1,0]
	v_pk_mul_f32 v[82:83], v[22:23], v[102:103]
	v_pk_mul_f32 v[74:75], v[30:31], v[18:19]
	v_pk_mul_f32 v[18:19], v[22:23], v[18:19]
	v_pk_mul_f32 v[106:107], v[62:63], v[104:105]
	v_add_f32_e32 v18, v94, v18
	v_add_f32_e32 v18, v18, v19
	v_mul_f32_e32 v19, 0xbfb8aa3b, v18
	v_exp_f32_e32 v19, v19
	v_and_b32_e32 v94, 0xffff0000, v194
	v_pk_mul_f32 v[92:93], v[14:15], v[86:87]
	v_pk_mul_f32 v[108:109], v[30:31], v[102:103]
	v_add_f32_e32 v19, 1.0, v19
	v_rcp_f32_e32 v19, v19
	s_nop 0
	v_mul_f32_e32 v98, v18, v19
	v_add_f32_e32 v18, v130, v131
	v_add_f32_e32 v18, v18, v82
	v_add_f32_e32 v130, v18, v83
	v_pk_mov_b32 v[18:19], v[76:77], v[94:95] op_sel:[1,0]
	v_pk_mul_f32 v[82:83], v[0:1], v[94:95]
	v_pk_mul_f32 v[76:77], v[8:9], v[18:19]
	v_pk_mul_f32 v[18:19], v[0:1], v[18:19]
	v_fmac_f32_e32 v192, v98, v98
	v_add_f32_e32 v18, v96, v18
	v_add_f32_e32 v18, v18, v19
	v_mul_f32_e32 v19, 0xbfb8aa3b, v18
	v_exp_f32_e32 v19, v19
	v_mul_f32_e32 v121, 0xbfb8aa3b, v130
	v_exp_f32_e32 v121, v121
	v_pk_mul_f32 v[96:97], v[8:9], v[94:95]
	v_add_f32_e32 v19, 1.0, v19
	v_rcp_f32_e32 v19, v19
	v_add_f32_e32 v121, 1.0, v121
	v_rcp_f32_e32 v121, v121
	v_mul_f32_e32 v18, v18, v19
	v_add_f32_e32 v19, v78, v79
	v_add_f32_e32 v19, v19, v82
	v_add_f32_e32 v131, v19, v83
	v_pk_mov_b32 v[82:83], v[124:125], v[100:101] op_sel:[1,0]
	v_add_f32_e32 v19, v110, v111
	v_pk_mul_f32 v[78:79], v[28:29], v[82:83]
	v_pk_mul_f32 v[82:83], v[26:27], v[82:83]
	v_fmac_f32_e32 v192, v18, v18
	v_add_f32_e32 v19, v19, v82
	v_add_f32_e32 v19, v19, v83
	v_mul_f32_e32 v82, 0xbfb8aa3b, v19
	v_exp_f32_e32 v82, v82
	v_cvt_pk_bf16_f32 v18, v98, v18
	v_pk_mul_f32 v[98:99], v[26:27], v[100:101]
	v_mul_f32_e32 v121, v130, v121
	v_add_f32_e32 v82, 1.0, v82
	v_rcp_f32_e32 v82, v82
	v_pk_mul_f32 v[110:111], v[28:29], v[100:101]
	v_mul_f32_e32 v19, v19, v82
	v_add_f32_e32 v82, v132, v133
	v_add_f32_e32 v82, v82, v98
	v_add_f32_e32 v133, v82, v99
	v_and_b32_e32 v99, 0xffff0000, v195
	v_and_b32_e32 v98, 0xffff0000, v193
	v_pk_mov_b32 v[82:83], v[80:81], v[98:99] op_sel:[1,0]
	v_fmac_f32_e32 v192, v19, v19
	v_pk_mul_f32 v[80:81], v[10:11], v[82:83]
	v_pk_mul_f32 v[82:83], v[2:3], v[82:83]
	v_pk_mul_f32 v[124:125], v[2:3], v[98:99]
	v_add_f32_e32 v82, v120, v82
	v_add_f32_e32 v82, v82, v83
	v_mul_f32_e32 v83, 0xbfb8aa3b, v82
	v_exp_f32_e32 v83, v83
	s_nop 0
	v_add_f32_e32 v83, 1.0, v83
	v_rcp_f32_e32 v83, v83
	s_nop 0
	v_mul_f32_e32 v120, v82, v83
	v_cvt_pk_bf16_f32 v19, v19, v120
	ds_write_b128 v169, v[16:19] offset:1360
	v_mul_f32_e32 v18, 0xbfb8aa3b, v127
	v_mul_f32_e32 v17, 0xbfb8aa3b, v126
	v_exp_f32_e32 v18, v18
	v_exp_f32_e32 v17, v17
	v_mul_f32_e32 v19, 0xbfb8aa3b, v128
	v_fmac_f32_e32 v192, v120, v120
	v_exp_f32_e32 v19, v19
	v_mul_f32_e32 v120, 0xbfb8aa3b, v129
	v_add_f32_e32 v16, v122, v123
	v_exp_f32_e32 v120, v120
	v_add_f32_e32 v16, v16, v124
	v_add_f32_e32 v18, 1.0, v18
	v_mul_f32_e32 v122, 0xbfb8aa3b, v131
	v_add_f32_e32 v16, v16, v125
	v_add_f32_e32 v17, 1.0, v17
	v_rcp_f32_e32 v18, v18
	v_exp_f32_e32 v122, v122
	v_mul_f32_e32 v123, 0xbfb8aa3b, v133
	v_rcp_f32_e32 v17, v17
	v_add_f32_e32 v19, 1.0, v19
	v_exp_f32_e32 v123, v123
	v_mul_f32_e32 v124, 0xbfb8aa3b, v16
	v_rcp_f32_e32 v19, v19
	v_add_f32_e32 v120, 1.0, v120
	v_exp_f32_e32 v124, v124
	v_rcp_f32_e32 v120, v120
	v_mul_f32_e32 v18, v127, v18
	v_add_f32_e32 v122, 1.0, v122
	v_mul_f32_e32 v17, v126, v17
	v_mul_f32_e32 v132, v18, v18
	v_rcp_f32_e32 v122, v122
	v_add_f32_e32 v123, 1.0, v123
	v_fmac_f32_e32 v132, v17, v17
	v_mul_f32_e32 v19, v128, v19
	v_rcp_f32_e32 v123, v123
	v_add_f32_e32 v124, 1.0, v124
	v_fmac_f32_e32 v132, v19, v19
	v_mul_f32_e32 v120, v129, v120
	v_rcp_f32_e32 v124, v124
	v_fmac_f32_e32 v132, v120, v120
	v_fmac_f32_e32 v132, v121, v121
	v_mul_f32_e32 v122, v131, v122
	v_fmac_f32_e32 v132, v122, v122
	v_mul_f32_e32 v123, v133, v123
	v_fmac_f32_e32 v132, v123, v123
	v_mul_f32_e32 v124, v16, v124
	v_fmac_f32_e32 v132, v124, v124
	v_pk_mul_f32 v[82:83], v[10:11], v[98:99]
	v_cvt_pk_bf16_f32 v16, v17, v18
	v_cvt_pk_bf16_f32 v17, v19, v120
	v_cvt_pk_bf16_f32 v18, v121, v122
	v_cvt_pk_bf16_f32 v19, v123, v124
	ds_write_b128 v169, v[16:19] offset:1632
	s_mov_b32 s28, 0x130df000
	v_add_co_u32_e32 v120, vcc, 0x130c3000, v66
	s_nop 1
	v_addc_co_u32_e32 v121, vcc, 0, v67, vcc
	global_load_dwordx4 v[126:129], v[120:121], off
	v_add_co_u32_e32 v16, vcc, 0x130be000, v66
	s_nop 1
	v_addc_co_u32_e32 v17, vcc, 0, v67, vcc
	global_load_dwordx4 v[16:19], v[16:17], off offset:3584
	v_add_co_u32_e32 v120, vcc, 0x130c7000, v66
	s_nop 1
	v_addc_co_u32_e32 v121, vcc, 0, v67, vcc
	global_load_dwordx4 v[242:245], v[120:121], off offset:512
	v_add_co_u32_e32 v120, vcc, 0x130cb000, v66
	s_nop 1
	v_addc_co_u32_e32 v121, vcc, 0, v67, vcc
	global_load_dwordx4 v[246:249], v[120:121], off offset:1024
	v_add_co_u32_e32 v120, vcc, 0x130cf000, v66
	s_nop 1
	v_addc_co_u32_e32 v121, vcc, 0, v67, vcc
	global_load_dwordx2 v[130:131], v[120:121], off offset:1536
	global_load_dwordx2 v[152:153], v[120:121], off offset:1544
	v_add_co_u32_e32 v120, vcc, 0x130d3000, v66
	s_nop 1
	v_addc_co_u32_e32 v121, vcc, 0, v67, vcc
	global_load_dwordx2 v[238:239], v[120:121], off offset:2048
	global_load_dword v133, v[120:121], off offset:2056
	global_load_dword v194, v[120:121], off offset:2060
	v_add_f32_e32 v114, v114, v115
	v_add_f32_e32 v116, v116, v117
	v_add_f32_e32 v70, v70, v71
	v_add_f32_e32 v74, v74, v75
	v_add_f32_e32 v78, v78, v79
	s_waitcnt vmcnt(8)
	v_cndmask_b32_e64 v122, v129, 0, s[48:49]
	v_cndmask_b32_e64 v123, v128, 0, s[48:49]
	v_cndmask_b32_e64 v124, v127, 0, s[48:49]
	v_cndmask_b32_e64 v125, v126, 0, s[48:49]
	v_add_co_u32_e32 v120, vcc, 0x130df000, v66
	s_nop 1
	v_addc_co_u32_e32 v121, vcc, 0, v67, vcc
	global_load_dwordx4 v[126:129], v[120:121], off offset:3584
	v_and_b32_e32 v115, 0xffff0000, v125
	s_waitcnt vmcnt(7)
	v_cndmask_b32_e64 v231, v245, 0, s[48:49]
	v_cndmask_b32_e64 v233, v244, 0, s[48:49]
	v_cndmask_b32_e64 v235, v243, 0, s[48:49]
	v_cndmask_b32_e64 v214, v242, 0, s[48:49]
	v_add_co_u32_e32 v120, vcc, 0x130d7000, v66
	s_nop 1
	v_addc_co_u32_e32 v121, vcc, 0, v67, vcc
	global_load_dwordx4 v[242:245], v[120:121], off offset:2560
	s_waitcnt vmcnt(7)
	v_cndmask_b32_e64 v232, v249, 0, s[48:49]
	v_cndmask_b32_e64 v234, v248, 0, s[48:49]
	v_cndmask_b32_e64 v236, v247, 0, s[48:49]
	v_cndmask_b32_e64 v237, v246, 0, s[48:49]
	v_add_co_u32_e32 v120, vcc, 0x130db000, v66
	s_nop 1
	v_addc_co_u32_e32 v121, vcc, 0, v67, vcc
	global_load_dwordx4 v[246:249], v[120:121], off offset:3072
	s_waitcnt vmcnt(6)
	v_cndmask_b32_e64 v223, v153, 0, s[48:49]
	v_cndmask_b32_e64 v225, v152, 0, s[48:49]
	v_cndmask_b32_e64 v227, v131, 0, s[48:49]
	v_cndmask_b32_e64 v229, v130, 0, s[48:49]
	s_waitcnt vmcnt(3)
	v_cndmask_b32_e64 v224, v194, 0, s[48:49]
	v_cndmask_b32_e64 v226, v133, 0, s[48:49]
	v_cndmask_b32_e64 v228, v239, 0, s[48:49]
	v_cndmask_b32_e64 v230, v238, 0, s[48:49]
	s_waitcnt vmcnt(1)
	v_cndmask_b32_e64 v215, v245, 0, s[62:63]
	v_cndmask_b32_e64 v217, v244, 0, s[62:63]
	v_cndmask_b32_e64 v219, v243, 0, s[62:63]
	v_cndmask_b32_e64 v221, v242, 0, s[62:63]
	v_lshlrev_b32_e32 v121, 16, v125
	s_waitcnt vmcnt(0)
	v_cndmask_b32_e64 v216, v249, 0, s[64:65]
	v_cndmask_b32_e64 v218, v248, 0, s[64:65]
	v_cndmask_b32_e64 v220, v247, 0, s[64:65]
	v_cndmask_b32_e64 v222, v246, 0, s[64:65]
	v_cndmask_b32_e64 v16, v16, 0, s[48:49]
	v_lshlrev_b32_e32 v120, 16, v16
	v_pk_mov_b32 v[118:119], v[118:119], v[120:121] op_sel:[1,0]
	v_cndmask_b32_e64 v17, v17, 0, s[48:49]
	v_pk_mul_f32 v[66:67], v[64:65], v[118:119]
	v_pk_mul_f32 v[118:119], v[24:25], v[118:119]
	v_cndmask_b32_e64 v18, v18, 0, s[48:49]
	v_add_f32_e32 v116, v116, v118
	v_add_f32_e32 v116, v116, v119
	v_mul_f32_e32 v117, 0xbfb8aa3b, v116
	v_exp_f32_e32 v117, v117
	v_cndmask_b32_e64 v19, v19, 0, s[48:49]
	v_add_f32_e32 v66, v66, v67
	v_add_f32_e32 v117, 1.0, v117
	v_rcp_f32_e32 v117, v117
	s_waitcnt vmcnt(0)
	v_cndmask_b32_e64 v212, v127, 0, s[66:67]
	v_cndmask_b32_e64 v213, v126, 0, s[66:67]
	v_pk_mul_f32 v[126:127], v[24:25], v[120:121]
	v_cndmask_b32_e64 v195, v128, 0, s[66:67]
	v_add_f32_e32 v114, v114, v126
	v_add_f32_e32 v193, v114, v127
	v_and_b32_e32 v114, 0xffff0000, v16
	v_pk_mov_b32 v[118:119], v[112:113], v[114:115] op_sel:[1,0]
	v_add_f32_e32 v16, v68, v69
	v_pk_mul_f32 v[112:113], v[12:13], v[118:119]
	v_pk_mul_f32 v[118:119], v[4:5], v[118:119]
	v_pk_mul_f32 v[126:127], v[4:5], v[114:115]
	v_add_f32_e32 v16, v16, v118
	v_add_f32_e32 v16, v16, v119
	v_mul_f32_e32 v68, 0xbfb8aa3b, v16
	v_exp_f32_e32 v68, v68
	v_mul_f32_e32 v128, v116, v117
	v_cndmask_b32_e64 v194, v129, 0, s[66:67]
	v_pk_mul_f32 v[116:117], v[64:65], v[120:121]
	v_add_f32_e32 v68, 1.0, v68
	v_rcp_f32_e32 v68, v68
	v_pk_mul_f32 v[118:119], v[12:13], v[114:115]
	v_mul_f32_e32 v16, v16, v68
	v_add_f32_e32 v68, v84, v85
	v_lshlrev_b32_e32 v85, 16, v124
	v_lshlrev_b32_e32 v84, 16, v17
	v_add_f32_e32 v68, v68, v126
	v_pk_mov_b32 v[104:105], v[104:105], v[84:85] op_sel:[1,0]
	v_add_f32_e32 v152, v68, v127
	v_pk_mul_f32 v[68:69], v[62:63], v[104:105]
	v_pk_mul_f32 v[104:105], v[20:21], v[104:105]
	v_mul_f32_e32 v133, v16, v16
	v_add_f32_e32 v70, v70, v104
	v_add_f32_e32 v70, v70, v105
	v_mul_f32_e32 v71, 0xbfb8aa3b, v70
	v_exp_f32_e32 v71, v71
	v_fmac_f32_e32 v133, v128, v128
	v_cvt_pk_bf16_f32 v16, v128, v16
	v_pk_mul_f32 v[128:129], v[20:21], v[84:85]
	v_add_f32_e32 v71, 1.0, v71
	v_rcp_f32_e32 v71, v71
	v_and_b32_e32 v105, 0xffff0000, v124
	v_and_b32_e32 v104, 0xffff0000, v17
	v_pk_mov_b32 v[86:87], v[86:87], v[104:105] op_sel:[1,0]
	v_mul_f32_e32 v125, v70, v71
	v_add_f32_e32 v70, v106, v107
	v_add_f32_e32 v70, v70, v128
	v_add_f32_e32 v153, v70, v129
	v_pk_mul_f32 v[70:71], v[14:15], v[86:87]
	v_pk_mul_f32 v[86:87], v[6:7], v[86:87]
	v_add_f32_e32 v17, v72, v73
	v_add_f32_e32 v17, v17, v86
	v_add_f32_e32 v17, v17, v87
	v_mul_f32_e32 v72, 0xbfb8aa3b, v17
	v_exp_f32_e32 v72, v72
	v_pk_mul_f32 v[106:107], v[6:7], v[104:105]
	v_fmac_f32_e32 v133, v125, v125
	v_pk_mul_f32 v[126:127], v[62:63], v[84:85]
	v_add_f32_e32 v72, 1.0, v72
	v_rcp_f32_e32 v72, v72
	v_add_f32_e32 v70, v70, v71
	v_pk_mul_f32 v[86:87], v[14:15], v[104:105]
	v_mul_f32_e32 v17, v17, v72
	v_add_f32_e32 v72, v92, v93
	v_add_f32_e32 v72, v72, v106
	v_add_f32_e32 v238, v72, v107
	v_lshlrev_b32_e32 v107, 16, v123
	v_lshlrev_b32_e32 v106, 16, v18
	v_pk_mov_b32 v[92:93], v[102:103], v[106:107] op_sel:[1,0]
	v_pk_mul_f32 v[102:103], v[22:23], v[106:107]
	v_pk_mul_f32 v[72:73], v[30:31], v[92:93]
	v_pk_mul_f32 v[92:93], v[22:23], v[92:93]
	v_fmac_f32_e32 v133, v17, v17
	v_add_f32_e32 v74, v74, v92
	v_add_f32_e32 v74, v74, v93
	v_mul_f32_e32 v75, 0xbfb8aa3b, v74
	v_exp_f32_e32 v75, v75
	v_and_b32_e32 v93, 0xffff0000, v123
	v_and_b32_e32 v92, 0xffff0000, v18
	v_pk_mov_b32 v[94:95], v[94:95], v[92:93] op_sel:[1,0]
	v_add_f32_e32 v75, 1.0, v75
	v_rcp_f32_e32 v75, v75
	v_add_f32_e32 v18, v76, v77
	v_cvt_pk_bf16_f32 v17, v125, v17
	v_lshlrev_b32_e32 v125, 16, v122
	v_mul_f32_e32 v124, v74, v75
	v_add_f32_e32 v74, v108, v109
	v_add_f32_e32 v74, v74, v102
	v_add_f32_e32 v108, v74, v103
	v_pk_mul_f32 v[74:75], v[8:9], v[94:95]
	v_pk_mul_f32 v[94:95], v[0:1], v[94:95]
	v_fmac_f32_e32 v133, v124, v124
	v_add_f32_e32 v18, v18, v94
	v_add_f32_e32 v18, v18, v95
	v_mul_f32_e32 v76, 0xbfb8aa3b, v18
	v_exp_f32_e32 v76, v76
	v_pk_mul_f32 v[102:103], v[0:1], v[92:93]
	v_lshlrev_b32_e32 v123, 16, v237
	v_add_f32_e32 v72, v72, v73
	v_add_f32_e32 v76, 1.0, v76
	v_rcp_f32_e32 v76, v76
	v_pk_mul_f32 v[128:129], v[30:31], v[106:107]
	v_add_f32_e32 v74, v74, v75
	v_pk_mul_f32 v[94:95], v[8:9], v[92:93]
	v_mul_f32_e32 v18, v18, v76
	v_fmac_f32_e32 v133, v18, v18
	v_cvt_pk_bf16_f32 v18, v124, v18
	v_add_f32_e32 v76, v96, v97
	v_lshlrev_b32_e32 v124, 16, v19
	v_add_f32_e32 v76, v76, v102
	v_pk_mov_b32 v[96:97], v[100:101], v[124:125] op_sel:[1,0]
	v_add_f32_e32 v102, v76, v103
	v_pk_mul_f32 v[76:77], v[28:29], v[96:97]
	v_pk_mul_f32 v[96:97], v[26:27], v[96:97]
	v_pk_mul_f32 v[100:101], v[26:27], v[124:125]
	v_add_f32_e32 v78, v78, v96
	v_add_f32_e32 v78, v78, v97
	v_mul_f32_e32 v79, 0xbfb8aa3b, v78
	v_exp_f32_e32 v79, v79
	v_and_b32_e32 v97, 0xffff0000, v122
	v_and_b32_e32 v96, 0xffff0000, v19
	v_pk_mov_b32 v[98:99], v[98:99], v[96:97] op_sel:[1,0]
	v_add_f32_e32 v79, 1.0, v79
	v_rcp_f32_e32 v79, v79
	v_add_f32_e32 v19, v80, v81
	v_lshlrev_b32_e32 v122, 16, v214
	v_pk_mul_f32 v[130:131], v[28:29], v[124:125]
	v_mul_f32_e32 v103, v78, v79
	v_add_f32_e32 v78, v110, v111
	v_add_f32_e32 v78, v78, v100
	v_add_f32_e32 v109, v78, v101
	v_pk_mul_f32 v[78:79], v[10:11], v[98:99]
	v_pk_mul_f32 v[98:99], v[2:3], v[98:99]
	v_fmac_f32_e32 v133, v103, v103
	v_add_f32_e32 v19, v19, v98
	v_add_f32_e32 v19, v19, v99
	v_mul_f32_e32 v80, 0xbfb8aa3b, v19
	v_exp_f32_e32 v80, v80
	v_pk_mul_f32 v[100:101], v[2:3], v[96:97]
	v_mul_f32_e32 v98, 0xbfb8aa3b, v102
	v_mul_f32_e32 v99, 0xbfb8aa3b, v109
	v_add_f32_e32 v80, 1.0, v80
	v_rcp_f32_e32 v80, v80
	v_exp_f32_e32 v98, v98
	v_exp_f32_e32 v99, v99
	v_lshlrev_b32_e32 v111, 16, v236
	v_mul_f32_e32 v19, v19, v80
	v_fmac_f32_e32 v133, v19, v19
	v_cvt_pk_bf16_f32 v19, v103, v19
	ds_write_b128 v169, v[16:19] offset:1904
	v_add_f32_e32 v16, v82, v83
	v_mul_f32_e32 v18, 0xbfb8aa3b, v152
	v_add_f32_e32 v16, v16, v100
	v_mul_f32_e32 v17, 0xbfb8aa3b, v193
	v_exp_f32_e32 v18, v18
	v_add_f32_e32 v16, v16, v101
	v_exp_f32_e32 v17, v17
	v_mul_f32_e32 v19, 0xbfb8aa3b, v153
	v_exp_f32_e32 v19, v19
	v_mul_f32_e32 v82, 0xbfb8aa3b, v238
	v_mul_f32_e32 v100, 0xbfb8aa3b, v16
	v_exp_f32_e32 v82, v82
	v_mul_f32_e32 v83, 0xbfb8aa3b, v108
	v_exp_f32_e32 v100, v100
	v_add_f32_e32 v18, 1.0, v18
	v_exp_f32_e32 v83, v83
	v_add_f32_e32 v17, 1.0, v17
	v_rcp_f32_e32 v18, v18
	v_rcp_f32_e32 v17, v17
	v_add_f32_e32 v19, 1.0, v19
	v_rcp_f32_e32 v19, v19
	v_add_f32_e32 v82, 1.0, v82
	v_add_f32_e32 v100, 1.0, v100
	v_rcp_f32_e32 v82, v82
	v_add_f32_e32 v83, 1.0, v83
	v_add_f32_e32 v98, 1.0, v98
	v_add_f32_e32 v99, 1.0, v99
	v_rcp_f32_e32 v100, v100
	v_mul_f32_e32 v18, v152, v18
	v_rcp_f32_e32 v83, v83
	v_rcp_f32_e32 v98, v98
	v_rcp_f32_e32 v99, v99
	v_mul_f32_e32 v17, v193, v17
	v_mul_f32_e32 v193, v18, v18
	v_fmac_f32_e32 v193, v17, v17
	v_mul_f32_e32 v19, v153, v19
	v_fmac_f32_e32 v193, v19, v19
	v_mul_f32_e32 v82, v238, v82
	v_mul_f32_e32 v100, v16, v100
	v_cvt_pk_bf16_f32 v16, v17, v18
	v_cvt_pk_bf16_f32 v17, v19, v82
	v_fmac_f32_e32 v193, v82, v82
	v_mul_f32_e32 v83, v108, v83
	v_mul_f32_e32 v98, v102, v98
	v_mul_f32_e32 v99, v109, v99
	v_cvt_pk_bf16_f32 v18, v83, v98
	v_cvt_pk_bf16_f32 v19, v99, v100
	ds_write_b128 v169, v[16:19] offset:2176
	v_pk_mov_b32 v[16:17], v[120:121], v[122:123] op_sel:[1,0]
	v_fmac_f32_e32 v193, v83, v83
	v_pk_mul_f32 v[82:83], v[64:65], v[16:17]
	v_pk_mul_f32 v[16:17], v[24:25], v[16:17]
	v_fmac_f32_e32 v193, v98, v98
	v_add_f32_e32 v16, v66, v16
	v_add_f32_e32 v16, v16, v17
	v_mul_f32_e32 v17, 0xbfb8aa3b, v16
	v_exp_f32_e32 v17, v17
	v_pk_mul_f32 v[18:19], v[24:25], v[122:123]
	v_fmac_f32_e32 v193, v99, v99
	v_and_b32_e32 v99, 0xffff0000, v237
	v_add_f32_e32 v17, 1.0, v17
	v_rcp_f32_e32 v17, v17
	v_and_b32_e32 v98, 0xffff0000, v214
	v_fmac_f32_e32 v193, v100, v100
	v_add_f32_e32 v100, v112, v113
	v_mul_f32_e32 v102, v16, v17
	v_add_f32_e32 v16, v116, v117
	v_add_f32_e32 v16, v16, v18
	v_add_f32_e32 v238, v16, v19
	v_pk_mov_b32 v[16:17], v[114:115], v[98:99] op_sel:[1,0]
	v_pk_mul_f32 v[18:19], v[4:5], v[98:99]
	v_pk_mul_f32 v[66:67], v[12:13], v[16:17]
	v_pk_mul_f32 v[16:17], v[4:5], v[16:17]
	v_lshlrev_b32_e32 v110, 16, v235
	v_add_f32_e32 v16, v100, v16
	v_add_f32_e32 v16, v16, v17
	v_mul_f32_e32 v17, 0xbfb8aa3b, v16
	v_exp_f32_e32 v17, v17
	v_pk_mul_f32 v[80:81], v[10:11], v[96:97]
	v_add_f32_e32 v78, v78, v79
	v_add_f32_e32 v17, 1.0, v17
	v_rcp_f32_e32 v17, v17
	v_add_f32_e32 v82, v82, v83
	v_pk_mul_f32 v[120:121], v[64:65], v[122:123]
	v_add_f32_e32 v66, v66, v67
	v_mul_f32_e32 v16, v16, v17
	v_add_f32_e32 v17, v118, v119
	v_add_f32_e32 v17, v17, v18
	v_add_f32_e32 v152, v17, v19
	v_pk_mov_b32 v[18:19], v[84:85], v[110:111] op_sel:[1,0]
	v_add_f32_e32 v17, v68, v69
	v_pk_mul_f32 v[84:85], v[62:63], v[18:19]
	v_pk_mul_f32 v[18:19], v[20:21], v[18:19]
	v_mul_f32_e32 v214, v16, v16
	v_add_f32_e32 v17, v17, v18
	v_add_f32_e32 v17, v17, v19
	v_mul_f32_e32 v18, 0xbfb8aa3b, v17
	v_exp_f32_e32 v18, v18
	v_fmac_f32_e32 v214, v102, v102
	v_cvt_pk_bf16_f32 v16, v102, v16
	v_pk_mul_f32 v[102:103], v[20:21], v[110:111]
	v_add_f32_e32 v18, 1.0, v18
	v_rcp_f32_e32 v18, v18
	v_pk_mul_f32 v[100:101], v[12:13], v[98:99]
	v_pk_mul_f32 v[112:113], v[62:63], v[110:111]
	v_mul_f32_e32 v17, v17, v18
	v_add_f32_e32 v18, v126, v127
	v_add_f32_e32 v18, v18, v102
	v_add_f32_e32 v127, v18, v103
	v_and_b32_e32 v103, 0xffff0000, v236
	v_and_b32_e32 v102, 0xffff0000, v235
	v_pk_mov_b32 v[18:19], v[104:105], v[102:103] op_sel:[1,0]
	v_fmac_f32_e32 v214, v17, v17
	v_pk_mul_f32 v[68:69], v[14:15], v[18:19]
	v_pk_mul_f32 v[18:19], v[6:7], v[18:19]
	v_pk_mul_f32 v[108:109], v[6:7], v[102:103]
	v_add_f32_e32 v18, v70, v18
	v_add_f32_e32 v18, v18, v19
	v_mul_f32_e32 v19, 0xbfb8aa3b, v18
	v_exp_f32_e32 v19, v19
	v_add_f32_e32 v68, v68, v69
	v_pk_mul_f32 v[104:105], v[14:15], v[102:103]
	v_add_f32_e32 v19, 1.0, v19
	v_rcp_f32_e32 v19, v19
	s_nop 0
	v_mul_f32_e32 v18, v18, v19
	v_fmac_f32_e32 v214, v18, v18
	v_cvt_pk_bf16_f32 v17, v17, v18
	v_add_f32_e32 v18, v86, v87
	v_add_f32_e32 v18, v18, v108
	v_add_f32_e32 v153, v18, v109
	v_lshlrev_b32_e32 v109, 16, v234
	v_lshlrev_b32_e32 v108, 16, v233
	v_pk_mov_b32 v[18:19], v[106:107], v[108:109] op_sel:[1,0]
	v_pk_mul_f32 v[86:87], v[22:23], v[108:109]
	v_pk_mul_f32 v[70:71], v[30:31], v[18:19]
	v_pk_mul_f32 v[18:19], v[22:23], v[18:19]
	v_add_f32_e32 v70, v70, v71
	v_add_f32_e32 v18, v72, v18
	v_add_f32_e32 v18, v18, v19
	v_mul_f32_e32 v19, 0xbfb8aa3b, v18
	v_exp_f32_e32 v19, v19
	v_pk_mul_f32 v[114:115], v[30:31], v[108:109]
	v_add_f32_e32 v19, 1.0, v19
	v_rcp_f32_e32 v19, v19
	s_nop 0
	v_mul_f32_e32 v116, v18, v19
	v_add_f32_e32 v18, v128, v129
	v_add_f32_e32 v18, v18, v86
	v_add_f32_e32 v128, v18, v87
	v_and_b32_e32 v87, 0xffff0000, v234
	v_and_b32_e32 v86, 0xffff0000, v233
	v_pk_mov_b32 v[18:19], v[92:93], v[86:87] op_sel:[1,0]
	v_pk_mul_f32 v[106:107], v[0:1], v[86:87]
	v_pk_mul_f32 v[72:73], v[8:9], v[18:19]
	v_pk_mul_f32 v[18:19], v[0:1], v[18:19]
	v_fmac_f32_e32 v214, v116, v116
	v_add_f32_e32 v18, v74, v18
	v_add_f32_e32 v18, v18, v19
	v_mul_f32_e32 v19, 0xbfb8aa3b, v18
	v_exp_f32_e32 v19, v19
	v_add_f32_e32 v72, v72, v73
	v_pk_mul_f32 v[92:93], v[8:9], v[86:87]
	v_add_f32_e32 v19, 1.0, v19
	v_rcp_f32_e32 v19, v19
	s_nop 0
	v_mul_f32_e32 v18, v18, v19
	v_add_f32_e32 v19, v94, v95
	v_add_f32_e32 v19, v19, v106
	v_add_f32_e32 v129, v19, v107
	v_lshlrev_b32_e32 v107, 16, v232
	v_lshlrev_b32_e32 v106, 16, v231
	v_pk_mov_b32 v[94:95], v[124:125], v[106:107] op_sel:[1,0]
	v_add_f32_e32 v19, v76, v77
	v_pk_mul_f32 v[74:75], v[28:29], v[94:95]
	v_pk_mul_f32 v[94:95], v[26:27], v[94:95]
	v_pk_mul_f32 v[118:119], v[26:27], v[106:107]
	v_add_f32_e32 v19, v19, v94
	v_add_f32_e32 v19, v19, v95
	v_mul_f32_e32 v76, 0xbfb8aa3b, v19
	v_exp_f32_e32 v76, v76
	v_and_b32_e32 v95, 0xffff0000, v232
	v_and_b32_e32 v94, 0xffff0000, v231
	v_pk_mov_b32 v[96:97], v[96:97], v[94:95] op_sel:[1,0]
	v_add_f32_e32 v76, 1.0, v76
	v_rcp_f32_e32 v76, v76
	v_fmac_f32_e32 v214, v18, v18
	v_cvt_pk_bf16_f32 v18, v116, v18
	v_pk_mul_f32 v[116:117], v[28:29], v[106:107]
	v_mul_f32_e32 v19, v19, v76
	v_add_f32_e32 v76, v130, v131
	v_add_f32_e32 v76, v76, v118
	v_add_f32_e32 v124, v76, v119
	v_pk_mul_f32 v[76:77], v[10:11], v[96:97]
	v_pk_mul_f32 v[96:97], v[2:3], v[96:97]
	v_fmac_f32_e32 v214, v19, v19
	v_add_f32_e32 v78, v78, v96
	v_add_f32_e32 v78, v78, v97
	v_mul_f32_e32 v79, 0xbfb8aa3b, v78
	v_exp_f32_e32 v79, v79
	v_pk_mul_f32 v[118:119], v[2:3], v[94:95]
	v_mul_f32_e32 v97, 0xbfb8aa3b, v124
	v_exp_f32_e32 v97, v97
	v_add_f32_e32 v79, 1.0, v79
	v_rcp_f32_e32 v79, v79
	v_add_f32_e32 v76, v76, v77
	v_add_f32_e32 v97, 1.0, v97
	v_rcp_f32_e32 v97, v97
	v_mul_f32_e32 v96, v78, v79
	v_cvt_pk_bf16_f32 v19, v19, v96
	ds_write_b128 v169, v[16:19] offset:2448
	v_mul_f32_e32 v18, 0xbfb8aa3b, v152
	v_mul_f32_e32 v17, 0xbfb8aa3b, v238
	v_exp_f32_e32 v18, v18
	v_exp_f32_e32 v17, v17
	v_mul_f32_e32 v19, 0xbfb8aa3b, v127
	v_add_f32_e32 v16, v80, v81
	v_exp_f32_e32 v19, v19
	v_mul_f32_e32 v80, 0xbfb8aa3b, v153
	v_exp_f32_e32 v80, v80
	v_mul_f32_e32 v81, 0xbfb8aa3b, v128
	v_fmac_f32_e32 v214, v96, v96
	v_add_f32_e32 v16, v16, v118
	v_add_f32_e32 v18, 1.0, v18
	v_exp_f32_e32 v81, v81
	v_mul_f32_e32 v96, 0xbfb8aa3b, v129
	v_add_f32_e32 v16, v16, v119
	v_add_f32_e32 v17, 1.0, v17
	v_rcp_f32_e32 v18, v18
	v_exp_f32_e32 v96, v96
	v_rcp_f32_e32 v17, v17
	v_add_f32_e32 v19, 1.0, v19
	v_mul_f32_e32 v118, 0xbfb8aa3b, v16
	v_rcp_f32_e32 v19, v19
	v_add_f32_e32 v80, 1.0, v80
	v_exp_f32_e32 v118, v118
	v_rcp_f32_e32 v80, v80
	v_add_f32_e32 v81, 1.0, v81
	v_mul_f32_e32 v18, v152, v18
	v_rcp_f32_e32 v81, v81
	v_add_f32_e32 v96, 1.0, v96
	v_mul_f32_e32 v17, v238, v17
	v_mul_f32_e32 v126, v18, v18
	v_rcp_f32_e32 v96, v96
	v_fmac_f32_e32 v126, v17, v17
	v_mul_f32_e32 v19, v127, v19
	v_add_f32_e32 v118, 1.0, v118
	v_fmac_f32_e32 v126, v19, v19
	v_mul_f32_e32 v80, v153, v80
	v_rcp_f32_e32 v118, v118
	v_fmac_f32_e32 v126, v80, v80
	v_mul_f32_e32 v81, v128, v81
	v_fmac_f32_e32 v126, v81, v81
	v_mul_f32_e32 v96, v129, v96
	v_fmac_f32_e32 v126, v96, v96
	v_mul_f32_e32 v97, v124, v97
	v_fmac_f32_e32 v126, v97, v97
	v_mul_f32_e32 v118, v16, v118
	v_cvt_pk_bf16_f32 v16, v17, v18
	v_cvt_pk_bf16_f32 v17, v19, v80
	v_cvt_pk_bf16_f32 v18, v81, v96
	v_cvt_pk_bf16_f32 v19, v97, v118
	v_lshlrev_b32_e32 v97, 16, v230
	v_lshlrev_b32_e32 v96, 16, v229
	ds_write_b128 v169, v[16:19] offset:2720
	v_pk_mov_b32 v[16:17], v[122:123], v[96:97] op_sel:[1,0]
	v_pk_mul_f32 v[18:19], v[24:25], v[96:97]
	v_pk_mul_f32 v[80:81], v[64:65], v[16:17]
	v_pk_mul_f32 v[16:17], v[24:25], v[16:17]
	v_fmac_f32_e32 v126, v118, v118
	v_add_f32_e32 v16, v82, v16
	v_add_f32_e32 v16, v16, v17
	v_mul_f32_e32 v17, 0xbfb8aa3b, v16
	v_exp_f32_e32 v17, v17
	v_and_b32_e32 v119, 0xffff0000, v230
	v_and_b32_e32 v118, 0xffff0000, v229
	v_pk_mul_f32 v[78:79], v[10:11], v[94:95]
	v_add_f32_e32 v17, 1.0, v17
	v_rcp_f32_e32 v17, v17
	v_pk_mul_f32 v[122:123], v[64:65], v[96:97]
	v_mul_f32_e32 v124, v16, v17
	v_add_f32_e32 v16, v120, v121
	v_add_f32_e32 v16, v16, v18
	v_add_f32_e32 v128, v16, v19
	v_pk_mov_b32 v[16:17], v[98:99], v[118:119] op_sel:[1,0]
	v_pk_mul_f32 v[18:19], v[4:5], v[118:119]
	v_pk_mul_f32 v[82:83], v[12:13], v[16:17]
	v_pk_mul_f32 v[16:17], v[4:5], v[16:17]
	v_lshlrev_b32_e32 v99, 16, v228
	v_add_f32_e32 v16, v66, v16
	v_add_f32_e32 v16, v16, v17
	v_mul_f32_e32 v17, 0xbfb8aa3b, v16
	v_exp_f32_e32 v17, v17
	v_lshlrev_b32_e32 v98, 16, v227
	v_pk_mul_f32 v[120:121], v[12:13], v[118:119]
	v_add_f32_e32 v17, 1.0, v17
	v_rcp_f32_e32 v17, v17
	s_nop 0
	v_mul_f32_e32 v16, v16, v17
	v_add_f32_e32 v17, v100, v101
	v_add_f32_e32 v17, v17, v18
	v_add_f32_e32 v129, v17, v19
	v_pk_mov_b32 v[18:19], v[110:111], v[98:99] op_sel:[1,0]
	v_add_f32_e32 v17, v84, v85
	v_pk_mul_f32 v[66:67], v[62:63], v[18:19]
	v_pk_mul_f32 v[18:19], v[20:21], v[18:19]
	v_pk_mul_f32 v[100:101], v[20:21], v[98:99]
	v_add_f32_e32 v17, v17, v18
	v_add_f32_e32 v17, v17, v19
	v_mul_f32_e32 v18, 0xbfb8aa3b, v17
	v_exp_f32_e32 v18, v18
	v_mul_f32_e32 v127, v16, v16
	v_fmac_f32_e32 v127, v124, v124
	v_cvt_pk_bf16_f32 v16, v124, v16
	v_add_f32_e32 v18, 1.0, v18
	v_rcp_f32_e32 v18, v18
	v_pk_mul_f32 v[124:125], v[62:63], v[98:99]
	v_mul_f32_e32 v17, v17, v18
	v_add_f32_e32 v18, v112, v113
	v_add_f32_e32 v18, v18, v100
	v_add_f32_e32 v130, v18, v101
	v_and_b32_e32 v101, 0xffff0000, v228
	v_and_b32_e32 v100, 0xffff0000, v227
	v_pk_mov_b32 v[18:19], v[102:103], v[100:101] op_sel:[1,0]
	v_fmac_f32_e32 v127, v17, v17
	v_pk_mul_f32 v[84:85], v[14:15], v[18:19]
	v_pk_mul_f32 v[18:19], v[6:7], v[18:19]
	v_pk_mul_f32 v[102:103], v[6:7], v[100:101]
	v_add_f32_e32 v18, v68, v18
	v_add_f32_e32 v18, v18, v19
	v_mul_f32_e32 v19, 0xbfb8aa3b, v18
	v_exp_f32_e32 v19, v19
	v_pk_mul_f32 v[110:111], v[14:15], v[100:101]
	v_add_f32_e32 v19, 1.0, v19
	v_rcp_f32_e32 v19, v19
	s_nop 0
	v_mul_f32_e32 v18, v18, v19
	v_fmac_f32_e32 v127, v18, v18
	v_cvt_pk_bf16_f32 v17, v17, v18
	v_add_f32_e32 v18, v104, v105
	v_add_f32_e32 v18, v18, v102
	v_add_f32_e32 v131, v18, v103
	v_lshlrev_b32_e32 v103, 16, v226
	v_lshlrev_b32_e32 v102, 16, v225
	v_pk_mov_b32 v[18:19], v[108:109], v[102:103] op_sel:[1,0]
	v_pk_mul_f32 v[104:105], v[22:23], v[102:103]
	v_pk_mul_f32 v[68:69], v[30:31], v[18:19]
	v_pk_mul_f32 v[18:19], v[22:23], v[18:19]
	v_pk_mul_f32 v[112:113], v[30:31], v[102:103]
	v_add_f32_e32 v18, v70, v18
	v_add_f32_e32 v18, v18, v19
	v_mul_f32_e32 v19, 0xbfb8aa3b, v18
	v_exp_f32_e32 v19, v19
	v_add_f32_e32 v68, v68, v69
	v_and_b32_e32 v69, 0xffff0000, v218
	v_add_f32_e32 v19, 1.0, v19
	v_rcp_f32_e32 v19, v19
	s_nop 0
	v_mul_f32_e32 v152, v18, v19
	v_add_f32_e32 v18, v114, v115
	v_add_f32_e32 v18, v18, v104
	v_add_f32_e32 v153, v18, v105
	v_and_b32_e32 v105, 0xffff0000, v226
	v_and_b32_e32 v104, 0xffff0000, v225
	v_pk_mov_b32 v[18:19], v[86:87], v[104:105] op_sel:[1,0]
	v_pk_mul_f32 v[86:87], v[0:1], v[104:105]
	v_pk_mul_f32 v[70:71], v[8:9], v[18:19]
	v_pk_mul_f32 v[18:19], v[0:1], v[18:19]
	v_fmac_f32_e32 v127, v152, v152
	v_add_f32_e32 v18, v72, v18
	v_add_f32_e32 v18, v18, v19
	v_mul_f32_e32 v19, 0xbfb8aa3b, v18
	v_exp_f32_e32 v19, v19
	v_pk_mul_f32 v[108:109], v[8:9], v[104:105]
	v_add_f32_e32 v19, 1.0, v19
	v_rcp_f32_e32 v19, v19
	s_nop 0
	v_mul_f32_e32 v18, v18, v19
	v_add_f32_e32 v19, v92, v93
	v_add_f32_e32 v19, v19, v86
	v_fmac_f32_e32 v127, v18, v18
	v_cvt_pk_bf16_f32 v18, v152, v18
	v_add_f32_e32 v152, v19, v87
	v_lshlrev_b32_e32 v87, 16, v224
	v_lshlrev_b32_e32 v86, 16, v223
	v_pk_mov_b32 v[92:93], v[106:107], v[86:87] op_sel:[1,0]
	v_add_f32_e32 v19, v74, v75
	v_pk_mul_f32 v[72:73], v[28:29], v[92:93]
	v_pk_mul_f32 v[92:93], v[26:27], v[92:93]
	v_pk_mul_f32 v[114:115], v[26:27], v[86:87]
	v_add_f32_e32 v19, v19, v92
	v_add_f32_e32 v19, v19, v93
	v_mul_f32_e32 v74, 0xbfb8aa3b, v19
	v_exp_f32_e32 v74, v74
	v_and_b32_e32 v93, 0xffff0000, v224
	v_and_b32_e32 v92, 0xffff0000, v223
	v_pk_mov_b32 v[94:95], v[94:95], v[92:93] op_sel:[1,0]
	v_add_f32_e32 v74, 1.0, v74
	v_rcp_f32_e32 v74, v74
	v_pk_mul_f32 v[106:107], v[28:29], v[86:87]
	v_mul_f32_e32 v19, v19, v74
	v_add_f32_e32 v74, v116, v117
	v_add_f32_e32 v74, v74, v114
	v_add_f32_e32 v116, v74, v115
	v_pk_mul_f32 v[74:75], v[10:11], v[94:95]
	v_pk_mul_f32 v[94:95], v[2:3], v[94:95]
	v_fmac_f32_e32 v127, v19, v19
	v_add_f32_e32 v76, v76, v94
	v_add_f32_e32 v76, v76, v95
	v_mul_f32_e32 v77, 0xbfb8aa3b, v76
	v_exp_f32_e32 v77, v77
	v_pk_mul_f32 v[114:115], v[2:3], v[92:93]
	v_mul_f32_e32 v95, 0xbfb8aa3b, v152
	v_exp_f32_e32 v95, v95
	v_add_f32_e32 v77, 1.0, v77
	v_rcp_f32_e32 v77, v77
	v_add_f32_e32 v95, 1.0, v95
	v_rcp_f32_e32 v95, v95
	v_mul_f32_e32 v94, v76, v77
	v_cvt_pk_bf16_f32 v19, v19, v94
	ds_write_b128 v169, v[16:19] offset:2992
	v_add_f32_e32 v16, v78, v79
	v_mul_f32_e32 v18, 0xbfb8aa3b, v129
	v_add_f32_e32 v16, v16, v114
	v_mul_f32_e32 v17, 0xbfb8aa3b, v128
	v_exp_f32_e32 v18, v18
	v_add_f32_e32 v16, v16, v115
	v_exp_f32_e32 v17, v17
	v_mul_f32_e32 v19, 0xbfb8aa3b, v130
	v_exp_f32_e32 v19, v19
	v_mul_f32_e32 v78, 0xbfb8aa3b, v131
	v_mul_f32_e32 v115, 0xbfb8aa3b, v16
	v_exp_f32_e32 v78, v78
	v_mul_f32_e32 v79, 0xbfb8aa3b, v153
	v_mul_f32_e32 v114, 0xbfb8aa3b, v116
	v_exp_f32_e32 v115, v115
	v_add_f32_e32 v18, 1.0, v18
	v_exp_f32_e32 v79, v79
	v_exp_f32_e32 v114, v114
	v_add_f32_e32 v17, 1.0, v17
	v_rcp_f32_e32 v18, v18
	v_rcp_f32_e32 v17, v17
	v_add_f32_e32 v19, 1.0, v19
	v_rcp_f32_e32 v19, v19
	v_add_f32_e32 v78, 1.0, v78
	v_add_f32_e32 v115, 1.0, v115
	v_rcp_f32_e32 v78, v78
	v_add_f32_e32 v79, 1.0, v79
	v_add_f32_e32 v114, 1.0, v114
	v_rcp_f32_e32 v115, v115
	v_mul_f32_e32 v18, v129, v18
	v_rcp_f32_e32 v79, v79
	v_rcp_f32_e32 v114, v114
	v_fmac_f32_e32 v127, v94, v94
	v_mul_f32_e32 v17, v128, v17
	v_mul_f32_e32 v94, v18, v18
	v_fmac_f32_e32 v94, v17, v17
	v_mul_f32_e32 v19, v130, v19
	v_fmac_f32_e32 v94, v19, v19
	v_mul_f32_e32 v78, v131, v78
	v_mul_f32_e32 v115, v16, v115
	v_cvt_pk_bf16_f32 v16, v17, v18
	v_cvt_pk_bf16_f32 v17, v19, v78
	v_fmac_f32_e32 v94, v78, v78
	v_mul_f32_e32 v79, v153, v79
	v_mul_f32_e32 v95, v152, v95
	v_mul_f32_e32 v114, v116, v114
	v_cvt_pk_bf16_f32 v18, v79, v95
	v_cvt_pk_bf16_f32 v19, v114, v115
	ds_write_b128 v169, v[16:19] offset:3264
	v_lshlrev_b32_e32 v16, 16, v221
	v_lshlrev_b32_e32 v17, 16, v222
	v_fmac_f32_e32 v94, v79, v79
	v_pk_mov_b32 v[78:79], v[96:97], v[16:17] op_sel:[1,0]
	v_fmac_f32_e32 v94, v95, v95
	v_pk_mul_f32 v[18:19], v[64:65], v[78:79]
	v_pk_mul_f32 v[64:65], v[24:25], v[16:17]
	v_pk_mul_f32 v[78:79], v[24:25], v[78:79]
	v_add_f32_e32 v16, v80, v81
	v_add_f32_e32 v16, v16, v78
	v_add_f32_e32 v16, v16, v79
	v_mul_f32_e32 v78, 0xbfb8aa3b, v16
	v_exp_f32_e32 v78, v78
	v_fmac_f32_e32 v94, v114, v114
	v_pk_mul_f32 v[76:77], v[10:11], v[92:93]
	v_fmac_f32_e32 v94, v115, v115
	v_add_f32_e32 v78, 1.0, v78
	v_rcp_f32_e32 v78, v78
	s_nop 0
	v_mul_f32_e32 v114, v16, v78
	v_add_f32_e32 v16, v122, v123
	v_add_f32_e32 v16, v16, v64
	v_add_f32_e32 v95, v16, v65
	v_and_b32_e32 v65, 0xffff0000, v222
	v_and_b32_e32 v64, 0xffff0000, v221
	v_pk_mov_b32 v[80:81], v[118:119], v[64:65] op_sel:[1,0]
	v_add_f32_e32 v16, v82, v83
	v_pk_mul_f32 v[78:79], v[12:13], v[80:81]
	v_pk_mul_f32 v[12:13], v[4:5], v[80:81]
	v_pk_mul_f32 v[96:97], v[4:5], v[64:65]
	v_add_f32_e32 v12, v16, v12
	v_add_f32_e32 v12, v12, v13
	v_mul_f32_e32 v13, 0xbfb8aa3b, v12
	v_exp_f32_e32 v13, v13
	v_lshlrev_b32_e32 v80, 16, v219
	v_lshlrev_b32_e32 v81, 16, v220
	v_pk_mov_b32 v[82:83], v[98:99], v[80:81] op_sel:[1,0]
	v_add_f32_e32 v13, 1.0, v13
	v_rcp_f32_e32 v13, v13
	v_pk_mul_f32 v[62:63], v[62:63], v[82:83]
	v_pk_mul_f32 v[82:83], v[20:21], v[82:83]
	v_lshlrev_b32_e32 v99, 16, v194
	v_mul_f32_e32 v12, v12, v13
	v_add_f32_e32 v13, v120, v121
	v_add_f32_e32 v13, v13, v96
	v_add_f32_e32 v64, v13, v97
	v_add_f32_e32 v13, v66, v67
	v_add_f32_e32 v13, v13, v82
	v_add_f32_e32 v13, v13, v83
	v_mul_f32_e32 v66, 0xbfb8aa3b, v13
	v_exp_f32_e32 v66, v66
	v_pk_mul_f32 v[96:97], v[20:21], v[80:81]
	v_and_b32_e32 v67, 0xffff0000, v220
	v_mul_f32_e32 v16, v12, v12
	v_add_f32_e32 v66, 1.0, v66
	v_rcp_f32_e32 v66, v66
	v_fmac_f32_e32 v16, v114, v114
	v_cvt_pk_bf16_f32 v12, v114, v12
	v_mul_f32_e32 v13, v13, v66
	v_add_f32_e32 v66, v124, v125
	v_add_f32_e32 v66, v66, v96
	v_add_f32_e32 v80, v66, v97
	v_and_b32_e32 v66, 0xffff0000, v219
	v_pk_mov_b32 v[96:97], v[100:101], v[66:67] op_sel:[1,0]
	v_fmac_f32_e32 v16, v13, v13
	v_pk_mul_f32 v[82:83], v[14:15], v[96:97]
	v_pk_mul_f32 v[14:15], v[6:7], v[66:67]
	v_pk_mul_f32 v[96:97], v[6:7], v[96:97]
	v_add_f32_e32 v66, v84, v85
	v_add_f32_e32 v66, v66, v96
	v_add_f32_e32 v66, v66, v97
	v_mul_f32_e32 v84, 0xbfb8aa3b, v66
	v_exp_f32_e32 v84, v84
	v_lshlrev_b32_e32 v85, 16, v218
	v_and_b32_e32 v101, 0xffff0000, v194
	v_add_f32_e32 v84, 1.0, v84
	v_rcp_f32_e32 v84, v84
	s_nop 0
	v_mul_f32_e32 v66, v66, v84
	v_fmac_f32_e32 v16, v66, v66
	v_cvt_pk_bf16_f32 v13, v13, v66
	v_add_f32_e32 v66, v110, v111
	v_add_f32_e32 v14, v66, v14
	v_lshlrev_b32_e32 v84, 16, v217
	v_add_f32_e32 v66, v14, v15
	v_pk_mov_b32 v[14:15], v[102:103], v[84:85] op_sel:[1,0]
	v_pk_mul_f32 v[96:97], v[22:23], v[84:85]
	v_pk_mul_f32 v[30:31], v[30:31], v[14:15]
	v_pk_mul_f32 v[14:15], v[22:23], v[14:15]
	s_nop 0
	v_add_f32_e32 v14, v68, v14
	v_add_f32_e32 v14, v14, v15
	v_mul_f32_e32 v15, 0xbfb8aa3b, v14
	v_exp_f32_e32 v15, v15
	v_and_b32_e32 v68, 0xffff0000, v217
	v_add_f32_e32 v15, 1.0, v15
	v_rcp_f32_e32 v15, v15
	s_nop 0
	v_mul_f32_e32 v84, v14, v15
	v_add_f32_e32 v14, v112, v113
	v_add_f32_e32 v14, v14, v96
	v_add_f32_e32 v98, v14, v97
	v_pk_mov_b32 v[14:15], v[104:105], v[68:69] op_sel:[1,0]
	v_pk_mul_f32 v[96:97], v[0:1], v[68:69]
	v_pk_mul_f32 v[8:9], v[8:9], v[14:15]
	v_pk_mul_f32 v[14:15], v[0:1], v[14:15]
	v_add_f32_e32 v68, v70, v71
	v_add_f32_e32 v14, v68, v14
	v_add_f32_e32 v14, v14, v15
	v_mul_f32_e32 v15, 0xbfb8aa3b, v14
	v_exp_f32_e32 v15, v15
	v_lshlrev_b32_e32 v70, 16, v215
	v_lshlrev_b32_e32 v71, 16, v216
	v_pk_mov_b32 v[86:87], v[86:87], v[70:71] op_sel:[1,0]
	v_add_f32_e32 v15, 1.0, v15
	v_rcp_f32_e32 v15, v15
	v_pk_mul_f32 v[28:29], v[28:29], v[86:87]
	v_pk_mul_f32 v[86:87], v[26:27], v[86:87]
	v_fmac_f32_e32 v16, v84, v84
	v_mul_f32_e32 v14, v14, v15
	v_add_f32_e32 v15, v108, v109
	v_add_f32_e32 v15, v15, v96
	v_add_f32_e32 v68, v15, v97
	v_add_f32_e32 v15, v72, v73
	v_add_f32_e32 v15, v15, v86
	v_and_b32_e32 v73, 0xffff0000, v216
	v_and_b32_e32 v72, 0xffff0000, v215
	v_add_f32_e32 v15, v15, v87
	v_pk_mov_b32 v[86:87], v[92:93], v[72:73] op_sel:[1,0]
	v_pk_mul_f32 v[92:93], v[2:3], v[72:73]
	v_pk_mul_f32 v[10:11], v[10:11], v[86:87]
	v_pk_mul_f32 v[86:87], v[2:3], v[86:87]
	v_add_f32_e32 v72, v74, v75
	v_add_f32_e32 v72, v72, v86
	v_pk_mul_f32 v[96:97], v[26:27], v[70:71]
	v_mul_f32_e32 v70, 0xbfb8aa3b, v15
	v_add_f32_e32 v72, v72, v87
	v_exp_f32_e32 v70, v70
	v_mul_f32_e32 v74, 0xbfb8aa3b, v72
	v_exp_f32_e32 v74, v74
	v_fmac_f32_e32 v16, v14, v14
	v_add_f32_e32 v70, 1.0, v70
	v_rcp_f32_e32 v70, v70
	v_add_f32_e32 v74, 1.0, v74
	v_rcp_f32_e32 v74, v74
	v_cvt_pk_bf16_f32 v14, v84, v14
	v_mul_f32_e32 v15, v15, v70
	v_fmac_f32_e32 v16, v15, v15
	v_mul_f32_e32 v72, v72, v74
	v_cvt_pk_bf16_f32 v15, v15, v72
	ds_write_b128 v169, v[12:15] offset:3536
	v_add_f32_e32 v12, v76, v77
	v_add_f32_e32 v12, v12, v92
	v_add_f32_e32 v13, v12, v93
	v_mul_f32_e32 v12, 0xbfb8aa3b, v95
	v_exp_f32_e32 v12, v12
	v_mul_f32_e32 v74, 0xbfb8aa3b, v68
	v_exp_f32_e32 v74, v74
	v_add_f32_e32 v70, v106, v107
	v_add_f32_e32 v12, 1.0, v12
	v_rcp_f32_e32 v12, v12
	v_add_f32_e32 v74, 1.0, v74
	v_rcp_f32_e32 v74, v74
	v_fmac_f32_e32 v16, v72, v72
	v_mul_f32_e32 v14, v95, v12
	v_mul_f32_e32 v12, 0xbfb8aa3b, v64
	v_exp_f32_e32 v12, v12
	v_mul_f32_e32 v72, 0xbfb8aa3b, v66
	v_add_f32_e32 v70, v70, v96
	v_exp_f32_e32 v72, v72
	v_add_f32_e32 v70, v70, v97
	v_add_f32_e32 v12, 1.0, v12
	v_mul_f32_e32 v68, v68, v74
	v_mul_f32_e32 v74, 0xbfb8aa3b, v70
	v_rcp_f32_e32 v12, v12
	v_exp_f32_e32 v74, v74
	v_add_f32_e32 v72, 1.0, v72
	v_rcp_f32_e32 v72, v72
	v_mul_f32_e32 v15, v64, v12
	v_mul_f32_e32 v64, 0xbfb8aa3b, v80
	v_add_f32_e32 v74, 1.0, v74
	v_exp_f32_e32 v64, v64
	v_rcp_f32_e32 v74, v74
	v_mul_f32_e32 v66, v66, v72
	v_mul_f32_e32 v72, 0xbfb8aa3b, v98
	v_exp_f32_e32 v72, v72
	v_add_f32_e32 v64, 1.0, v64
	v_mul_f32_e32 v70, v70, v74
	v_mul_f32_e32 v74, 0xbfb8aa3b, v13
	v_rcp_f32_e32 v64, v64
	v_exp_f32_e32 v74, v74
	v_add_f32_e32 v72, 1.0, v72
	v_rcp_f32_e32 v72, v72
	v_mul_f32_e32 v12, v15, v15
	v_fmac_f32_e32 v12, v14, v14
	v_mul_f32_e32 v64, v80, v64
	v_add_f32_e32 v74, 1.0, v74
	v_fmac_f32_e32 v12, v64, v64
	v_rcp_f32_e32 v74, v74
	v_fmac_f32_e32 v12, v66, v66
	v_mul_f32_e32 v72, v98, v72
	v_fmac_f32_e32 v12, v72, v72
	v_fmac_f32_e32 v12, v68, v68
	v_fmac_f32_e32 v12, v70, v70
	v_mul_f32_e32 v13, v13, v74
	v_cvt_pk_bf16_f32 v74, v14, v15
	v_cvt_pk_bf16_f32 v75, v64, v66
	v_lshlrev_b32_e32 v15, 16, v213
	v_mov_b32_e32 v14, v17
	v_fmac_f32_e32 v12, v13, v13
	v_cvt_pk_bf16_f32 v76, v72, v68
	v_cvt_pk_bf16_f32 v77, v70, v13
	ds_write_b128 v169, v[74:77] offset:3808
	v_and_b32_e32 v75, 0xffff0000, v213
	v_pk_mul_f32 v[14:15], v[24:25], v[14:15]
	v_add_f32_e32 v13, v18, v19
	v_mov_b32_e32 v74, v65
	v_add_f32_e32 v13, v13, v14
	v_pk_mul_f32 v[4:5], v[4:5], v[74:75]
	v_add_f32_e32 v14, v78, v79
	v_lshlrev_b32_e32 v77, 16, v212
	v_add_f32_e32 v4, v14, v4
	v_mov_b32_e32 v76, v81
	v_add_f32_e32 v13, v13, v15
	v_add_f32_e32 v14, v4, v5
	v_pk_mul_f32 v[4:5], v[20:21], v[76:77]
	v_add_f32_e32 v15, v62, v63
	v_and_b32_e32 v87, 0xffff0000, v212
	v_add_f32_e32 v4, v15, v4
	v_mov_b32_e32 v86, v67
	v_add_f32_e32 v15, v4, v5
	v_pk_mul_f32 v[4:5], v[6:7], v[86:87]
	v_add_f32_e32 v6, v82, v83
	v_lshlrev_b32_e32 v93, 16, v195
	v_add_f32_e32 v4, v6, v4
	v_mov_b32_e32 v92, v85
	v_add_f32_e32 v6, v4, v5
	v_pk_mul_f32 v[4:5], v[22:23], v[92:93]
	v_add_f32_e32 v7, v30, v31
	v_add_f32_e32 v4, v7, v4
	v_add_f32_e32 v4, v4, v5
	v_add_f32_e32 v5, v8, v9
	v_mul_f32_e32 v9, 0xbfb8aa3b, v6
	v_exp_f32_e32 v9, v9
	v_and_b32_e32 v97, 0xffff0000, v195
	v_mov_b32_e32 v96, v69
	v_pk_mul_f32 v[0:1], v[0:1], v[96:97]
	v_add_f32_e32 v9, 1.0, v9
	v_rcp_f32_e32 v9, v9
	v_add_f32_e32 v0, v5, v0
	v_mov_b32_e32 v98, v71
	v_add_f32_e32 v5, v0, v1
	v_mul_f32_e32 v6, v6, v9
	v_mul_f32_e32 v9, 0xbfb8aa3b, v4
	v_exp_f32_e32 v9, v9
	v_pk_mul_f32 v[0:1], v[26:27], v[98:99]
	v_add_f32_e32 v7, v28, v29
	v_add_f32_e32 v0, v7, v0
	v_add_f32_e32 v9, 1.0, v9
	v_rcp_f32_e32 v9, v9
	v_mov_b32_e32 v100, v73
	v_add_f32_e32 v7, v0, v1
	v_pk_mul_f32 v[0:1], v[2:3], v[100:101]
	v_mul_f32_e32 v4, v4, v9
	v_mul_f32_e32 v9, 0xbfb8aa3b, v5
	v_add_f32_e32 v2, v10, v11
	v_exp_f32_e32 v9, v9
	v_add_f32_e32 v0, v2, v0
	v_add_f32_e32 v1, v0, v1
	v_mul_f32_e32 v0, 0xbfb8aa3b, v13
	v_exp_f32_e32 v0, v0
	v_add_f32_e32 v9, 1.0, v9
	v_rcp_f32_e32 v9, v9
	v_mul_f32_e32 v8, 0xbfb8aa3b, v15
	v_add_f32_e32 v0, 1.0, v0
	v_rcp_f32_e32 v0, v0
	v_mul_f32_e32 v5, v5, v9
	v_mul_f32_e32 v9, 0xbfb8aa3b, v7
	v_exp_f32_e32 v9, v9
	v_mul_f32_e32 v2, v13, v0
	v_mul_f32_e32 v0, 0xbfb8aa3b, v14
	v_exp_f32_e32 v0, v0
	v_add_f32_e32 v9, 1.0, v9
	v_exp_f32_e32 v8, v8
	v_rcp_f32_e32 v9, v9
	v_add_f32_e32 v0, 1.0, v0
	v_rcp_f32_e32 v0, v0
	v_add_f32_e32 v8, 1.0, v8
	v_mul_f32_e32 v7, v7, v9
	v_mul_f32_e32 v9, 0xbfb8aa3b, v1
	v_rcp_f32_e32 v8, v8
	v_exp_f32_e32 v9, v9
	v_mul_f32_e32 v3, v14, v0
	v_mul_f32_e32 v0, v3, v3
	v_fmac_f32_e32 v0, v2, v2
	v_mul_f32_e32 v8, v15, v8
	v_add_f32_e32 v9, 1.0, v9
	v_fmac_f32_e32 v0, v8, v8
	v_rcp_f32_e32 v9, v9
	v_fmac_f32_e32 v0, v6, v6
	v_fmac_f32_e32 v0, v4, v4
	v_fmac_f32_e32 v0, v5, v5
	v_fmac_f32_e32 v0, v7, v7
	v_mul_f32_e32 v1, v1, v9
	v_fmac_f32_e32 v0, v1, v1
	v_cvt_pk_bf16_f32 v2, v2, v3
	v_cvt_pk_bf16_f32 v3, v8, v6
	v_cvt_pk_bf16_f32 v4, v4, v5
	v_cvt_pk_bf16_f32 v5, v7, v1
	ds_write_b128 v169, v[2:5] offset:4080
	v_readlane_b32 s8, v255, 7
	v_readlane_b32 s9, v255, 8
	s_andn2_b64 vcc, exec, s[8:9]
	s_cbranch_vccnz .LBB0_286
	v_and_b32_e32 v2, 64, v202
	v_add_u32_e32 v5, 64, v2
	v_xor_b32_e32 v1, 1, v202
	v_cmp_lt_i32_e32 vcc, v1, v5
	s_nop 1
	v_cndmask_b32_e32 v1, v202, v1, vcc
	v_lshlrev_b32_e32 v4, 2, v1
	v_xor_b32_e32 v1, 2, v202
	v_cmp_lt_i32_e32 vcc, v1, v5
	s_nop 1
	v_cndmask_b32_e32 v1, v202, v1, vcc
	v_lshlrev_b32_e32 v3, 2, v1
	v_xor_b32_e32 v1, 4, v202
	v_cmp_lt_i32_e32 vcc, v1, v5
	s_nop 1
	v_cndmask_b32_e32 v1, v202, v1, vcc
	v_lshlrev_b32_e32 v2, 2, v1
	v_xor_b32_e32 v1, 8, v202
	v_cmp_lt_i32_e32 vcc, v1, v5
	s_nop 1
	v_cndmask_b32_e32 v1, v202, v1, vcc
	v_lshlrev_b32_e32 v1, 2, v1
	ds_bpermute_b32 v20, v4, v134
	ds_bpermute_b32 v21, v4, v135
	ds_bpermute_b32 v22, v4, v136
	ds_bpermute_b32 v23, v4, v137
	ds_bpermute_b32 v24, v4, v191
	ds_bpermute_b32 v25, v4, v192
	ds_bpermute_b32 v26, v4, v132
	ds_bpermute_b32 v27, v4, v133
	s_waitcnt lgkmcnt(7)
	v_add_f32_e32 v134, v134, v20
	s_waitcnt lgkmcnt(6)
	v_add_f32_e32 v135, v135, v21
	s_waitcnt lgkmcnt(5)
	v_add_f32_e32 v136, v136, v22
	s_waitcnt lgkmcnt(4)
	v_add_f32_e32 v137, v137, v23
	s_waitcnt lgkmcnt(3)
	v_add_f32_e32 v191, v191, v24
	s_waitcnt lgkmcnt(2)
	v_add_f32_e32 v192, v192, v25
	s_waitcnt lgkmcnt(1)
	v_add_f32_e32 v132, v132, v26
	s_waitcnt lgkmcnt(0)
	v_add_f32_e32 v133, v133, v27
	ds_bpermute_b32 v20, v4, v193
	ds_bpermute_b32 v21, v4, v214
	ds_bpermute_b32 v22, v4, v126
	ds_bpermute_b32 v23, v4, v127
	ds_bpermute_b32 v24, v4, v94
	ds_bpermute_b32 v25, v4, v16
	ds_bpermute_b32 v26, v4, v12
	ds_bpermute_b32 v27, v4, v0
	s_waitcnt lgkmcnt(7)
	v_add_f32_e32 v193, v193, v20
	s_waitcnt lgkmcnt(6)
	v_add_f32_e32 v214, v214, v21
	s_waitcnt lgkmcnt(5)
	v_add_f32_e32 v126, v126, v22
	s_waitcnt lgkmcnt(4)
	v_add_f32_e32 v127, v127, v23
	s_waitcnt lgkmcnt(3)
	v_add_f32_e32 v94, v94, v24
	s_waitcnt lgkmcnt(2)
	v_add_f32_e32 v16, v16, v25
	s_waitcnt lgkmcnt(1)
	v_add_f32_e32 v12, v12, v26
	s_waitcnt lgkmcnt(0)
	v_add_f32_e32 v0, v0, v27
	ds_bpermute_b32 v20, v3, v134
	ds_bpermute_b32 v21, v3, v135
	ds_bpermute_b32 v22, v3, v136
	ds_bpermute_b32 v23, v3, v137
	ds_bpermute_b32 v24, v3, v191
	ds_bpermute_b32 v25, v3, v192
	ds_bpermute_b32 v26, v3, v132
	ds_bpermute_b32 v27, v3, v133
	s_waitcnt lgkmcnt(7)
	v_add_f32_e32 v134, v134, v20
	s_waitcnt lgkmcnt(6)
	v_add_f32_e32 v135, v135, v21
	s_waitcnt lgkmcnt(5)
	v_add_f32_e32 v136, v136, v22
	s_waitcnt lgkmcnt(4)
	v_add_f32_e32 v137, v137, v23
	s_waitcnt lgkmcnt(3)
	v_add_f32_e32 v191, v191, v24
	s_waitcnt lgkmcnt(2)
	v_add_f32_e32 v192, v192, v25
	s_waitcnt lgkmcnt(1)
	v_add_f32_e32 v132, v132, v26
	s_waitcnt lgkmcnt(0)
	v_add_f32_e32 v133, v133, v27
	ds_bpermute_b32 v20, v3, v193
	ds_bpermute_b32 v21, v3, v214
	ds_bpermute_b32 v22, v3, v126
	ds_bpermute_b32 v23, v3, v127
	ds_bpermute_b32 v24, v3, v94
	ds_bpermute_b32 v25, v3, v16
	ds_bpermute_b32 v26, v3, v12
	ds_bpermute_b32 v27, v3, v0
	s_waitcnt lgkmcnt(7)
	v_add_f32_e32 v193, v193, v20
	s_waitcnt lgkmcnt(6)
	v_add_f32_e32 v214, v214, v21
	s_waitcnt lgkmcnt(5)
	v_add_f32_e32 v126, v126, v22
	s_waitcnt lgkmcnt(4)
	v_add_f32_e32 v127, v127, v23
	s_waitcnt lgkmcnt(3)
	v_add_f32_e32 v94, v94, v24
	s_waitcnt lgkmcnt(2)
	v_add_f32_e32 v16, v16, v25
	s_waitcnt lgkmcnt(1)
	v_add_f32_e32 v12, v12, v26
	s_waitcnt lgkmcnt(0)
	v_add_f32_e32 v0, v0, v27
	ds_bpermute_b32 v20, v2, v134
	ds_bpermute_b32 v21, v2, v135
	ds_bpermute_b32 v22, v2, v136
	ds_bpermute_b32 v23, v2, v137
	ds_bpermute_b32 v24, v2, v191
	ds_bpermute_b32 v25, v2, v192
	ds_bpermute_b32 v26, v2, v132
	ds_bpermute_b32 v27, v2, v133
	s_waitcnt lgkmcnt(7)
	v_add_f32_e32 v134, v134, v20
	s_waitcnt lgkmcnt(6)
	v_add_f32_e32 v135, v135, v21
	s_waitcnt lgkmcnt(5)
	v_add_f32_e32 v136, v136, v22
	s_waitcnt lgkmcnt(4)
	v_add_f32_e32 v137, v137, v23
	s_waitcnt lgkmcnt(3)
	v_add_f32_e32 v191, v191, v24
	s_waitcnt lgkmcnt(2)
	v_add_f32_e32 v192, v192, v25
	s_waitcnt lgkmcnt(1)
	v_add_f32_e32 v132, v132, v26
	s_waitcnt lgkmcnt(0)
	v_add_f32_e32 v133, v133, v27
	ds_bpermute_b32 v20, v2, v193
	ds_bpermute_b32 v21, v2, v214
	ds_bpermute_b32 v22, v2, v126
	ds_bpermute_b32 v23, v2, v127
	ds_bpermute_b32 v24, v2, v94
	ds_bpermute_b32 v25, v2, v16
	ds_bpermute_b32 v26, v2, v12
	ds_bpermute_b32 v27, v2, v0
	s_waitcnt lgkmcnt(7)
	v_add_f32_e32 v193, v193, v20
	s_waitcnt lgkmcnt(6)
	v_add_f32_e32 v214, v214, v21
	s_waitcnt lgkmcnt(5)
	v_add_f32_e32 v126, v126, v22
	s_waitcnt lgkmcnt(4)
	v_add_f32_e32 v127, v127, v23
	s_waitcnt lgkmcnt(3)
	v_add_f32_e32 v94, v94, v24
	s_waitcnt lgkmcnt(2)
	v_add_f32_e32 v16, v16, v25
	s_waitcnt lgkmcnt(1)
	v_add_f32_e32 v12, v12, v26
	s_waitcnt lgkmcnt(0)
	v_add_f32_e32 v0, v0, v27
	ds_bpermute_b32 v20, v1, v134
	ds_bpermute_b32 v21, v1, v135
	ds_bpermute_b32 v22, v1, v136
	ds_bpermute_b32 v23, v1, v137
	ds_bpermute_b32 v24, v1, v191
	ds_bpermute_b32 v25, v1, v192
	ds_bpermute_b32 v26, v1, v132
	ds_bpermute_b32 v27, v1, v133
	s_waitcnt lgkmcnt(7)
	v_add_f32_e32 v134, v134, v20
	s_waitcnt lgkmcnt(6)
	v_add_f32_e32 v135, v135, v21
	s_waitcnt lgkmcnt(5)
	v_add_f32_e32 v136, v136, v22
	s_waitcnt lgkmcnt(4)
	v_add_f32_e32 v137, v137, v23
	s_waitcnt lgkmcnt(3)
	v_add_f32_e32 v191, v191, v24
	s_waitcnt lgkmcnt(2)
	v_add_f32_e32 v192, v192, v25
	s_waitcnt lgkmcnt(1)
	v_add_f32_e32 v132, v132, v26
	s_waitcnt lgkmcnt(0)
	v_add_f32_e32 v133, v133, v27
	ds_bpermute_b32 v20, v1, v193
	ds_bpermute_b32 v21, v1, v214
	ds_bpermute_b32 v22, v1, v126
	ds_bpermute_b32 v23, v1, v127
	ds_bpermute_b32 v24, v1, v94
	ds_bpermute_b32 v25, v1, v16
	ds_bpermute_b32 v26, v1, v12
	ds_bpermute_b32 v27, v1, v0
	s_waitcnt lgkmcnt(7)
	v_add_f32_e32 v193, v193, v20
	s_waitcnt lgkmcnt(6)
	v_add_f32_e32 v214, v214, v21
	s_waitcnt lgkmcnt(5)
	v_add_f32_e32 v126, v126, v22
	s_waitcnt lgkmcnt(4)
	v_add_f32_e32 v127, v127, v23
	s_waitcnt lgkmcnt(3)
	v_add_f32_e32 v94, v94, v24
	s_waitcnt lgkmcnt(2)
	v_add_f32_e32 v16, v16, v25
	s_waitcnt lgkmcnt(1)
	v_add_f32_e32 v12, v12, v26
	s_waitcnt lgkmcnt(0)
	v_add_f32_e32 v0, v0, v27
	v_cndmask_b32_e64 v5, 0, v134, s[6:7]
	v_readlane_b32 s8, v254, 20
	v_readlane_b32 s9, v254, 21
	s_nop 1
	v_cndmask_b32_e64 v5, v5, v135, s[8:9]
	v_readlane_b32 s8, v254, 22
	v_readlane_b32 s9, v254, 23
	s_nop 1
	v_cndmask_b32_e64 v5, v5, v136, s[8:9]
	v_readlane_b32 s8, v254, 24
	v_readlane_b32 s9, v254, 25
	s_nop 1
	v_cndmask_b32_e64 v5, v5, v137, s[8:9]
	v_readlane_b32 s8, v254, 26
	v_readlane_b32 s9, v254, 27
	s_nop 1
	v_cndmask_b32_e64 v5, v5, v191, s[8:9]
	v_readlane_b32 s8, v254, 28
	v_readlane_b32 s9, v254, 29
	s_nop 1
	v_cndmask_b32_e64 v5, v5, v192, s[8:9]
	v_readlane_b32 s8, v254, 30
	v_readlane_b32 s9, v254, 31
	s_nop 1
	v_cndmask_b32_e64 v5, v5, v132, s[8:9]
	v_readlane_b32 s8, v254, 32
	v_readlane_b32 s9, v254, 33
	s_nop 1
	v_cndmask_b32_e64 v5, v5, v133, s[8:9]
	v_readlane_b32 s8, v254, 34
	v_readlane_b32 s9, v254, 35
	s_nop 1
	v_cndmask_b32_e64 v5, v5, v193, s[8:9]
	v_readlane_b32 s8, v254, 36
	v_readlane_b32 s9, v254, 37
	s_nop 1
	v_cndmask_b32_e64 v5, v5, v214, s[8:9]
	v_readlane_b32 s8, v254, 38
	v_readlane_b32 s9, v254, 39
	s_nop 1
	v_cndmask_b32_e64 v5, v5, v126, s[8:9]
	v_readlane_b32 s8, v254, 40
	v_readlane_b32 s9, v254, 41
	s_nop 1
	v_cndmask_b32_e64 v5, v5, v127, s[8:9]
	v_readlane_b32 s8, v254, 42
	v_readlane_b32 s9, v254, 43
	s_nop 1
	v_cndmask_b32_e64 v5, v5, v94, s[8:9]
	v_readlane_b32 s8, v254, 44
	v_readlane_b32 s9, v254, 45
	s_nop 1
	v_cndmask_b32_e64 v5, v5, v16, s[8:9]
	v_readlane_b32 s8, v254, 46
	v_readlane_b32 s9, v254, 47
	s_nop 1
	v_cndmask_b32_e64 v5, v5, v12, s[8:9]
	v_readlane_b32 s8, v254, 48
	v_readlane_b32 s9, v254, 49
	s_nop 1
	v_cndmask_b32_e64 v0, v5, v0, s[8:9]
	v_add_f32_e32 v0, 0x358637bd, v0
	v_cmp_gt_f32_e32 vcc, s86, v0
	v_mul_f32_e32 v1, 0x4b800000, v0
	s_nop 0
	v_cndmask_b32_e32 v0, v0, v1, vcc
	v_rsq_f32_e32 v0, v0
	s_nop 0
	v_mul_f32_e32 v1, 0x45800000, v0
	v_cndmask_b32_e32 v0, v0, v1, vcc
	v_mul_f32_e32 v0, v170, v0
	ds_write_b32 v171, v0
